# strategy 9: scalar pointer/counter updates and loop test of the 8 GEMM K loops moved in front of the iteration's last barrier (on top of v59)
# baseline (speedup 1.0000x reference)
; #define PG8_STAGE(bufoff, gbase, voff) do { _Pragma("unroll") for (int _i = 0; _i < 2; ++_i) \
;         __builtin_amdgcn_global_load_lds((const unsigned*)((const char*)(gbase) + (voff)[_i]), (LAS unsigned*)(lds + (bufoff) + ldsw + _i * 8192), 16, 0, 0); } while (0)
; #define PG8_LDA(dst, b, h) do { _Pragma("unroll") for (int m = 0; m < 4; ++m) _Pragma("unroll") for (int k = 0; k < 2; ++k) dst[m][k] = *(const LAS bf16x8*)(lds + PG8_SA(b, h) + aoff + m * 2048 + k * 1024); } while (0)
; #define PG8_LDB(dst, b, h) do { _Pragma("unroll") for (int n = 0; n < 2; ++n) _Pragma("unroll") for (int k = 0; k < 2; ++k) dst[n][k] = *(const LAS bf16x8*)(lds + PG8_SB(b, h) + boff + n * 2048 + k * 1024); } while (0)
; #define PG8_MMA(ai, bj, At, Bt) do { __builtin_amdgcn_s_setprio(1); _Pragma("unroll") for (int m = 0; m < 4; ++m) _Pragma("unroll") for (int n = 0; n < 2; ++n) _Pragma("unroll") for (int k = 0; k < 2; ++k) \
;         acc[ai][bj][m][n] = mma16<I8>(Bt[n][k], At[m][k], acc[ai][bj][m][n]); __builtin_amdgcn_s_setprio(0); } while (0)
; #define PG8_WAIT_V(n) asm volatile("s_waitcnt vmcnt(" #n ")" ::: "memory")
; #define PG8_WAIT_L(n) asm volatile("s_waitcnt lgkmcnt(" #n ")" ::: "memory")
; #define PG8_BAR __builtin_amdgcn_s_barrier()
; #define PG8_SCHED __builtin_amdgcn_sched_barrier(0)
; template <class Epi, class Sched, bool I8 = false>
; __device__ __forceinline__ void gemm_phase(LAS unsigned char* lds, const Gemm g, const Sched& S, const Epi& E) {
;     ...
;         for (int t = 0; t < nt; t += 2) {
;             const bool last = (t == nt - 2);
;             const char* a1 = cA + (size_t)(t + 1) * kstep;
;             const char* a2 = last ? nA : cA + (size_t)(t + 2) * kstep; const char* b2 = last ? nB : cB + (size_t)(t + 2) * kstep;
;             const char* a3 = a2 + kstep; const char* b3 = b2 + kstep;
;             if (PG8_SP2) {
;             PG8_LDB(B0, 0, 0); PG8_LDB(B1, 0, 1); PG8_SCHED; PG8_LDA(At, 0, 0); PG8_STAGE(PG8_SA(1, 1), a1 + hstepA, voffA);
;             PG8_WAIT_V(8); PG8_WAIT_L(0); PG8_BAR; PG8_MMA(0, 0, At, B0); PG8_MMA(0, 1, At, B1); PG8_BAR; PG8_SCHED;
;             PG8_LDA(At, 0, 1); PG8_STAGE(PG8_SB(0, 0), b2, voffB); PG8_STAGE(PG8_SB(0, 1), b2 + hstepB, voffB); PG8_STAGE(PG8_SA(0, 0), a2, voffA);
;             PG8_WAIT_V(8); PG8_WAIT_L(0); PG8_BAR; PG8_MMA(1, 0, At, B0); PG8_MMA(1, 1, At, B1); PG8_BAR; PG8_SCHED;
.LBB0_281:
	s_add_i32 s4, s0, 0xff840080
	s_cmp_lg_u32 s24, 28
	s_cselect_b32 s4, s4, 0
	s_add_u32 s6, s34, s4
	s_addc_u32 s7, s35, 0
	s_add_i32 s25, 0, 0x10000
	s_add_u32 s4, s30, s4
	s_addc_u32 s5, s31, 0
	s_add_i32 s29, 0, 0x14000
	v_add_u32_e32 v158, s25, v144
	v_add_u32_e32 v174, s29, v144
	ds_read_b128 v[146:149], v158
	ds_read_b128 v[150:153], v158 offset:1024
	ds_read_b128 v[154:157], v158 offset:2048
	ds_read_b128 v[158:161], v158 offset:3072
	ds_read_b128 v[162:165], v174
	ds_read_b128 v[166:169], v174 offset:1024
	ds_read_b128 v[170:173], v174 offset:2048
	ds_read_b128 v[174:177], v174 offset:3072
	v_lshl_add_u64 v[202:203], v[138:139], 0, s[0:1]
	s_add_i32 m0, s8, 0xc000
	ds_read_b128 v[178:181], v145
	ds_read_b128 v[182:185], v145 offset:1024
	ds_read_b128 v[186:189], v145 offset:2048
	ds_read_b128 v[190:193], v145 offset:3072
	ds_read_b128 v[194:197], v145 offset:4096
	ds_read_b128 v[198:201], v145 offset:5120
	ds_read_b128 v[212:215], v145 offset:6144
	ds_read_b128 v[216:219], v145 offset:7168
	global_load_lds_dwordx4 v[202:203], off
	v_lshl_add_u64 v[202:203], v[140:141], 0, s[0:1]
	s_add_i32 m0, s8, 0xe000
	s_nop 0
	global_load_lds_dwordx4 v[202:203], off
	s_waitcnt vmcnt(8)
	s_waitcnt lgkmcnt(0)
	s_barrier
	s_setprio 1
	s_waitcnt lgkmcnt(0)
	v_mfma_f32_16x16x32_bf16 v[126:129], v[146:149], v[178:181], v[126:129]
	v_mfma_f32_16x16x32_bf16 v[122:125], v[154:157], v[178:181], v[122:125]
	v_mfma_f32_16x16x32_bf16 v[110:113], v[146:149], v[186:189], v[110:113]
	v_mfma_f32_16x16x32_bf16 v[106:109], v[154:157], v[186:189], v[106:109]
	v_mfma_f32_16x16x32_bf16 v[94:97], v[146:149], v[194:197], v[94:97]
	v_mfma_f32_16x16x32_bf16 v[90:93], v[154:157], v[194:197], v[90:93]
	v_mfma_f32_16x16x32_bf16 v[78:81], v[146:149], v[212:215], v[78:81]
	v_mfma_f32_16x16x32_bf16 v[74:77], v[154:157], v[212:215], v[74:77]
	v_mfma_f32_16x16x32_bf16 v[126:129], v[150:153], v[182:185], v[126:129]
	v_mfma_f32_16x16x32_bf16 v[122:125], v[158:161], v[182:185], v[122:125]
	v_mfma_f32_16x16x32_bf16 v[110:113], v[150:153], v[190:193], v[110:113]
	v_mfma_f32_16x16x32_bf16 v[106:109], v[158:161], v[190:193], v[106:109]
	v_mfma_f32_16x16x32_bf16 v[94:97], v[150:153], v[198:201], v[94:97]
	v_mfma_f32_16x16x32_bf16 v[90:93], v[158:161], v[198:201], v[90:93]
	v_mfma_f32_16x16x32_bf16 v[78:81], v[150:153], v[216:219], v[78:81]
	v_mfma_f32_16x16x32_bf16 v[74:77], v[158:161], v[216:219], v[74:77]
	s_setprio 0
	s_setprio 1
	v_mfma_f32_16x16x32_bf16 v[118:121], v[162:165], v[178:181], v[118:121]
	v_mfma_f32_16x16x32_bf16 v[114:117], v[170:173], v[178:181], v[114:117]
	v_mfma_f32_16x16x32_bf16 v[102:105], v[162:165], v[186:189], v[102:105]
	v_mfma_f32_16x16x32_bf16 v[98:101], v[170:173], v[186:189], v[98:101]
	v_mfma_f32_16x16x32_bf16 v[86:89], v[162:165], v[194:197], v[86:89]
	v_mfma_f32_16x16x32_bf16 v[82:85], v[170:173], v[194:197], v[82:85]
	v_mfma_f32_16x16x32_bf16 v[70:73], v[162:165], v[212:215], v[70:73]
	v_mfma_f32_16x16x32_bf16 v[66:69], v[170:173], v[212:215], v[66:69]
	v_mfma_f32_16x16x32_bf16 v[118:121], v[166:169], v[182:185], v[118:121]
	v_mfma_f32_16x16x32_bf16 v[114:117], v[174:177], v[182:185], v[114:117]
	v_mfma_f32_16x16x32_bf16 v[102:105], v[166:169], v[190:193], v[102:105]
	v_mfma_f32_16x16x32_bf16 v[98:101], v[174:177], v[190:193], v[98:101]
	v_mfma_f32_16x16x32_bf16 v[86:89], v[166:169], v[198:201], v[86:89]
	v_mfma_f32_16x16x32_bf16 v[82:85], v[174:177], v[198:201], v[82:85]
	v_mfma_f32_16x16x32_bf16 v[70:73], v[166:169], v[216:219], v[70:73]
	v_mfma_f32_16x16x32_bf16 v[66:69], v[174:177], v[216:219], v[66:69]
	s_setprio 0
	s_barrier
	s_add_i32 s25, s25, s3
	v_lshl_add_u64 v[202:203], s[4:5], 0, v[130:131]
	s_mov_b32 m0, s25
	ds_read_b128 v[178:181], v145 offset:16384
	ds_read_b128 v[182:185], v145 offset:17408
	ds_read_b128 v[186:189], v145 offset:18432
	ds_read_b128 v[190:193], v145 offset:19456
	ds_read_b128 v[194:197], v145 offset:20480
	ds_read_b128 v[198:201], v145 offset:21504
	ds_read_b128 v[212:215], v145 offset:22528
	ds_read_b128 v[216:219], v145 offset:23552
	global_load_lds_dwordx4 v[202:203], off
	s_add_i32 m0, s25, 0x2000
	s_add_u32 s26, s4, 0x20000
	v_lshl_add_u64 v[220:221], s[4:5], 0, v[132:133]
	s_addc_u32 s27, s5, 0
	s_add_i32 s25, s29, s3
	global_load_lds_dwordx4 v[220:221], off
	v_lshl_add_u64 v[222:223], s[26:27], 0, v[130:131]
	s_mov_b32 m0, s25
	v_lshl_add_u64 v[224:225], s[6:7], 0, v[134:135]
	global_load_lds_dwordx4 v[222:223], off
	v_lshl_add_u64 v[222:223], s[26:27], 0, v[132:133]
	s_add_i32 m0, s25, 0x2000
	s_nop 0
	global_load_lds_dwordx4 v[222:223], off
	v_lshl_add_u64 v[222:223], s[6:7], 0, v[136:137]
	s_mov_b32 m0, s8
	s_nop 0
	global_load_lds_dwordx4 v[222:223], off
	s_mov_b32 m0, s9
	s_nop 0
	global_load_lds_dwordx4 v[224:225], off
	s_waitcnt vmcnt(8)
	s_waitcnt lgkmcnt(0)
	s_barrier
; #define PG8_STAGE(bufoff, gbase, voff) do { _Pragma("unroll") for (int _i = 0; _i < 2; ++_i) \
;         __builtin_amdgcn_global_load_lds((const unsigned*)((const char*)(gbase) + (voff)[_i]), (LAS unsigned*)(lds + (bufoff) + ldsw + _i * 8192), 16, 0, 0); } while (0)
; #define PG8_LDA(dst, b, h) do { _Pragma("unroll") for (int m = 0; m < 4; ++m) _Pragma("unroll") for (int k = 0; k < 2; ++k) dst[m][k] = *(const LAS bf16x8*)(lds + PG8_SA(b, h) + aoff + m * 2048 + k * 1024); } while (0)
; #define PG8_LDB(dst, b, h) do { _Pragma("unroll") for (int n = 0; n < 2; ++n) _Pragma("unroll") for (int k = 0; k < 2; ++k) dst[n][k] = *(const LAS bf16x8*)(lds + PG8_SB(b, h) + boff + n * 2048 + k * 1024); } while (0)
; #define PG8_MMA(ai, bj, At, Bt) do { __builtin_amdgcn_s_setprio(1); _Pragma("unroll") for (int m = 0; m < 4; ++m) _Pragma("unroll") for (int n = 0; n < 2; ++n) _Pragma("unroll") for (int k = 0; k < 2; ++k) \
;         acc[ai][bj][m][n] = mma16<I8>(Bt[n][k], At[m][k], acc[ai][bj][m][n]); __builtin_amdgcn_s_setprio(0); } while (0)
; #define PG8_WAIT_V(n) asm volatile("s_waitcnt vmcnt(" #n ")" ::: "memory")
; #define PG8_WAIT_L(n) asm volatile("s_waitcnt lgkmcnt(" #n ")" ::: "memory")
; #define PG8_BAR __builtin_amdgcn_s_barrier()
; #define PG8_SCHED __builtin_amdgcn_sched_barrier(0)
; template <class Epi, class Sched, bool I8 = false>
; __device__ __forceinline__ void gemm_phase(LAS unsigned char* lds, const Gemm g, const Sched& S, const Epi& E) {
;     ...
;             PG8_WAIT_V(8); PG8_WAIT_L(0); PG8_BAR; PG8_MMA(1, 0, At, B0); PG8_MMA(1, 1, At, B1); PG8_BAR; PG8_SCHED;
;             PG8_LDB(B0, 1, 0); PG8_LDB(B1, 1, 1); PG8_SCHED; PG8_LDA(At, 1, 0); PG8_STAGE(PG8_SA(0, 1), a2 + hstepA, voffA);
;             PG8_WAIT_V(8); PG8_WAIT_L(0); PG8_BAR; PG8_MMA(0, 0, At, B0); PG8_MMA(0, 1, At, B1); PG8_BAR; PG8_SCHED;
	s_setprio 1
	s_waitcnt lgkmcnt(0)
	v_mfma_f32_16x16x32_bf16 v[62:65], v[146:149], v[178:181], v[62:65]
	v_mfma_f32_16x16x32_bf16 v[58:61], v[154:157], v[178:181], v[58:61]
	v_mfma_f32_16x16x32_bf16 v[46:49], v[146:149], v[186:189], v[46:49]
	v_mfma_f32_16x16x32_bf16 v[42:45], v[154:157], v[186:189], v[42:45]
	v_mfma_f32_16x16x32_bf16 v[30:33], v[146:149], v[194:197], v[30:33]
	v_mfma_f32_16x16x32_bf16 v[26:29], v[154:157], v[194:197], v[26:29]
	v_mfma_f32_16x16x32_bf16 v[14:17], v[146:149], v[212:215], v[14:17]
	v_mfma_f32_16x16x32_bf16 v[10:13], v[154:157], v[212:215], v[10:13]
	v_mfma_f32_16x16x32_bf16 v[62:65], v[150:153], v[182:185], v[62:65]
	v_mfma_f32_16x16x32_bf16 v[58:61], v[158:161], v[182:185], v[58:61]
	v_mfma_f32_16x16x32_bf16 v[46:49], v[150:153], v[190:193], v[46:49]
	v_mfma_f32_16x16x32_bf16 v[42:45], v[158:161], v[190:193], v[42:45]
	v_mfma_f32_16x16x32_bf16 v[30:33], v[150:153], v[198:201], v[30:33]
	v_mfma_f32_16x16x32_bf16 v[26:29], v[158:161], v[198:201], v[26:29]
	v_mfma_f32_16x16x32_bf16 v[14:17], v[150:153], v[216:219], v[14:17]
	v_mfma_f32_16x16x32_bf16 v[10:13], v[158:161], v[216:219], v[10:13]
	s_setprio 0
	s_setprio 1
	v_mfma_f32_16x16x32_bf16 v[54:57], v[162:165], v[178:181], v[54:57]
	v_mfma_f32_16x16x32_bf16 v[50:53], v[170:173], v[178:181], v[50:53]
	v_mfma_f32_16x16x32_bf16 v[38:41], v[162:165], v[186:189], v[38:41]
	v_mfma_f32_16x16x32_bf16 v[34:37], v[170:173], v[186:189], v[34:37]
	v_mfma_f32_16x16x32_bf16 v[22:25], v[162:165], v[194:197], v[22:25]
	v_mfma_f32_16x16x32_bf16 v[18:21], v[170:173], v[194:197], v[18:21]
	v_mfma_f32_16x16x32_bf16 v[6:9], v[162:165], v[212:215], v[6:9]
	v_mfma_f32_16x16x32_bf16 v[2:5], v[170:173], v[212:215], v[2:5]
	v_mfma_f32_16x16x32_bf16 v[54:57], v[166:169], v[182:185], v[54:57]
	v_mfma_f32_16x16x32_bf16 v[50:53], v[174:177], v[182:185], v[50:53]
	v_mfma_f32_16x16x32_bf16 v[38:41], v[166:169], v[190:193], v[38:41]
	v_mfma_f32_16x16x32_bf16 v[34:37], v[174:177], v[190:193], v[34:37]
	v_mfma_f32_16x16x32_bf16 v[22:25], v[166:169], v[198:201], v[22:25]
	v_mfma_f32_16x16x32_bf16 v[18:21], v[174:177], v[198:201], v[18:21]
	v_mfma_f32_16x16x32_bf16 v[6:9], v[166:169], v[216:219], v[6:9]
	v_mfma_f32_16x16x32_bf16 v[2:5], v[174:177], v[216:219], v[2:5]
	s_setprio 0
	s_barrier
	s_add_i32 s25, 0, 0x18000
	s_add_i32 s26, 0, 0x1c000
	v_add_u32_e32 v158, s25, v144
	v_add_u32_e32 v174, s26, v144
	ds_read_b128 v[146:149], v158
	ds_read_b128 v[150:153], v158 offset:1024
	ds_read_b128 v[154:157], v158 offset:2048
	ds_read_b128 v[158:161], v158 offset:3072
	ds_read_b128 v[162:165], v174
	ds_read_b128 v[166:169], v174 offset:1024
	ds_read_b128 v[170:173], v174 offset:2048
	ds_read_b128 v[174:177], v174 offset:3072
	s_add_u32 s6, s6, 0x80000
	s_addc_u32 s7, s7, 0
	s_mov_b32 m0, s14
	v_lshl_add_u64 v[226:227], s[6:7], 0, v[136:137]
	ds_read_b128 v[178:181], v145 offset:32768
	ds_read_b128 v[182:185], v145 offset:33792
	ds_read_b128 v[186:189], v145 offset:34816
	ds_read_b128 v[190:193], v145 offset:35840
	ds_read_b128 v[194:197], v145 offset:36864
	ds_read_b128 v[198:201], v145 offset:37888
	ds_read_b128 v[212:215], v145 offset:38912
	ds_read_b128 v[216:219], v145 offset:39936
	global_load_lds_dwordx4 v[226:227], off
	v_lshl_add_u64 v[226:227], s[6:7], 0, v[134:135]
	s_mov_b32 m0, s16
	s_nop 0
	global_load_lds_dwordx4 v[226:227], off
	s_waitcnt vmcnt(8)
	s_waitcnt lgkmcnt(0)
	s_barrier
	s_setprio 1
	s_waitcnt lgkmcnt(0)
	v_mfma_f32_16x16x32_bf16 v[126:129], v[146:149], v[178:181], v[126:129]
	v_mfma_f32_16x16x32_bf16 v[122:125], v[154:157], v[178:181], v[122:125]
	v_mfma_f32_16x16x32_bf16 v[110:113], v[146:149], v[186:189], v[110:113]
	v_mfma_f32_16x16x32_bf16 v[106:109], v[154:157], v[186:189], v[106:109]
	v_mfma_f32_16x16x32_bf16 v[94:97], v[146:149], v[194:197], v[94:97]
	v_mfma_f32_16x16x32_bf16 v[90:93], v[154:157], v[194:197], v[90:93]
	v_mfma_f32_16x16x32_bf16 v[78:81], v[146:149], v[212:215], v[78:81]
	v_mfma_f32_16x16x32_bf16 v[74:77], v[154:157], v[212:215], v[74:77]
	v_mfma_f32_16x16x32_bf16 v[126:129], v[150:153], v[182:185], v[126:129]
	v_mfma_f32_16x16x32_bf16 v[122:125], v[158:161], v[182:185], v[122:125]
	v_mfma_f32_16x16x32_bf16 v[110:113], v[150:153], v[190:193], v[110:113]
	v_mfma_f32_16x16x32_bf16 v[106:109], v[158:161], v[190:193], v[106:109]
	v_mfma_f32_16x16x32_bf16 v[94:97], v[150:153], v[198:201], v[94:97]
	v_mfma_f32_16x16x32_bf16 v[90:93], v[158:161], v[198:201], v[90:93]
	v_mfma_f32_16x16x32_bf16 v[78:81], v[150:153], v[216:219], v[78:81]
	v_mfma_f32_16x16x32_bf16 v[74:77], v[158:161], v[216:219], v[74:77]
	s_setprio 0
	s_setprio 1
	v_mfma_f32_16x16x32_bf16 v[118:121], v[162:165], v[178:181], v[118:121]
	v_mfma_f32_16x16x32_bf16 v[114:117], v[170:173], v[178:181], v[114:117]
	v_mfma_f32_16x16x32_bf16 v[102:105], v[162:165], v[186:189], v[102:105]
	v_mfma_f32_16x16x32_bf16 v[98:101], v[170:173], v[186:189], v[98:101]
	v_mfma_f32_16x16x32_bf16 v[86:89], v[162:165], v[194:197], v[86:89]
	v_mfma_f32_16x16x32_bf16 v[82:85], v[170:173], v[194:197], v[82:85]
	v_mfma_f32_16x16x32_bf16 v[70:73], v[162:165], v[212:215], v[70:73]
	v_mfma_f32_16x16x32_bf16 v[66:69], v[170:173], v[212:215], v[66:69]
	v_mfma_f32_16x16x32_bf16 v[118:121], v[166:169], v[182:185], v[118:121]
	v_mfma_f32_16x16x32_bf16 v[114:117], v[174:177], v[182:185], v[114:117]
	v_mfma_f32_16x16x32_bf16 v[102:105], v[166:169], v[190:193], v[102:105]
	v_mfma_f32_16x16x32_bf16 v[98:101], v[174:177], v[190:193], v[98:101]
	v_mfma_f32_16x16x32_bf16 v[86:89], v[166:169], v[198:201], v[86:89]
	v_mfma_f32_16x16x32_bf16 v[82:85], v[174:177], v[198:201], v[82:85]
	v_mfma_f32_16x16x32_bf16 v[70:73], v[166:169], v[216:219], v[70:73]
	v_mfma_f32_16x16x32_bf16 v[66:69], v[174:177], v[216:219], v[66:69]
	s_setprio 0
	s_barrier
; #define PG8_STAGE(bufoff, gbase, voff) do { _Pragma("unroll") for (int _i = 0; _i < 2; ++_i) \
;         __builtin_amdgcn_global_load_lds((const unsigned*)((const char*)(gbase) + (voff)[_i]), (LAS unsigned*)(lds + (bufoff) + ldsw + _i * 8192), 16, 0, 0); } while (0)
; #define PG8_LDA(dst, b, h) do { _Pragma("unroll") for (int m = 0; m < 4; ++m) _Pragma("unroll") for (int k = 0; k < 2; ++k) dst[m][k] = *(const LAS bf16x8*)(lds + PG8_SA(b, h) + aoff + m * 2048 + k * 1024); } while (0)
; #define PG8_MMA(ai, bj, At, Bt) do { __builtin_amdgcn_s_setprio(1); _Pragma("unroll") for (int m = 0; m < 4; ++m) _Pragma("unroll") for (int n = 0; n < 2; ++n) _Pragma("unroll") for (int k = 0; k < 2; ++k) \
;         acc[ai][bj][m][n] = mma16<I8>(Bt[n][k], At[m][k], acc[ai][bj][m][n]); __builtin_amdgcn_s_setprio(0); } while (0)
; #define PG8_WAIT_V(n) asm volatile("s_waitcnt vmcnt(" #n ")" ::: "memory")
; #define PG8_WAIT_L(n) asm volatile("s_waitcnt lgkmcnt(" #n ")" ::: "memory")
; #define PG8_BAR __builtin_amdgcn_s_barrier()
; #define PG8_SCHED __builtin_amdgcn_sched_barrier(0)
; template <class Epi, class Sched, bool I8 = false>
; __device__ __forceinline__ void gemm_phase(LAS unsigned char* lds, const Gemm g, const Sched& S, const Epi& E) {
;     ...
;         for (int t = 0; t < nt; t += 2) {
;             const bool last = (t == nt - 2);
;             const char* a1 = cA + (size_t)(t + 1) * kstep;
;             const char* a2 = last ? nA : cA + (size_t)(t + 2) * kstep; const char* b2 = last ? nB : cB + (size_t)(t + 2) * kstep;
;             const char* a3 = a2 + kstep; const char* b3 = b2 + kstep;
;     ...
;             PG8_LDA(At, 1, 1); PG8_STAGE(PG8_SB(1, 0), b3, voffB); PG8_STAGE(PG8_SB(1, 1), b3 + hstepB, voffB); PG8_STAGE(PG8_SA(1, 0), a3, voffA);
;             PG8_WAIT_V(8); PG8_WAIT_L(0); PG8_BAR; PG8_MMA(1, 0, At, B0); PG8_MMA(1, 1, At, B1); PG8_BAR; PG8_SCHED;
	s_add_i32 s6, s25, s3
	v_lshl_add_u64 v[202:203], v[202:203], 0, s[12:13]
	s_mov_b32 m0, s6
	ds_read_b128 v[178:181], v145 offset:49152
	ds_read_b128 v[182:185], v145 offset:50176
	ds_read_b128 v[186:189], v145 offset:51200
	ds_read_b128 v[190:193], v145 offset:52224
	ds_read_b128 v[194:197], v145 offset:53248
	ds_read_b128 v[198:201], v145 offset:54272
	ds_read_b128 v[212:215], v145 offset:55296
	ds_read_b128 v[216:219], v145 offset:56320
	global_load_lds_dwordx4 v[202:203], off
	s_add_i32 m0, s6, 0x2000
	s_add_u32 s4, s4, 0x20080
	v_lshl_add_u64 v[202:203], v[220:221], 0, s[12:13]
	s_addc_u32 s5, s5, 0
	s_add_i32 s6, s26, s3
	global_load_lds_dwordx4 v[202:203], off
	v_lshl_add_u64 v[202:203], s[4:5], 0, v[130:131]
	s_mov_b32 m0, s6
	s_nop 0
	global_load_lds_dwordx4 v[202:203], off
	v_lshl_add_u64 v[202:203], s[4:5], 0, v[132:133]
	s_add_i32 m0, s6, 0x2000
	s_nop 0
	global_load_lds_dwordx4 v[202:203], off
	v_lshl_add_u64 v[202:203], v[222:223], 0, s[12:13]
	s_mov_b32 m0, s22
	s_nop 0
	global_load_lds_dwordx4 v[202:203], off
	v_lshl_add_u64 v[202:203], v[224:225], 0, s[12:13]
	s_mov_b32 m0, s23
	s_nop 0
	global_load_lds_dwordx4 v[202:203], off
	s_waitcnt vmcnt(8)
	s_waitcnt lgkmcnt(0)
	s_barrier
	s_setprio 1
	s_waitcnt lgkmcnt(0)
	v_mfma_f32_16x16x32_bf16 v[62:65], v[146:149], v[178:181], v[62:65]
	v_mfma_f32_16x16x32_bf16 v[58:61], v[154:157], v[178:181], v[58:61]
	v_mfma_f32_16x16x32_bf16 v[46:49], v[146:149], v[186:189], v[46:49]
	v_mfma_f32_16x16x32_bf16 v[42:45], v[154:157], v[186:189], v[42:45]
	v_mfma_f32_16x16x32_bf16 v[30:33], v[146:149], v[194:197], v[30:33]
	v_mfma_f32_16x16x32_bf16 v[26:29], v[154:157], v[194:197], v[26:29]
	v_mfma_f32_16x16x32_bf16 v[14:17], v[146:149], v[212:215], v[14:17]
	v_mfma_f32_16x16x32_bf16 v[10:13], v[154:157], v[212:215], v[10:13]
	v_mfma_f32_16x16x32_bf16 v[62:65], v[150:153], v[182:185], v[62:65]
	v_mfma_f32_16x16x32_bf16 v[58:61], v[158:161], v[182:185], v[58:61]
	v_mfma_f32_16x16x32_bf16 v[46:49], v[150:153], v[190:193], v[46:49]
	v_mfma_f32_16x16x32_bf16 v[42:45], v[158:161], v[190:193], v[42:45]
	v_mfma_f32_16x16x32_bf16 v[30:33], v[150:153], v[198:201], v[30:33]
	v_mfma_f32_16x16x32_bf16 v[26:29], v[158:161], v[198:201], v[26:29]
	v_mfma_f32_16x16x32_bf16 v[14:17], v[150:153], v[216:219], v[14:17]
	v_mfma_f32_16x16x32_bf16 v[10:13], v[158:161], v[216:219], v[10:13]
	s_setprio 0
	s_setprio 1
	v_mfma_f32_16x16x32_bf16 v[54:57], v[162:165], v[178:181], v[54:57]
	v_mfma_f32_16x16x32_bf16 v[50:53], v[170:173], v[178:181], v[50:53]
	v_mfma_f32_16x16x32_bf16 v[38:41], v[162:165], v[186:189], v[38:41]
	v_mfma_f32_16x16x32_bf16 v[34:37], v[170:173], v[186:189], v[34:37]
	v_mfma_f32_16x16x32_bf16 v[22:25], v[162:165], v[194:197], v[22:25]
	v_mfma_f32_16x16x32_bf16 v[18:21], v[170:173], v[194:197], v[18:21]
	v_mfma_f32_16x16x32_bf16 v[6:9], v[162:165], v[212:215], v[6:9]
	v_mfma_f32_16x16x32_bf16 v[2:5], v[170:173], v[212:215], v[2:5]
	v_mfma_f32_16x16x32_bf16 v[54:57], v[166:169], v[182:185], v[54:57]
	v_mfma_f32_16x16x32_bf16 v[50:53], v[174:177], v[182:185], v[50:53]
	v_mfma_f32_16x16x32_bf16 v[38:41], v[166:169], v[190:193], v[38:41]
	v_mfma_f32_16x16x32_bf16 v[34:37], v[174:177], v[190:193], v[34:37]
	v_mfma_f32_16x16x32_bf16 v[22:25], v[166:169], v[198:201], v[22:25]
	v_mfma_f32_16x16x32_bf16 v[18:21], v[174:177], v[198:201], v[18:21]
	v_mfma_f32_16x16x32_bf16 v[6:9], v[166:169], v[216:219], v[6:9]
	v_mfma_f32_16x16x32_bf16 v[2:5], v[174:177], v[216:219], v[2:5]
	s_setprio 0
	s_add_i32 s24, s24, 2
	s_add_u32 s0, s0, 0x100
	s_addc_u32 s1, s1, 0
	s_cmp_gt_u32 s24, 29
	s_barrier
	s_cbranch_scc0 .LBB0_281
	s_cmpk_lt_u32 s2, 0x100
	v_readlane_b32 s22, v249, 31
	v_readlane_b32 s23, v249, 32
	s_cbranch_scc0 .LBB0_284
	s_barrier

; #define PG8_STAGE(bufoff, gbase, voff) do { _Pragma("unroll") for (int _i = 0; _i < 2; ++_i) \
;         __builtin_amdgcn_global_load_lds((const unsigned*)((const char*)(gbase) + (voff)[_i]), (LAS unsigned*)(lds + (bufoff) + ldsw + _i * 8192), 16, 0, 0); } while (0)
; #define PG8_LDA(dst, b, h) do { _Pragma("unroll") for (int m = 0; m < 4; ++m) _Pragma("unroll") for (int k = 0; k < 2; ++k) dst[m][k] = *(const LAS bf16x8*)(lds + PG8_SA(b, h) + aoff + m * 2048 + k * 1024); } while (0)
; #define PG8_LDB(dst, b, h) do { _Pragma("unroll") for (int n = 0; n < 2; ++n) _Pragma("unroll") for (int k = 0; k < 2; ++k) dst[n][k] = *(const LAS bf16x8*)(lds + PG8_SB(b, h) + boff + n * 2048 + k * 1024); } while (0)
; #define PG8_MMA(ai, bj, At, Bt) do { __builtin_amdgcn_s_setprio(1); _Pragma("unroll") for (int m = 0; m < 4; ++m) _Pragma("unroll") for (int n = 0; n < 2; ++n) _Pragma("unroll") for (int k = 0; k < 2; ++k) \
;         acc[ai][bj][m][n] = mma16<I8>(Bt[n][k], At[m][k], acc[ai][bj][m][n]); __builtin_amdgcn_s_setprio(0); } while (0)
; #define PG8_WAIT_V(n) asm volatile("s_waitcnt vmcnt(" #n ")" ::: "memory")
; #define PG8_WAIT_L(n) asm volatile("s_waitcnt lgkmcnt(" #n ")" ::: "memory")
; #define PG8_BAR __builtin_amdgcn_s_barrier()
; #define PG8_SCHED __builtin_amdgcn_sched_barrier(0)
; template <class Epi, class Sched, bool I8 = false>
; __device__ __forceinline__ void gemm_phase(LAS unsigned char* lds, const Gemm g, const Sched& S, const Epi& E) {
;     ...
;         for (int t = 0; t < nt; t += 2) {
;             const bool last = (t == nt - 2);
;             const char* a1 = cA + (size_t)(t + 1) * kstep;
;             const char* a2 = last ? nA : cA + (size_t)(t + 2) * kstep; const char* b2 = last ? nB : cB + (size_t)(t + 2) * kstep;
;             const char* a3 = a2 + kstep; const char* b3 = b2 + kstep;
;             if (PG8_SP2) {
;             PG8_LDB(B0, 0, 0); PG8_LDB(B1, 0, 1); PG8_SCHED; PG8_LDA(At, 0, 0); PG8_STAGE(PG8_SA(1, 1), a1 + hstepA, voffA);
;             PG8_WAIT_V(8); PG8_WAIT_L(0); PG8_BAR; PG8_MMA(0, 0, At, B0); PG8_MMA(0, 1, At, B1); PG8_BAR; PG8_SCHED;
;             PG8_LDA(At, 0, 1); PG8_STAGE(PG8_SB(0, 0), b2, voffB); PG8_STAGE(PG8_SB(0, 1), b2 + hstepB, voffB); PG8_STAGE(PG8_SA(0, 0), a2, voffA);
;             PG8_WAIT_V(8); PG8_WAIT_L(0); PG8_BAR; PG8_MMA(1, 0, At, B0); PG8_MMA(1, 1, At, B1); PG8_BAR; PG8_SCHED;
.LBB0_356:
	s_add_u32 s4, s0, 0xfff80080
	s_addc_u32 s5, s1, -1
	s_add_i32 s30, 0, 0x10000
	s_cmp_eq_u32 s29, 28
	s_cselect_b32 s7, s14, s5
	s_cselect_b32 s6, s21, s4
	v_add_u32_e32 v130, s30, v141
	s_cselect_b32 s5, s22, s25
	s_cselect_b32 s4, s23, s24
	s_add_i32 s34, 0, 0x14000
	ds_read_b128 v[150:153], v130
	ds_read_b128 v[154:157], v130 offset:1024
	ds_read_b128 v[158:161], v130 offset:2048
	ds_read_b128 v[162:165], v130 offset:3072
	v_add_u32_e32 v130, s34, v141
	ds_read_b128 v[166:169], v130
	ds_read_b128 v[170:173], v130 offset:1024
	ds_read_b128 v[174:177], v130 offset:2048
	ds_read_b128 v[178:181], v130 offset:3072
	v_lshl_add_u64 v[202:203], s[0:1], 0, v[146:147]
	s_add_i32 m0, s41, 0xc000
	ds_read_b128 v[182:185], v143
	ds_read_b128 v[186:189], v143 offset:1024
	ds_read_b128 v[190:193], v143 offset:2048
	ds_read_b128 v[194:197], v143 offset:3072
	ds_read_b128 v[198:201], v143 offset:4096
	ds_read_b128 v[212:215], v143 offset:5120
	ds_read_b128 v[216:219], v143 offset:6144
	ds_read_b128 v[220:223], v143 offset:7168
	global_load_lds_dwordx4 v[202:203], off
	v_lshl_add_u64 v[202:203], s[0:1], 0, v[148:149]
	s_add_i32 m0, s41, 0xe000
	s_nop 0
	global_load_lds_dwordx4 v[202:203], off
	s_waitcnt vmcnt(8)
	s_waitcnt lgkmcnt(0)
	s_barrier
	s_setprio 1
	s_waitcnt lgkmcnt(0)
	v_mfma_f32_16x16x32_bf16 v[126:129], v[150:153], v[182:185], v[126:129]
	v_mfma_f32_16x16x32_bf16 v[122:125], v[158:161], v[182:185], v[122:125]
	v_mfma_f32_16x16x32_bf16 v[110:113], v[150:153], v[190:193], v[110:113]
	v_mfma_f32_16x16x32_bf16 v[106:109], v[158:161], v[190:193], v[106:109]
	v_mfma_f32_16x16x32_bf16 v[94:97], v[150:153], v[198:201], v[94:97]
	v_mfma_f32_16x16x32_bf16 v[90:93], v[158:161], v[198:201], v[90:93]
	v_mfma_f32_16x16x32_bf16 v[78:81], v[150:153], v[216:219], v[78:81]
	v_mfma_f32_16x16x32_bf16 v[74:77], v[158:161], v[216:219], v[74:77]
	v_mfma_f32_16x16x32_bf16 v[126:129], v[154:157], v[186:189], v[126:129]
	v_mfma_f32_16x16x32_bf16 v[122:125], v[162:165], v[186:189], v[122:125]
	v_mfma_f32_16x16x32_bf16 v[110:113], v[154:157], v[194:197], v[110:113]
	v_mfma_f32_16x16x32_bf16 v[106:109], v[162:165], v[194:197], v[106:109]
	v_mfma_f32_16x16x32_bf16 v[94:97], v[154:157], v[212:215], v[94:97]
	v_mfma_f32_16x16x32_bf16 v[90:93], v[162:165], v[212:215], v[90:93]
	v_mfma_f32_16x16x32_bf16 v[78:81], v[154:157], v[220:223], v[78:81]
	v_mfma_f32_16x16x32_bf16 v[74:77], v[162:165], v[220:223], v[74:77]
	s_setprio 0
	s_setprio 1
	v_mfma_f32_16x16x32_bf16 v[118:121], v[166:169], v[182:185], v[118:121]
	v_mfma_f32_16x16x32_bf16 v[114:117], v[174:177], v[182:185], v[114:117]
	v_mfma_f32_16x16x32_bf16 v[102:105], v[166:169], v[190:193], v[102:105]
	v_mfma_f32_16x16x32_bf16 v[98:101], v[174:177], v[190:193], v[98:101]
	v_mfma_f32_16x16x32_bf16 v[86:89], v[166:169], v[198:201], v[86:89]
	v_mfma_f32_16x16x32_bf16 v[82:85], v[174:177], v[198:201], v[82:85]
	v_mfma_f32_16x16x32_bf16 v[70:73], v[166:169], v[216:219], v[70:73]
	v_mfma_f32_16x16x32_bf16 v[66:69], v[174:177], v[216:219], v[66:69]
	v_mfma_f32_16x16x32_bf16 v[118:121], v[170:173], v[186:189], v[118:121]
	v_mfma_f32_16x16x32_bf16 v[114:117], v[178:181], v[186:189], v[114:117]
	v_mfma_f32_16x16x32_bf16 v[102:105], v[170:173], v[194:197], v[102:105]
	v_mfma_f32_16x16x32_bf16 v[98:101], v[178:181], v[194:197], v[98:101]
	v_mfma_f32_16x16x32_bf16 v[86:89], v[170:173], v[212:215], v[86:89]
	v_mfma_f32_16x16x32_bf16 v[82:85], v[178:181], v[212:215], v[82:85]
	v_mfma_f32_16x16x32_bf16 v[70:73], v[170:173], v[220:223], v[70:73]
	v_mfma_f32_16x16x32_bf16 v[66:69], v[178:181], v[220:223], v[66:69]
	s_setprio 0
	s_barrier
	s_add_i32 s30, s30, s40
	v_lshl_add_u64 v[202:203], s[4:5], 0, v[136:137]
	s_mov_b32 m0, s30
	ds_read_b128 v[182:185], v143 offset:16384
	ds_read_b128 v[186:189], v143 offset:17408
	ds_read_b128 v[190:193], v143 offset:18432
	ds_read_b128 v[194:197], v143 offset:19456
	ds_read_b128 v[198:201], v143 offset:20480
	ds_read_b128 v[212:215], v143 offset:21504
	ds_read_b128 v[216:219], v143 offset:22528
	ds_read_b128 v[220:223], v143 offset:23552
	global_load_lds_dwordx4 v[202:203], off
	s_add_i32 m0, s30, 0x2000
	s_add_u32 s30, s4, 0x20000
	v_lshl_add_u64 v[224:225], s[4:5], 0, v[132:133]
	s_addc_u32 s31, s5, 0
	s_add_i32 s34, s34, s40
	global_load_lds_dwordx4 v[224:225], off
	v_lshl_add_u64 v[226:227], s[30:31], 0, v[136:137]
	s_mov_b32 m0, s34
	v_lshl_add_u64 v[228:229], s[6:7], 0, v[134:135]
	global_load_lds_dwordx4 v[226:227], off
	v_lshl_add_u64 v[226:227], s[30:31], 0, v[132:133]
	s_add_i32 m0, s34, 0x2000
	s_nop 0
	global_load_lds_dwordx4 v[226:227], off
	v_lshl_add_u64 v[226:227], s[6:7], 0, v[138:139]
	s_mov_b32 m0, s41
	s_nop 0
	global_load_lds_dwordx4 v[226:227], off
	s_mov_b32 m0, s42
	s_nop 0
	global_load_lds_dwordx4 v[228:229], off
	s_waitcnt vmcnt(8)
	s_waitcnt lgkmcnt(0)
	s_barrier
; #define PG8_STAGE(bufoff, gbase, voff) do { _Pragma("unroll") for (int _i = 0; _i < 2; ++_i) \
;         __builtin_amdgcn_global_load_lds((const unsigned*)((const char*)(gbase) + (voff)[_i]), (LAS unsigned*)(lds + (bufoff) + ldsw + _i * 8192), 16, 0, 0); } while (0)
; #define PG8_LDA(dst, b, h) do { _Pragma("unroll") for (int m = 0; m < 4; ++m) _Pragma("unroll") for (int k = 0; k < 2; ++k) dst[m][k] = *(const LAS bf16x8*)(lds + PG8_SA(b, h) + aoff + m * 2048 + k * 1024); } while (0)
; #define PG8_LDB(dst, b, h) do { _Pragma("unroll") for (int n = 0; n < 2; ++n) _Pragma("unroll") for (int k = 0; k < 2; ++k) dst[n][k] = *(const LAS bf16x8*)(lds + PG8_SB(b, h) + boff + n * 2048 + k * 1024); } while (0)
; #define PG8_MMA(ai, bj, At, Bt) do { __builtin_amdgcn_s_setprio(1); _Pragma("unroll") for (int m = 0; m < 4; ++m) _Pragma("unroll") for (int n = 0; n < 2; ++n) _Pragma("unroll") for (int k = 0; k < 2; ++k) \
;         acc[ai][bj][m][n] = mma16<I8>(Bt[n][k], At[m][k], acc[ai][bj][m][n]); __builtin_amdgcn_s_setprio(0); } while (0)
; #define PG8_WAIT_V(n) asm volatile("s_waitcnt vmcnt(" #n ")" ::: "memory")
; #define PG8_WAIT_L(n) asm volatile("s_waitcnt lgkmcnt(" #n ")" ::: "memory")
; #define PG8_BAR __builtin_amdgcn_s_barrier()
; #define PG8_SCHED __builtin_amdgcn_sched_barrier(0)
; template <class Epi, class Sched, bool I8 = false>
; __device__ __forceinline__ void gemm_phase(LAS unsigned char* lds, const Gemm g, const Sched& S, const Epi& E) {
;     ...
;             PG8_WAIT_V(8); PG8_WAIT_L(0); PG8_BAR; PG8_MMA(1, 0, At, B0); PG8_MMA(1, 1, At, B1); PG8_BAR; PG8_SCHED;
;             PG8_LDB(B0, 1, 0); PG8_LDB(B1, 1, 1); PG8_SCHED; PG8_LDA(At, 1, 0); PG8_STAGE(PG8_SA(0, 1), a2 + hstepA, voffA);
;             PG8_WAIT_V(8); PG8_WAIT_L(0); PG8_BAR; PG8_MMA(0, 0, At, B0); PG8_MMA(0, 1, At, B1); PG8_BAR; PG8_SCHED;
	s_setprio 1
	s_waitcnt lgkmcnt(0)
	v_mfma_f32_16x16x32_bf16 v[62:65], v[150:153], v[182:185], v[62:65]
	v_mfma_f32_16x16x32_bf16 v[58:61], v[158:161], v[182:185], v[58:61]
	v_mfma_f32_16x16x32_bf16 v[46:49], v[150:153], v[190:193], v[46:49]
	v_mfma_f32_16x16x32_bf16 v[42:45], v[158:161], v[190:193], v[42:45]
	v_mfma_f32_16x16x32_bf16 v[30:33], v[150:153], v[198:201], v[30:33]
	v_mfma_f32_16x16x32_bf16 v[26:29], v[158:161], v[198:201], v[26:29]
	v_mfma_f32_16x16x32_bf16 v[14:17], v[150:153], v[216:219], v[14:17]
	v_mfma_f32_16x16x32_bf16 v[10:13], v[158:161], v[216:219], v[10:13]
	v_mfma_f32_16x16x32_bf16 v[62:65], v[154:157], v[186:189], v[62:65]
	v_mfma_f32_16x16x32_bf16 v[58:61], v[162:165], v[186:189], v[58:61]
	v_mfma_f32_16x16x32_bf16 v[46:49], v[154:157], v[194:197], v[46:49]
	v_mfma_f32_16x16x32_bf16 v[42:45], v[162:165], v[194:197], v[42:45]
	v_mfma_f32_16x16x32_bf16 v[30:33], v[154:157], v[212:215], v[30:33]
	v_mfma_f32_16x16x32_bf16 v[26:29], v[162:165], v[212:215], v[26:29]
	v_mfma_f32_16x16x32_bf16 v[14:17], v[154:157], v[220:223], v[14:17]
	v_mfma_f32_16x16x32_bf16 v[10:13], v[162:165], v[220:223], v[10:13]
	s_setprio 0
	s_setprio 1
	v_mfma_f32_16x16x32_bf16 v[54:57], v[166:169], v[182:185], v[54:57]
	v_mfma_f32_16x16x32_bf16 v[50:53], v[174:177], v[182:185], v[50:53]
	v_mfma_f32_16x16x32_bf16 v[38:41], v[166:169], v[190:193], v[38:41]
	v_mfma_f32_16x16x32_bf16 v[34:37], v[174:177], v[190:193], v[34:37]
	v_mfma_f32_16x16x32_bf16 v[22:25], v[166:169], v[198:201], v[22:25]
	v_mfma_f32_16x16x32_bf16 v[18:21], v[174:177], v[198:201], v[18:21]
	v_mfma_f32_16x16x32_bf16 v[6:9], v[166:169], v[216:219], v[6:9]
	v_mfma_f32_16x16x32_bf16 v[2:5], v[174:177], v[216:219], v[2:5]
	v_mfma_f32_16x16x32_bf16 v[54:57], v[170:173], v[186:189], v[54:57]
	v_mfma_f32_16x16x32_bf16 v[50:53], v[178:181], v[186:189], v[50:53]
	v_mfma_f32_16x16x32_bf16 v[38:41], v[170:173], v[194:197], v[38:41]
	v_mfma_f32_16x16x32_bf16 v[34:37], v[178:181], v[194:197], v[34:37]
	v_mfma_f32_16x16x32_bf16 v[22:25], v[170:173], v[212:215], v[22:25]
	v_mfma_f32_16x16x32_bf16 v[18:21], v[178:181], v[212:215], v[18:21]
	v_mfma_f32_16x16x32_bf16 v[6:9], v[170:173], v[220:223], v[6:9]
	v_mfma_f32_16x16x32_bf16 v[2:5], v[178:181], v[220:223], v[2:5]
	s_setprio 0
	s_barrier
	s_add_i32 s30, 0, 0x18000
	v_add_u32_e32 v130, s30, v141
	s_add_i32 s31, 0, 0x1c000
	ds_read_b128 v[150:153], v130
	ds_read_b128 v[154:157], v130 offset:1024
	ds_read_b128 v[158:161], v130 offset:2048
	ds_read_b128 v[162:165], v130 offset:3072
	v_add_u32_e32 v130, s31, v141
	ds_read_b128 v[166:169], v130
	ds_read_b128 v[170:173], v130 offset:1024
	ds_read_b128 v[174:177], v130 offset:2048
	ds_read_b128 v[178:181], v130 offset:3072
	s_add_u32 s6, s6, 0x80000
	s_addc_u32 s7, s7, 0
	s_mov_b32 m0, s43
	v_lshl_add_u64 v[230:231], s[6:7], 0, v[138:139]
	ds_read_b128 v[182:185], v143 offset:32768
	ds_read_b128 v[186:189], v143 offset:33792
	ds_read_b128 v[190:193], v143 offset:34816
	ds_read_b128 v[194:197], v143 offset:35840
	ds_read_b128 v[198:201], v143 offset:36864
	ds_read_b128 v[212:215], v143 offset:37888
	ds_read_b128 v[216:219], v143 offset:38912
	ds_read_b128 v[220:223], v143 offset:39936
	global_load_lds_dwordx4 v[230:231], off
	v_lshl_add_u64 v[230:231], s[6:7], 0, v[134:135]
	s_mov_b32 m0, s44
	s_nop 0
	global_load_lds_dwordx4 v[230:231], off
	s_waitcnt vmcnt(8)
	s_waitcnt lgkmcnt(0)
	s_barrier
	s_setprio 1
	s_waitcnt lgkmcnt(0)
	v_mfma_f32_16x16x32_bf16 v[126:129], v[150:153], v[182:185], v[126:129]
	v_mfma_f32_16x16x32_bf16 v[122:125], v[158:161], v[182:185], v[122:125]
	v_mfma_f32_16x16x32_bf16 v[110:113], v[150:153], v[190:193], v[110:113]
	v_mfma_f32_16x16x32_bf16 v[106:109], v[158:161], v[190:193], v[106:109]
	v_mfma_f32_16x16x32_bf16 v[94:97], v[150:153], v[198:201], v[94:97]
	v_mfma_f32_16x16x32_bf16 v[90:93], v[158:161], v[198:201], v[90:93]
	v_mfma_f32_16x16x32_bf16 v[78:81], v[150:153], v[216:219], v[78:81]
	v_mfma_f32_16x16x32_bf16 v[74:77], v[158:161], v[216:219], v[74:77]
	v_mfma_f32_16x16x32_bf16 v[126:129], v[154:157], v[186:189], v[126:129]
	v_mfma_f32_16x16x32_bf16 v[122:125], v[162:165], v[186:189], v[122:125]
	v_mfma_f32_16x16x32_bf16 v[110:113], v[154:157], v[194:197], v[110:113]
	v_mfma_f32_16x16x32_bf16 v[106:109], v[162:165], v[194:197], v[106:109]
	v_mfma_f32_16x16x32_bf16 v[94:97], v[154:157], v[212:215], v[94:97]
	v_mfma_f32_16x16x32_bf16 v[90:93], v[162:165], v[212:215], v[90:93]
	v_mfma_f32_16x16x32_bf16 v[78:81], v[154:157], v[220:223], v[78:81]
	v_mfma_f32_16x16x32_bf16 v[74:77], v[162:165], v[220:223], v[74:77]
	s_setprio 0
	s_setprio 1
	v_mfma_f32_16x16x32_bf16 v[118:121], v[166:169], v[182:185], v[118:121]
	v_mfma_f32_16x16x32_bf16 v[114:117], v[174:177], v[182:185], v[114:117]
	v_mfma_f32_16x16x32_bf16 v[102:105], v[166:169], v[190:193], v[102:105]
	v_mfma_f32_16x16x32_bf16 v[98:101], v[174:177], v[190:193], v[98:101]
	v_mfma_f32_16x16x32_bf16 v[86:89], v[166:169], v[198:201], v[86:89]
	v_mfma_f32_16x16x32_bf16 v[82:85], v[174:177], v[198:201], v[82:85]
	v_mfma_f32_16x16x32_bf16 v[70:73], v[166:169], v[216:219], v[70:73]
	v_mfma_f32_16x16x32_bf16 v[66:69], v[174:177], v[216:219], v[66:69]
	v_mfma_f32_16x16x32_bf16 v[118:121], v[170:173], v[186:189], v[118:121]
	v_mfma_f32_16x16x32_bf16 v[114:117], v[178:181], v[186:189], v[114:117]
	v_mfma_f32_16x16x32_bf16 v[102:105], v[170:173], v[194:197], v[102:105]
	v_mfma_f32_16x16x32_bf16 v[98:101], v[178:181], v[194:197], v[98:101]
	v_mfma_f32_16x16x32_bf16 v[86:89], v[170:173], v[212:215], v[86:89]
	v_mfma_f32_16x16x32_bf16 v[82:85], v[178:181], v[212:215], v[82:85]
	v_mfma_f32_16x16x32_bf16 v[70:73], v[170:173], v[220:223], v[70:73]
	v_mfma_f32_16x16x32_bf16 v[66:69], v[178:181], v[220:223], v[66:69]
	s_setprio 0
	s_barrier
; #define PG8_STAGE(bufoff, gbase, voff) do { _Pragma("unroll") for (int _i = 0; _i < 2; ++_i) \
;         __builtin_amdgcn_global_load_lds((const unsigned*)((const char*)(gbase) + (voff)[_i]), (LAS unsigned*)(lds + (bufoff) + ldsw + _i * 8192), 16, 0, 0); } while (0)
; #define PG8_LDA(dst, b, h) do { _Pragma("unroll") for (int m = 0; m < 4; ++m) _Pragma("unroll") for (int k = 0; k < 2; ++k) dst[m][k] = *(const LAS bf16x8*)(lds + PG8_SA(b, h) + aoff + m * 2048 + k * 1024); } while (0)
; #define PG8_MMA(ai, bj, At, Bt) do { __builtin_amdgcn_s_setprio(1); _Pragma("unroll") for (int m = 0; m < 4; ++m) _Pragma("unroll") for (int n = 0; n < 2; ++n) _Pragma("unroll") for (int k = 0; k < 2; ++k) \
;         acc[ai][bj][m][n] = mma16<I8>(Bt[n][k], At[m][k], acc[ai][bj][m][n]); __builtin_amdgcn_s_setprio(0); } while (0)
; #define PG8_WAIT_V(n) asm volatile("s_waitcnt vmcnt(" #n ")" ::: "memory")
; #define PG8_WAIT_L(n) asm volatile("s_waitcnt lgkmcnt(" #n ")" ::: "memory")
; #define PG8_BAR __builtin_amdgcn_s_barrier()
; #define PG8_SCHED __builtin_amdgcn_sched_barrier(0)
; template <class Epi, class Sched, bool I8 = false>
; __device__ __forceinline__ void gemm_phase(LAS unsigned char* lds, const Gemm g, const Sched& S, const Epi& E) {
;     ...
;         for (int t = 0; t < nt; t += 2) {
;             const bool last = (t == nt - 2);
;             const char* a1 = cA + (size_t)(t + 1) * kstep;
;             const char* a2 = last ? nA : cA + (size_t)(t + 2) * kstep; const char* b2 = last ? nB : cB + (size_t)(t + 2) * kstep;
;             const char* a3 = a2 + kstep; const char* b3 = b2 + kstep;
;     ...
;             PG8_LDA(At, 1, 1); PG8_STAGE(PG8_SB(1, 0), b3, voffB); PG8_STAGE(PG8_SB(1, 1), b3 + hstepB, voffB); PG8_STAGE(PG8_SA(1, 0), a3, voffA);
;             PG8_WAIT_V(8); PG8_WAIT_L(0); PG8_BAR; PG8_MMA(1, 0, At, B0); PG8_MMA(1, 1, At, B1); PG8_BAR; PG8_SCHED;
	s_add_i32 s6, s30, s40
	v_lshl_add_u64 v[202:203], v[202:203], 0, s[12:13]
	s_mov_b32 m0, s6
	ds_read_b128 v[182:185], v143 offset:49152
	ds_read_b128 v[186:189], v143 offset:50176
	ds_read_b128 v[190:193], v143 offset:51200
	ds_read_b128 v[194:197], v143 offset:52224
	ds_read_b128 v[198:201], v143 offset:53248
	ds_read_b128 v[212:215], v143 offset:54272
	ds_read_b128 v[216:219], v143 offset:55296
	ds_read_b128 v[220:223], v143 offset:56320
	global_load_lds_dwordx4 v[202:203], off
	s_add_i32 m0, s6, 0x2000
	s_add_u32 s4, s4, 0x20080
	v_lshl_add_u64 v[202:203], v[224:225], 0, s[12:13]
	s_addc_u32 s5, s5, 0
	s_add_i32 s6, s31, s40
	global_load_lds_dwordx4 v[202:203], off
	v_lshl_add_u64 v[202:203], s[4:5], 0, v[136:137]
	s_mov_b32 m0, s6
	s_nop 0
	global_load_lds_dwordx4 v[202:203], off
	v_lshl_add_u64 v[202:203], s[4:5], 0, v[132:133]
	s_add_i32 m0, s6, 0x2000
	s_nop 0
	global_load_lds_dwordx4 v[202:203], off
	v_lshl_add_u64 v[202:203], v[226:227], 0, s[12:13]
	s_mov_b32 m0, s80
	s_nop 0
	global_load_lds_dwordx4 v[202:203], off
	v_lshl_add_u64 v[202:203], v[228:229], 0, s[12:13]
	s_mov_b32 m0, s82
	s_nop 0
	global_load_lds_dwordx4 v[202:203], off
	s_waitcnt vmcnt(8)
	s_waitcnt lgkmcnt(0)
	s_barrier
	s_setprio 1
	s_waitcnt lgkmcnt(0)
	v_mfma_f32_16x16x32_bf16 v[62:65], v[150:153], v[182:185], v[62:65]
	v_mfma_f32_16x16x32_bf16 v[58:61], v[158:161], v[182:185], v[58:61]
	v_mfma_f32_16x16x32_bf16 v[46:49], v[150:153], v[190:193], v[46:49]
	v_mfma_f32_16x16x32_bf16 v[42:45], v[158:161], v[190:193], v[42:45]
	v_mfma_f32_16x16x32_bf16 v[30:33], v[150:153], v[198:201], v[30:33]
	v_mfma_f32_16x16x32_bf16 v[26:29], v[158:161], v[198:201], v[26:29]
	v_mfma_f32_16x16x32_bf16 v[14:17], v[150:153], v[216:219], v[14:17]
	v_mfma_f32_16x16x32_bf16 v[10:13], v[158:161], v[216:219], v[10:13]
	v_mfma_f32_16x16x32_bf16 v[62:65], v[154:157], v[186:189], v[62:65]
	v_mfma_f32_16x16x32_bf16 v[58:61], v[162:165], v[186:189], v[58:61]
	v_mfma_f32_16x16x32_bf16 v[46:49], v[154:157], v[194:197], v[46:49]
	v_mfma_f32_16x16x32_bf16 v[42:45], v[162:165], v[194:197], v[42:45]
	v_mfma_f32_16x16x32_bf16 v[30:33], v[154:157], v[212:215], v[30:33]
	v_mfma_f32_16x16x32_bf16 v[26:29], v[162:165], v[212:215], v[26:29]
	v_mfma_f32_16x16x32_bf16 v[14:17], v[154:157], v[220:223], v[14:17]
	v_mfma_f32_16x16x32_bf16 v[10:13], v[162:165], v[220:223], v[10:13]
	s_setprio 0
	s_setprio 1
	v_mfma_f32_16x16x32_bf16 v[54:57], v[166:169], v[182:185], v[54:57]
	v_mfma_f32_16x16x32_bf16 v[50:53], v[174:177], v[182:185], v[50:53]
	v_mfma_f32_16x16x32_bf16 v[38:41], v[166:169], v[190:193], v[38:41]
	v_mfma_f32_16x16x32_bf16 v[34:37], v[174:177], v[190:193], v[34:37]
	v_mfma_f32_16x16x32_bf16 v[22:25], v[166:169], v[198:201], v[22:25]
	v_mfma_f32_16x16x32_bf16 v[18:21], v[174:177], v[198:201], v[18:21]
	v_mfma_f32_16x16x32_bf16 v[6:9], v[166:169], v[216:219], v[6:9]
	v_mfma_f32_16x16x32_bf16 v[2:5], v[174:177], v[216:219], v[2:5]
	v_mfma_f32_16x16x32_bf16 v[54:57], v[170:173], v[186:189], v[54:57]
	v_mfma_f32_16x16x32_bf16 v[50:53], v[178:181], v[186:189], v[50:53]
	v_mfma_f32_16x16x32_bf16 v[38:41], v[170:173], v[194:197], v[38:41]
	v_mfma_f32_16x16x32_bf16 v[34:37], v[178:181], v[194:197], v[34:37]
	v_mfma_f32_16x16x32_bf16 v[22:25], v[170:173], v[212:215], v[22:25]
	v_mfma_f32_16x16x32_bf16 v[18:21], v[178:181], v[212:215], v[18:21]
	v_mfma_f32_16x16x32_bf16 v[6:9], v[170:173], v[220:223], v[6:9]
	v_mfma_f32_16x16x32_bf16 v[2:5], v[178:181], v[220:223], v[2:5]
	s_setprio 0
	s_add_i32 s29, s29, 2
	s_add_u32 s0, s0, 0x100
	s_addc_u32 s1, s1, 0
	s_add_u32 s24, s24, 0x100
	s_addc_u32 s25, s25, 0
	s_cmp_gt_u32 s29, 29
	s_barrier
	s_cbranch_scc0 .LBB0_356
	s_and_b64 vcc, exec, s[8:9]
	s_cbranch_vccz .LBB0_359
	s_barrier

; #define PG8_STAGE(bufoff, gbase, voff) do { _Pragma("unroll") for (int _i = 0; _i < 2; ++_i) \
;         __builtin_amdgcn_global_load_lds((const unsigned*)((const char*)(gbase) + (voff)[_i]), (LAS unsigned*)(lds + (bufoff) + ldsw + _i * 8192), 16, 0, 0); } while (0)
; #define PG8_LDA(dst, b, h) do { _Pragma("unroll") for (int m = 0; m < 4; ++m) _Pragma("unroll") for (int k = 0; k < 2; ++k) dst[m][k] = *(const LAS bf16x8*)(lds + PG8_SA(b, h) + aoff + m * 2048 + k * 1024); } while (0)
; #define PG8_LDB(dst, b, h) do { _Pragma("unroll") for (int n = 0; n < 2; ++n) _Pragma("unroll") for (int k = 0; k < 2; ++k) dst[n][k] = *(const LAS bf16x8*)(lds + PG8_SB(b, h) + boff + n * 2048 + k * 1024); } while (0)
; #define PG8_MMA(ai, bj, At, Bt) do { __builtin_amdgcn_s_setprio(1); _Pragma("unroll") for (int m = 0; m < 4; ++m) _Pragma("unroll") for (int n = 0; n < 2; ++n) _Pragma("unroll") for (int k = 0; k < 2; ++k) \
;         acc[ai][bj][m][n] = mma16<I8>(Bt[n][k], At[m][k], acc[ai][bj][m][n]); __builtin_amdgcn_s_setprio(0); } while (0)
; #define PG8_WAIT_V(n) asm volatile("s_waitcnt vmcnt(" #n ")" ::: "memory")
; #define PG8_WAIT_L(n) asm volatile("s_waitcnt lgkmcnt(" #n ")" ::: "memory")
; #define PG8_BAR __builtin_amdgcn_s_barrier()
; #define PG8_SCHED __builtin_amdgcn_sched_barrier(0)
; template <class Epi, class Sched, bool I8 = false>
; __device__ __forceinline__ void gemm_phase(LAS unsigned char* lds, const Gemm g, const Sched& S, const Epi& E) {
;     ...
;         for (int t = 0; t < nt; t += 2) {
;             const bool last = (t == nt - 2);
;             const char* a1 = cA + (size_t)(t + 1) * kstep;
;             const char* a2 = last ? nA : cA + (size_t)(t + 2) * kstep; const char* b2 = last ? nB : cB + (size_t)(t + 2) * kstep;
;             const char* a3 = a2 + kstep; const char* b3 = b2 + kstep;
;             if (PG8_SP2) {
;             PG8_LDB(B0, 0, 0); PG8_LDB(B1, 0, 1); PG8_SCHED; PG8_LDA(At, 0, 0); PG8_STAGE(PG8_SA(1, 1), a1 + hstepA, voffA);
;             PG8_WAIT_V(8); PG8_WAIT_L(0); PG8_BAR; PG8_MMA(0, 0, At, B0); PG8_MMA(0, 1, At, B1); PG8_BAR; PG8_SCHED;
;             PG8_LDA(At, 0, 1); PG8_STAGE(PG8_SB(0, 0), b2, voffB); PG8_STAGE(PG8_SB(0, 1), b2 + hstepB, voffB); PG8_STAGE(PG8_SA(0, 0), a2, voffA);
;             PG8_WAIT_V(8); PG8_WAIT_L(0); PG8_BAR; PG8_MMA(1, 0, At, B0); PG8_MMA(1, 1, At, B1); PG8_BAR; PG8_SCHED;
.LBB0_539:
	s_add_u32 s6, s0, 0xfffc0080
	s_addc_u32 s7, s1, -1
	s_add_i32 s31, 0, 0x10000
	s_cmp_eq_u32 s30, 12
	s_cselect_b32 s27, s14, s7
	s_cselect_b32 s26, s21, s6
	v_add_u32_e32 v149, s31, v175
	s_cselect_b32 s7, s22, s25
	s_cselect_b32 s6, s23, s24
	s_add_i32 s38, 0, 0x14000
	ds_read_b128 v[152:155], v149
	ds_read_b128 v[156:159], v149 offset:1024
	ds_read_b128 v[160:163], v149 offset:2048
	ds_read_b128 v[164:167], v149 offset:3072
	v_add_u32_e32 v149, s38, v175
	ds_read_b128 v[168:171], v149
	ds_read_b128 v[180:183], v149 offset:1024
	ds_read_b128 v[184:187], v149 offset:2048
	ds_read_b128 v[188:191], v149 offset:3072
	v_lshl_add_u64 v[172:173], s[0:1], 0, v[144:145]
	s_add_i32 m0, s43, 0xc000
	ds_read_b128 v[192:195], v179
	ds_read_b128 v[196:199], v179 offset:1024
	ds_read_b128 v[200:203], v179 offset:2048
	ds_read_b128 v[212:215], v179 offset:3072
	ds_read_b128 v[216:219], v179 offset:4096
	ds_read_b128 v[220:223], v179 offset:5120
	ds_read_b128 v[224:227], v179 offset:6144
	ds_read_b128 v[228:231], v179 offset:7168
	global_load_lds_dwordx4 v[172:173], off
	v_lshl_add_u64 v[172:173], s[0:1], 0, v[146:147]
	s_add_i32 m0, s43, 0xe000
	s_nop 0
	global_load_lds_dwordx4 v[172:173], off
	s_waitcnt vmcnt(8)
	s_waitcnt lgkmcnt(0)
	s_barrier
	s_setprio 1
	s_waitcnt lgkmcnt(0)
	v_mfma_i32_16x16x64_i8 v[126:129], v[152:155], v[192:195], v[126:129]
	v_mfma_i32_16x16x64_i8 v[122:125], v[160:163], v[192:195], v[122:125]
	v_mfma_i32_16x16x64_i8 v[118:121], v[152:155], v[200:203], v[118:121]
	v_mfma_i32_16x16x64_i8 v[114:117], v[160:163], v[200:203], v[114:117]
	v_mfma_i32_16x16x64_i8 v[102:105], v[152:155], v[216:219], v[102:105]
	v_mfma_i32_16x16x64_i8 v[98:101], v[160:163], v[216:219], v[98:101]
	v_mfma_i32_16x16x64_i8 v[86:89], v[152:155], v[224:227], v[86:89]
	v_mfma_i32_16x16x64_i8 v[82:85], v[160:163], v[224:227], v[82:85]
	v_mfma_i32_16x16x64_i8 v[126:129], v[156:159], v[196:199], v[126:129]
	v_mfma_i32_16x16x64_i8 v[122:125], v[164:167], v[196:199], v[122:125]
	v_mfma_i32_16x16x64_i8 v[118:121], v[156:159], v[212:215], v[118:121]
	v_mfma_i32_16x16x64_i8 v[114:117], v[164:167], v[212:215], v[114:117]
	v_mfma_i32_16x16x64_i8 v[102:105], v[156:159], v[220:223], v[102:105]
	v_mfma_i32_16x16x64_i8 v[98:101], v[164:167], v[220:223], v[98:101]
	v_mfma_i32_16x16x64_i8 v[86:89], v[156:159], v[228:231], v[86:89]
	v_mfma_i32_16x16x64_i8 v[82:85], v[164:167], v[228:231], v[82:85]
	s_setprio 0
	s_setprio 1
	v_mfma_i32_16x16x64_i8 v[110:113], v[168:171], v[192:195], v[110:113]
	v_mfma_i32_16x16x64_i8 v[106:109], v[184:187], v[192:195], v[106:109]
	v_mfma_i32_16x16x64_i8 v[94:97], v[168:171], v[200:203], v[94:97]
	v_mfma_i32_16x16x64_i8 v[90:93], v[184:187], v[200:203], v[90:93]
	v_mfma_i32_16x16x64_i8 v[78:81], v[168:171], v[216:219], v[78:81]
	v_mfma_i32_16x16x64_i8 v[74:77], v[184:187], v[216:219], v[74:77]
	v_mfma_i32_16x16x64_i8 v[70:73], v[168:171], v[224:227], v[70:73]
	v_mfma_i32_16x16x64_i8 v[66:69], v[184:187], v[224:227], v[66:69]
	v_mfma_i32_16x16x64_i8 v[110:113], v[180:183], v[196:199], v[110:113]
	v_mfma_i32_16x16x64_i8 v[106:109], v[188:191], v[196:199], v[106:109]
	v_mfma_i32_16x16x64_i8 v[94:97], v[180:183], v[212:215], v[94:97]
	v_mfma_i32_16x16x64_i8 v[90:93], v[188:191], v[212:215], v[90:93]
	v_mfma_i32_16x16x64_i8 v[78:81], v[180:183], v[220:223], v[78:81]
	v_mfma_i32_16x16x64_i8 v[74:77], v[188:191], v[220:223], v[74:77]
	v_mfma_i32_16x16x64_i8 v[70:73], v[180:183], v[228:231], v[70:73]
	v_mfma_i32_16x16x64_i8 v[66:69], v[188:191], v[228:231], v[66:69]
	s_setprio 0
	s_barrier
	s_add_i32 s31, s31, s42
	v_lshl_add_u64 v[172:173], s[6:7], 0, v[136:137]
	s_mov_b32 m0, s31
	ds_read_b128 v[192:195], v179 offset:16384
	ds_read_b128 v[196:199], v179 offset:17408
	ds_read_b128 v[200:203], v179 offset:18432
	ds_read_b128 v[212:215], v179 offset:19456
	ds_read_b128 v[216:219], v179 offset:20480
	ds_read_b128 v[220:223], v179 offset:21504
	ds_read_b128 v[224:227], v179 offset:22528
	ds_read_b128 v[228:231], v179 offset:23552
	global_load_lds_dwordx4 v[172:173], off
	s_add_i32 m0, s31, 0x2000
	s_add_u32 s34, s6, 0x10000
	v_lshl_add_u64 v[232:233], s[6:7], 0, v[132:133]
	s_addc_u32 s35, s7, 0
	s_add_i32 s31, s38, s42
	global_load_lds_dwordx4 v[232:233], off
	v_lshl_add_u64 v[234:235], s[34:35], 0, v[136:137]
	s_mov_b32 m0, s31
	v_lshl_add_u64 v[236:237], s[26:27], 0, v[134:135]
	global_load_lds_dwordx4 v[234:235], off
	v_lshl_add_u64 v[234:235], s[34:35], 0, v[132:133]
	s_add_i32 m0, s31, 0x2000
	s_nop 0
	global_load_lds_dwordx4 v[234:235], off
	v_lshl_add_u64 v[234:235], s[26:27], 0, v[138:139]
	s_mov_b32 m0, s43
	s_nop 0
	global_load_lds_dwordx4 v[234:235], off
	s_mov_b32 m0, s44
	s_nop 0
	global_load_lds_dwordx4 v[236:237], off
	s_waitcnt vmcnt(8)
	s_waitcnt lgkmcnt(0)
	s_barrier
; #define PG8_STAGE(bufoff, gbase, voff) do { _Pragma("unroll") for (int _i = 0; _i < 2; ++_i) \
;         __builtin_amdgcn_global_load_lds((const unsigned*)((const char*)(gbase) + (voff)[_i]), (LAS unsigned*)(lds + (bufoff) + ldsw + _i * 8192), 16, 0, 0); } while (0)
; #define PG8_LDA(dst, b, h) do { _Pragma("unroll") for (int m = 0; m < 4; ++m) _Pragma("unroll") for (int k = 0; k < 2; ++k) dst[m][k] = *(const LAS bf16x8*)(lds + PG8_SA(b, h) + aoff + m * 2048 + k * 1024); } while (0)
; #define PG8_LDB(dst, b, h) do { _Pragma("unroll") for (int n = 0; n < 2; ++n) _Pragma("unroll") for (int k = 0; k < 2; ++k) dst[n][k] = *(const LAS bf16x8*)(lds + PG8_SB(b, h) + boff + n * 2048 + k * 1024); } while (0)
; #define PG8_MMA(ai, bj, At, Bt) do { __builtin_amdgcn_s_setprio(1); _Pragma("unroll") for (int m = 0; m < 4; ++m) _Pragma("unroll") for (int n = 0; n < 2; ++n) _Pragma("unroll") for (int k = 0; k < 2; ++k) \
;         acc[ai][bj][m][n] = mma16<I8>(Bt[n][k], At[m][k], acc[ai][bj][m][n]); __builtin_amdgcn_s_setprio(0); } while (0)
; #define PG8_WAIT_V(n) asm volatile("s_waitcnt vmcnt(" #n ")" ::: "memory")
; #define PG8_WAIT_L(n) asm volatile("s_waitcnt lgkmcnt(" #n ")" ::: "memory")
; #define PG8_BAR __builtin_amdgcn_s_barrier()
; #define PG8_SCHED __builtin_amdgcn_sched_barrier(0)
; template <class Epi, class Sched, bool I8 = false>
; __device__ __forceinline__ void gemm_phase(LAS unsigned char* lds, const Gemm g, const Sched& S, const Epi& E) {
;     ...
;             PG8_WAIT_V(8); PG8_WAIT_L(0); PG8_BAR; PG8_MMA(1, 0, At, B0); PG8_MMA(1, 1, At, B1); PG8_BAR; PG8_SCHED;
;             PG8_LDB(B0, 1, 0); PG8_LDB(B1, 1, 1); PG8_SCHED; PG8_LDA(At, 1, 0); PG8_STAGE(PG8_SA(0, 1), a2 + hstepA, voffA);
;             PG8_WAIT_V(8); PG8_WAIT_L(0); PG8_BAR; PG8_MMA(0, 0, At, B0); PG8_MMA(0, 1, At, B1); PG8_BAR; PG8_SCHED;
	s_setprio 1
	s_waitcnt lgkmcnt(0)
	v_mfma_i32_16x16x64_i8 v[62:65], v[152:155], v[192:195], v[62:65]
	v_mfma_i32_16x16x64_i8 v[58:61], v[160:163], v[192:195], v[58:61]
	v_mfma_i32_16x16x64_i8 v[54:57], v[152:155], v[200:203], v[54:57]
	v_mfma_i32_16x16x64_i8 v[50:53], v[160:163], v[200:203], v[50:53]
	v_mfma_i32_16x16x64_i8 v[30:33], v[152:155], v[216:219], v[30:33]
	v_mfma_i32_16x16x64_i8 v[26:29], v[160:163], v[216:219], v[26:29]
	v_mfma_i32_16x16x64_i8 v[14:17], v[152:155], v[224:227], v[14:17]
	v_mfma_i32_16x16x64_i8 v[10:13], v[160:163], v[224:227], v[10:13]
	v_mfma_i32_16x16x64_i8 v[62:65], v[156:159], v[196:199], v[62:65]
	v_mfma_i32_16x16x64_i8 v[58:61], v[164:167], v[196:199], v[58:61]
	v_mfma_i32_16x16x64_i8 v[54:57], v[156:159], v[212:215], v[54:57]
	v_mfma_i32_16x16x64_i8 v[50:53], v[164:167], v[212:215], v[50:53]
	v_mfma_i32_16x16x64_i8 v[30:33], v[156:159], v[220:223], v[30:33]
	v_mfma_i32_16x16x64_i8 v[26:29], v[164:167], v[220:223], v[26:29]
	v_mfma_i32_16x16x64_i8 v[14:17], v[156:159], v[228:231], v[14:17]
	v_mfma_i32_16x16x64_i8 v[10:13], v[164:167], v[228:231], v[10:13]
	s_setprio 0
	s_setprio 1
	v_mfma_i32_16x16x64_i8 v[46:49], v[168:171], v[192:195], v[46:49]
	v_mfma_i32_16x16x64_i8 v[42:45], v[184:187], v[192:195], v[42:45]
	v_mfma_i32_16x16x64_i8 v[38:41], v[168:171], v[200:203], v[38:41]
	v_mfma_i32_16x16x64_i8 v[34:37], v[184:187], v[200:203], v[34:37]
	v_mfma_i32_16x16x64_i8 v[22:25], v[168:171], v[216:219], v[22:25]
	v_mfma_i32_16x16x64_i8 v[18:21], v[184:187], v[216:219], v[18:21]
	v_mfma_i32_16x16x64_i8 v[6:9], v[168:171], v[224:227], v[6:9]
	v_mfma_i32_16x16x64_i8 v[2:5], v[184:187], v[224:227], v[2:5]
	v_mfma_i32_16x16x64_i8 v[46:49], v[180:183], v[196:199], v[46:49]
	v_mfma_i32_16x16x64_i8 v[42:45], v[188:191], v[196:199], v[42:45]
	v_mfma_i32_16x16x64_i8 v[38:41], v[180:183], v[212:215], v[38:41]
	v_mfma_i32_16x16x64_i8 v[34:37], v[188:191], v[212:215], v[34:37]
	v_mfma_i32_16x16x64_i8 v[22:25], v[180:183], v[220:223], v[22:25]
	v_mfma_i32_16x16x64_i8 v[18:21], v[188:191], v[220:223], v[18:21]
	v_mfma_i32_16x16x64_i8 v[6:9], v[180:183], v[228:231], v[6:9]
	v_mfma_i32_16x16x64_i8 v[2:5], v[188:191], v[228:231], v[2:5]
	s_setprio 0
	s_barrier
	s_add_i32 s31, 0, 0x18000
	v_add_u32_e32 v149, s31, v175
	s_add_i32 s34, 0, 0x1c000
	ds_read_b128 v[152:155], v149
	ds_read_b128 v[156:159], v149 offset:1024
	ds_read_b128 v[160:163], v149 offset:2048
	ds_read_b128 v[164:167], v149 offset:3072
	v_add_u32_e32 v149, s34, v175
	ds_read_b128 v[168:171], v149
	ds_read_b128 v[180:183], v149 offset:1024
	ds_read_b128 v[184:187], v149 offset:2048
	ds_read_b128 v[188:191], v149 offset:3072
	s_add_u32 s26, s26, 0x40000
	s_addc_u32 s27, s27, 0
	s_mov_b32 m0, s45
	v_lshl_add_u64 v[238:239], s[26:27], 0, v[138:139]
	ds_read_b128 v[192:195], v179 offset:32768
	ds_read_b128 v[196:199], v179 offset:33792
	ds_read_b128 v[200:203], v179 offset:34816
	ds_read_b128 v[212:215], v179 offset:35840
	ds_read_b128 v[216:219], v179 offset:36864
	ds_read_b128 v[220:223], v179 offset:37888
	ds_read_b128 v[224:227], v179 offset:38912
	ds_read_b128 v[228:231], v179 offset:39936
	global_load_lds_dwordx4 v[238:239], off
	v_lshl_add_u64 v[238:239], s[26:27], 0, v[134:135]
	s_mov_b32 m0, s82
	s_nop 0
	global_load_lds_dwordx4 v[238:239], off
	s_waitcnt vmcnt(8)
	s_waitcnt lgkmcnt(0)
	s_barrier
	s_setprio 1
	s_waitcnt lgkmcnt(0)
	v_mfma_i32_16x16x64_i8 v[126:129], v[152:155], v[192:195], v[126:129]
	v_mfma_i32_16x16x64_i8 v[122:125], v[160:163], v[192:195], v[122:125]
	v_mfma_i32_16x16x64_i8 v[118:121], v[152:155], v[200:203], v[118:121]
	v_mfma_i32_16x16x64_i8 v[114:117], v[160:163], v[200:203], v[114:117]
	v_mfma_i32_16x16x64_i8 v[102:105], v[152:155], v[216:219], v[102:105]
	v_mfma_i32_16x16x64_i8 v[98:101], v[160:163], v[216:219], v[98:101]
	v_mfma_i32_16x16x64_i8 v[86:89], v[152:155], v[224:227], v[86:89]
	v_mfma_i32_16x16x64_i8 v[82:85], v[160:163], v[224:227], v[82:85]
	v_mfma_i32_16x16x64_i8 v[126:129], v[156:159], v[196:199], v[126:129]
	v_mfma_i32_16x16x64_i8 v[122:125], v[164:167], v[196:199], v[122:125]
	v_mfma_i32_16x16x64_i8 v[118:121], v[156:159], v[212:215], v[118:121]
	v_mfma_i32_16x16x64_i8 v[114:117], v[164:167], v[212:215], v[114:117]
	v_mfma_i32_16x16x64_i8 v[102:105], v[156:159], v[220:223], v[102:105]
	v_mfma_i32_16x16x64_i8 v[98:101], v[164:167], v[220:223], v[98:101]
	v_mfma_i32_16x16x64_i8 v[86:89], v[156:159], v[228:231], v[86:89]
	v_mfma_i32_16x16x64_i8 v[82:85], v[164:167], v[228:231], v[82:85]
	s_setprio 0
	s_setprio 1
	v_mfma_i32_16x16x64_i8 v[110:113], v[168:171], v[192:195], v[110:113]
	v_mfma_i32_16x16x64_i8 v[106:109], v[184:187], v[192:195], v[106:109]
	v_mfma_i32_16x16x64_i8 v[94:97], v[168:171], v[200:203], v[94:97]
	v_mfma_i32_16x16x64_i8 v[90:93], v[184:187], v[200:203], v[90:93]
	v_mfma_i32_16x16x64_i8 v[78:81], v[168:171], v[216:219], v[78:81]
	v_mfma_i32_16x16x64_i8 v[74:77], v[184:187], v[216:219], v[74:77]
	v_mfma_i32_16x16x64_i8 v[70:73], v[168:171], v[224:227], v[70:73]
	v_mfma_i32_16x16x64_i8 v[66:69], v[184:187], v[224:227], v[66:69]
	v_mfma_i32_16x16x64_i8 v[110:113], v[180:183], v[196:199], v[110:113]
	v_mfma_i32_16x16x64_i8 v[106:109], v[188:191], v[196:199], v[106:109]
	v_mfma_i32_16x16x64_i8 v[94:97], v[180:183], v[212:215], v[94:97]
	v_mfma_i32_16x16x64_i8 v[90:93], v[188:191], v[212:215], v[90:93]
	v_mfma_i32_16x16x64_i8 v[78:81], v[180:183], v[220:223], v[78:81]
	v_mfma_i32_16x16x64_i8 v[74:77], v[188:191], v[220:223], v[74:77]
	v_mfma_i32_16x16x64_i8 v[70:73], v[180:183], v[228:231], v[70:73]
	v_mfma_i32_16x16x64_i8 v[66:69], v[188:191], v[228:231], v[66:69]
	s_setprio 0
	s_barrier
; #define PG8_STAGE(bufoff, gbase, voff) do { _Pragma("unroll") for (int _i = 0; _i < 2; ++_i) \
;         __builtin_amdgcn_global_load_lds((const unsigned*)((const char*)(gbase) + (voff)[_i]), (LAS unsigned*)(lds + (bufoff) + ldsw + _i * 8192), 16, 0, 0); } while (0)
; #define PG8_LDA(dst, b, h) do { _Pragma("unroll") for (int m = 0; m < 4; ++m) _Pragma("unroll") for (int k = 0; k < 2; ++k) dst[m][k] = *(const LAS bf16x8*)(lds + PG8_SA(b, h) + aoff + m * 2048 + k * 1024); } while (0)
; #define PG8_MMA(ai, bj, At, Bt) do { __builtin_amdgcn_s_setprio(1); _Pragma("unroll") for (int m = 0; m < 4; ++m) _Pragma("unroll") for (int n = 0; n < 2; ++n) _Pragma("unroll") for (int k = 0; k < 2; ++k) \
;         acc[ai][bj][m][n] = mma16<I8>(Bt[n][k], At[m][k], acc[ai][bj][m][n]); __builtin_amdgcn_s_setprio(0); } while (0)
; #define PG8_WAIT_V(n) asm volatile("s_waitcnt vmcnt(" #n ")" ::: "memory")
; #define PG8_WAIT_L(n) asm volatile("s_waitcnt lgkmcnt(" #n ")" ::: "memory")
; #define PG8_BAR __builtin_amdgcn_s_barrier()
; #define PG8_SCHED __builtin_amdgcn_sched_barrier(0)
; template <class Epi, class Sched, bool I8 = false>
; __device__ __forceinline__ void gemm_phase(LAS unsigned char* lds, const Gemm g, const Sched& S, const Epi& E) {
;     ...
;         for (int t = 0; t < nt; t += 2) {
;             const bool last = (t == nt - 2);
;             const char* a1 = cA + (size_t)(t + 1) * kstep;
;             const char* a2 = last ? nA : cA + (size_t)(t + 2) * kstep; const char* b2 = last ? nB : cB + (size_t)(t + 2) * kstep;
;             const char* a3 = a2 + kstep; const char* b3 = b2 + kstep;
;     ...
;             PG8_LDA(At, 1, 1); PG8_STAGE(PG8_SB(1, 0), b3, voffB); PG8_STAGE(PG8_SB(1, 1), b3 + hstepB, voffB); PG8_STAGE(PG8_SA(1, 0), a3, voffA);
;             PG8_WAIT_V(8); PG8_WAIT_L(0); PG8_BAR; PG8_MMA(1, 0, At, B0); PG8_MMA(1, 1, At, B1); PG8_BAR; PG8_SCHED;
	s_add_i32 s26, s31, s42
	v_lshl_add_u64 v[172:173], v[172:173], 0, s[12:13]
	s_mov_b32 m0, s26
	ds_read_b128 v[192:195], v179 offset:49152
	ds_read_b128 v[196:199], v179 offset:50176
	ds_read_b128 v[200:203], v179 offset:51200
	ds_read_b128 v[212:215], v179 offset:52224
	ds_read_b128 v[216:219], v179 offset:53248
	ds_read_b128 v[220:223], v179 offset:54272
	ds_read_b128 v[224:227], v179 offset:55296
	ds_read_b128 v[228:231], v179 offset:56320
	global_load_lds_dwordx4 v[172:173], off
	s_add_i32 m0, s26, 0x2000
	s_add_u32 s6, s6, 0x10080
	v_lshl_add_u64 v[172:173], v[232:233], 0, s[12:13]
	s_addc_u32 s7, s7, 0
	s_add_i32 s26, s34, s42
	global_load_lds_dwordx4 v[172:173], off
	v_lshl_add_u64 v[172:173], s[6:7], 0, v[136:137]
	s_mov_b32 m0, s26
	s_nop 0
	global_load_lds_dwordx4 v[172:173], off
	v_lshl_add_u64 v[172:173], s[6:7], 0, v[132:133]
	s_add_i32 m0, s26, 0x2000
	s_nop 0
	global_load_lds_dwordx4 v[172:173], off
	v_lshl_add_u64 v[172:173], v[234:235], 0, s[12:13]
	s_mov_b32 m0, s83
	s_nop 0
	global_load_lds_dwordx4 v[172:173], off
	v_lshl_add_u64 v[172:173], v[236:237], 0, s[12:13]
	s_mov_b32 m0, s94
	s_nop 0
	global_load_lds_dwordx4 v[172:173], off
	s_waitcnt vmcnt(8)
	s_waitcnt lgkmcnt(0)
	s_barrier
	s_setprio 1
	s_waitcnt lgkmcnt(0)
	v_mfma_i32_16x16x64_i8 v[62:65], v[152:155], v[192:195], v[62:65]
	v_mfma_i32_16x16x64_i8 v[58:61], v[160:163], v[192:195], v[58:61]
	v_mfma_i32_16x16x64_i8 v[54:57], v[152:155], v[200:203], v[54:57]
	v_mfma_i32_16x16x64_i8 v[50:53], v[160:163], v[200:203], v[50:53]
	v_mfma_i32_16x16x64_i8 v[30:33], v[152:155], v[216:219], v[30:33]
	v_mfma_i32_16x16x64_i8 v[26:29], v[160:163], v[216:219], v[26:29]
	v_mfma_i32_16x16x64_i8 v[14:17], v[152:155], v[224:227], v[14:17]
	v_mfma_i32_16x16x64_i8 v[10:13], v[160:163], v[224:227], v[10:13]
	v_mfma_i32_16x16x64_i8 v[62:65], v[156:159], v[196:199], v[62:65]
	v_mfma_i32_16x16x64_i8 v[58:61], v[164:167], v[196:199], v[58:61]
	v_mfma_i32_16x16x64_i8 v[54:57], v[156:159], v[212:215], v[54:57]
	v_mfma_i32_16x16x64_i8 v[50:53], v[164:167], v[212:215], v[50:53]
	v_mfma_i32_16x16x64_i8 v[30:33], v[156:159], v[220:223], v[30:33]
	v_mfma_i32_16x16x64_i8 v[26:29], v[164:167], v[220:223], v[26:29]
	v_mfma_i32_16x16x64_i8 v[14:17], v[156:159], v[228:231], v[14:17]
	v_mfma_i32_16x16x64_i8 v[10:13], v[164:167], v[228:231], v[10:13]
	s_setprio 0
	s_setprio 1
	v_mfma_i32_16x16x64_i8 v[46:49], v[168:171], v[192:195], v[46:49]
	v_mfma_i32_16x16x64_i8 v[42:45], v[184:187], v[192:195], v[42:45]
	v_mfma_i32_16x16x64_i8 v[38:41], v[168:171], v[200:203], v[38:41]
	v_mfma_i32_16x16x64_i8 v[34:37], v[184:187], v[200:203], v[34:37]
	v_mfma_i32_16x16x64_i8 v[22:25], v[168:171], v[216:219], v[22:25]
	v_mfma_i32_16x16x64_i8 v[18:21], v[184:187], v[216:219], v[18:21]
	v_mfma_i32_16x16x64_i8 v[6:9], v[168:171], v[224:227], v[6:9]
	v_mfma_i32_16x16x64_i8 v[2:5], v[184:187], v[224:227], v[2:5]
	v_mfma_i32_16x16x64_i8 v[46:49], v[180:183], v[196:199], v[46:49]
	v_mfma_i32_16x16x64_i8 v[42:45], v[188:191], v[196:199], v[42:45]
	v_mfma_i32_16x16x64_i8 v[38:41], v[180:183], v[212:215], v[38:41]
	v_mfma_i32_16x16x64_i8 v[34:37], v[188:191], v[212:215], v[34:37]
	v_mfma_i32_16x16x64_i8 v[22:25], v[180:183], v[220:223], v[22:25]
	v_mfma_i32_16x16x64_i8 v[18:21], v[188:191], v[220:223], v[18:21]
	v_mfma_i32_16x16x64_i8 v[6:9], v[180:183], v[228:231], v[6:9]
	v_mfma_i32_16x16x64_i8 v[2:5], v[188:191], v[228:231], v[2:5]
	s_setprio 0
	s_add_i32 s30, s30, 2
	s_add_u32 s0, s0, 0x100
	s_addc_u32 s1, s1, 0
	s_add_u32 s24, s24, 0x100
	s_addc_u32 s25, s25, 0
	s_cmp_gt_u32 s30, 13
	s_barrier
	s_cbranch_scc0 .LBB0_539
	s_and_b64 vcc, exec, s[36:37]
	s_cbranch_vccz .LBB0_542
	s_barrier

; #define PG8_STAGE(bufoff, gbase, voff) do { _Pragma("unroll") for (int _i = 0; _i < 2; ++_i) \
;         __builtin_amdgcn_global_load_lds((const unsigned*)((const char*)(gbase) + (voff)[_i]), (LAS unsigned*)(lds + (bufoff) + ldsw + _i * 8192), 16, 0, 0); } while (0)
; #define PG8_LDA(dst, b, h) do { _Pragma("unroll") for (int m = 0; m < 4; ++m) _Pragma("unroll") for (int k = 0; k < 2; ++k) dst[m][k] = *(const LAS bf16x8*)(lds + PG8_SA(b, h) + aoff + m * 2048 + k * 1024); } while (0)
; #define PG8_LDB(dst, b, h) do { _Pragma("unroll") for (int n = 0; n < 2; ++n) _Pragma("unroll") for (int k = 0; k < 2; ++k) dst[n][k] = *(const LAS bf16x8*)(lds + PG8_SB(b, h) + boff + n * 2048 + k * 1024); } while (0)
; #define PG8_MMA(ai, bj, At, Bt) do { __builtin_amdgcn_s_setprio(1); _Pragma("unroll") for (int m = 0; m < 4; ++m) _Pragma("unroll") for (int n = 0; n < 2; ++n) _Pragma("unroll") for (int k = 0; k < 2; ++k) \
;         acc[ai][bj][m][n] = mma16<I8>(Bt[n][k], At[m][k], acc[ai][bj][m][n]); __builtin_amdgcn_s_setprio(0); } while (0)
; #define PG8_WAIT_V(n) asm volatile("s_waitcnt vmcnt(" #n ")" ::: "memory")
; #define PG8_WAIT_L(n) asm volatile("s_waitcnt lgkmcnt(" #n ")" ::: "memory")
; #define PG8_BAR __builtin_amdgcn_s_barrier()
; #define PG8_SCHED __builtin_amdgcn_sched_barrier(0)
; template <class Epi, class Sched, bool I8 = false>
; __device__ __forceinline__ void gemm_phase(LAS unsigned char* lds, const Gemm g, const Sched& S, const Epi& E) {
;     ...
;         for (int t = 0; t < nt; t += 2) {
;             const bool last = (t == nt - 2);
;             const char* a1 = cA + (size_t)(t + 1) * kstep;
;             const char* a2 = last ? nA : cA + (size_t)(t + 2) * kstep; const char* b2 = last ? nB : cB + (size_t)(t + 2) * kstep;
;             const char* a3 = a2 + kstep; const char* b3 = b2 + kstep;
;             if (PG8_SP2) {
;             PG8_LDB(B0, 0, 0); PG8_LDB(B1, 0, 1); PG8_SCHED; PG8_LDA(At, 0, 0); PG8_STAGE(PG8_SA(1, 1), a1 + hstepA, voffA);
;             PG8_WAIT_V(8); PG8_WAIT_L(0); PG8_BAR; PG8_MMA(0, 0, At, B0); PG8_MMA(0, 1, At, B1); PG8_BAR; PG8_SCHED;
;             PG8_LDA(At, 0, 1); PG8_STAGE(PG8_SB(0, 0), b2, voffB); PG8_STAGE(PG8_SB(0, 1), b2 + hstepB, voffB); PG8_STAGE(PG8_SA(0, 0), a2, voffA);
;             PG8_WAIT_V(8); PG8_WAIT_L(0); PG8_BAR; PG8_MMA(1, 0, At, B0); PG8_MMA(1, 1, At, B1); PG8_BAR; PG8_SCHED;
.LBB0_768:
	s_add_u32 s40, s0, 0xfffc0080
	s_addc_u32 s41, s1, -1
	s_add_i32 s46, 0, 0x10000
	s_cmp_eq_u32 s45, 12
	s_cselect_b32 s43, s37, s41
	s_cselect_b32 s42, s36, s40
	s_cselect_b32 s41, s9, s44
	s_cselect_b32 s40, s17, s27
	s_add_i32 s49, 0, 0x14000
	v_add_u32_e32 v14, s46, v163
	v_add_u32_e32 v130, s49, v163
	ds_read_b128 v[2:5], v14
	ds_read_b128 v[6:9], v14 offset:1024
	ds_read_b128 v[10:13], v14 offset:2048
	ds_read_b128 v[14:17], v14 offset:3072
	ds_read_b128 v[132:135], v130
	ds_read_b128 v[174:177], v130 offset:1024
	ds_read_b128 v[178:181], v130 offset:2048
	ds_read_b128 v[182:185], v130 offset:3072
	v_lshl_add_u64 v[136:137], s[0:1], 0, v[170:171]
	s_add_i32 m0, s14, 0xc000
	ds_read_b128 v[186:189], v167
	ds_read_b128 v[190:193], v167 offset:1024
	ds_read_b128 v[194:197], v167 offset:2048
	ds_read_b128 v[198:201], v167 offset:3072
	ds_read_b128 v[212:215], v167 offset:4096
	ds_read_b128 v[216:219], v167 offset:5120
	ds_read_b128 v[220:223], v167 offset:6144
	ds_read_b128 v[224:227], v167 offset:7168
	global_load_lds_dwordx4 v[136:137], off
	v_lshl_add_u64 v[136:137], s[0:1], 0, v[172:173]
	s_add_i32 m0, s14, 0xe000
	s_nop 0
	global_load_lds_dwordx4 v[136:137], off
	s_waitcnt vmcnt(8)
	s_waitcnt lgkmcnt(0)
	s_barrier
	s_setprio 1
	s_waitcnt lgkmcnt(0)
	v_mfma_f32_16x16x32_bf16 v[150:153], v[2:5], v[186:189], v[150:153]
	v_mfma_f32_16x16x32_bf16 v[146:149], v[10:13], v[186:189], v[146:149]
	v_mfma_f32_16x16x32_bf16 v[142:145], v[2:5], v[194:197], v[142:145]
	v_mfma_f32_16x16x32_bf16 v[136:139], v[10:13], v[194:197], v[138:141]
	v_mfma_f32_16x16x32_bf16 v[126:129], v[2:5], v[212:215], v[126:129]
	v_mfma_f32_16x16x32_bf16 v[122:125], v[10:13], v[212:215], v[122:125]
	v_mfma_f32_16x16x32_bf16 v[118:121], v[2:5], v[220:223], v[118:121]
	v_mfma_f32_16x16x32_bf16 v[114:117], v[10:13], v[220:223], v[114:117]
	v_mfma_f32_16x16x32_bf16 v[150:153], v[6:9], v[190:193], v[150:153]
	v_mfma_f32_16x16x32_bf16 v[146:149], v[14:17], v[190:193], v[146:149]
	v_mfma_f32_16x16x32_bf16 v[142:145], v[6:9], v[198:201], v[142:145]
	v_mfma_f32_16x16x32_bf16 v[136:139], v[14:17], v[198:201], v[136:139]
	v_mfma_f32_16x16x32_bf16 v[126:129], v[6:9], v[216:219], v[126:129]
	v_mfma_f32_16x16x32_bf16 v[122:125], v[14:17], v[216:219], v[122:125]
	v_mfma_f32_16x16x32_bf16 v[118:121], v[6:9], v[224:227], v[118:121]
	v_mfma_f32_16x16x32_bf16 v[114:117], v[14:17], v[224:227], v[114:117]
	s_setprio 0
	s_setprio 1
	v_mfma_f32_16x16x32_bf16 v[110:113], v[132:135], v[186:189], v[110:113]
	v_mfma_f32_16x16x32_bf16 v[106:109], v[178:181], v[186:189], v[106:109]
	v_mfma_f32_16x16x32_bf16 v[102:105], v[132:135], v[194:197], v[102:105]
	v_mfma_f32_16x16x32_bf16 v[98:101], v[178:181], v[194:197], v[98:101]
	v_mfma_f32_16x16x32_bf16 v[94:97], v[132:135], v[212:215], v[94:97]
	v_mfma_f32_16x16x32_bf16 v[90:93], v[178:181], v[212:215], v[90:93]
	v_mfma_f32_16x16x32_bf16 v[86:89], v[132:135], v[220:223], v[86:89]
	v_mfma_f32_16x16x32_bf16 v[82:85], v[178:181], v[220:223], v[82:85]
	v_mfma_f32_16x16x32_bf16 v[110:113], v[174:177], v[190:193], v[110:113]
	v_mfma_f32_16x16x32_bf16 v[106:109], v[182:185], v[190:193], v[106:109]
	v_mfma_f32_16x16x32_bf16 v[102:105], v[174:177], v[198:201], v[102:105]
	v_mfma_f32_16x16x32_bf16 v[98:101], v[182:185], v[198:201], v[98:101]
	v_mfma_f32_16x16x32_bf16 v[94:97], v[174:177], v[216:219], v[94:97]
	v_mfma_f32_16x16x32_bf16 v[90:93], v[182:185], v[216:219], v[90:93]
	v_mfma_f32_16x16x32_bf16 v[86:89], v[174:177], v[224:227], v[86:89]
	v_mfma_f32_16x16x32_bf16 v[82:85], v[182:185], v[224:227], v[82:85]
	s_setprio 0
	s_barrier
	s_add_i32 s46, s46, s21
	v_lshl_add_u64 v[202:203], s[40:41], 0, v[158:159]
	s_mov_b32 m0, s46
	ds_read_b128 v[186:189], v167 offset:16384
	ds_read_b128 v[190:193], v167 offset:17408
	ds_read_b128 v[194:197], v167 offset:18432
	ds_read_b128 v[198:201], v167 offset:19456
	ds_read_b128 v[212:215], v167 offset:20480
	ds_read_b128 v[216:219], v167 offset:21504
	ds_read_b128 v[220:223], v167 offset:22528
	ds_read_b128 v[224:227], v167 offset:23552
	global_load_lds_dwordx4 v[202:203], off
	s_add_i32 m0, s46, 0x2000
	s_add_u32 s46, s40, 0x10000
	v_lshl_add_u64 v[232:233], s[40:41], 0, v[154:155]
	s_addc_u32 s47, s41, 0
	s_add_i32 s49, s49, s21
	global_load_lds_dwordx4 v[232:233], off
	v_lshl_add_u64 v[140:141], s[46:47], 0, v[158:159]
	s_mov_b32 m0, s49
	v_lshl_add_u64 v[234:235], s[42:43], 0, v[160:161]
	global_load_lds_dwordx4 v[140:141], off
	v_lshl_add_u64 v[140:141], s[46:47], 0, v[154:155]
	s_add_i32 m0, s49, 0x2000
	v_lshl_add_u64 v[236:237], s[42:43], 0, v[156:157]
	global_load_lds_dwordx4 v[140:141], off
	s_mov_b32 m0, s14
	s_nop 0
	global_load_lds_dwordx4 v[234:235], off
	s_mov_b32 m0, s22
	s_nop 0
	global_load_lds_dwordx4 v[236:237], off
	s_waitcnt vmcnt(8)
	s_waitcnt lgkmcnt(0)
	s_barrier
; #define PG8_STAGE(bufoff, gbase, voff) do { _Pragma("unroll") for (int _i = 0; _i < 2; ++_i) \
;         __builtin_amdgcn_global_load_lds((const unsigned*)((const char*)(gbase) + (voff)[_i]), (LAS unsigned*)(lds + (bufoff) + ldsw + _i * 8192), 16, 0, 0); } while (0)
; #define PG8_LDA(dst, b, h) do { _Pragma("unroll") for (int m = 0; m < 4; ++m) _Pragma("unroll") for (int k = 0; k < 2; ++k) dst[m][k] = *(const LAS bf16x8*)(lds + PG8_SA(b, h) + aoff + m * 2048 + k * 1024); } while (0)
; #define PG8_LDB(dst, b, h) do { _Pragma("unroll") for (int n = 0; n < 2; ++n) _Pragma("unroll") for (int k = 0; k < 2; ++k) dst[n][k] = *(const LAS bf16x8*)(lds + PG8_SB(b, h) + boff + n * 2048 + k * 1024); } while (0)
; #define PG8_MMA(ai, bj, At, Bt) do { __builtin_amdgcn_s_setprio(1); _Pragma("unroll") for (int m = 0; m < 4; ++m) _Pragma("unroll") for (int n = 0; n < 2; ++n) _Pragma("unroll") for (int k = 0; k < 2; ++k) \
;         acc[ai][bj][m][n] = mma16<I8>(Bt[n][k], At[m][k], acc[ai][bj][m][n]); __builtin_amdgcn_s_setprio(0); } while (0)
; #define PG8_WAIT_V(n) asm volatile("s_waitcnt vmcnt(" #n ")" ::: "memory")
; #define PG8_WAIT_L(n) asm volatile("s_waitcnt lgkmcnt(" #n ")" ::: "memory")
; #define PG8_BAR __builtin_amdgcn_s_barrier()
; #define PG8_SCHED __builtin_amdgcn_sched_barrier(0)
; template <class Epi, class Sched, bool I8 = false>
; __device__ __forceinline__ void gemm_phase(LAS unsigned char* lds, const Gemm g, const Sched& S, const Epi& E) {
;     ...
;             PG8_WAIT_V(8); PG8_WAIT_L(0); PG8_BAR; PG8_MMA(1, 0, At, B0); PG8_MMA(1, 1, At, B1); PG8_BAR; PG8_SCHED;
;             PG8_LDB(B0, 1, 0); PG8_LDB(B1, 1, 1); PG8_SCHED; PG8_LDA(At, 1, 0); PG8_STAGE(PG8_SA(0, 1), a2 + hstepA, voffA);
;             PG8_WAIT_V(8); PG8_WAIT_L(0); PG8_BAR; PG8_MMA(0, 0, At, B0); PG8_MMA(0, 1, At, B1); PG8_BAR; PG8_SCHED;
	s_setprio 1
	s_waitcnt lgkmcnt(0)
	v_mfma_f32_16x16x32_bf16 v[78:81], v[2:5], v[186:189], v[78:81]
	v_mfma_f32_16x16x32_bf16 v[74:77], v[10:13], v[186:189], v[74:77]
	v_mfma_f32_16x16x32_bf16 v[70:73], v[2:5], v[194:197], v[70:73]
	v_mfma_f32_16x16x32_bf16 v[66:69], v[10:13], v[194:197], v[66:69]
	v_mfma_f32_16x16x32_bf16 v[62:65], v[2:5], v[212:215], v[62:65]
	v_mfma_f32_16x16x32_bf16 v[58:61], v[10:13], v[212:215], v[58:61]
	v_mfma_f32_16x16x32_bf16 v[2:5], v[2:5], v[220:223], v[54:57]
	v_mfma_f32_16x16x32_bf16 v[78:81], v[6:9], v[190:193], v[78:81]
	v_mfma_f32_16x16x32_bf16 v[74:77], v[14:17], v[190:193], v[74:77]
	v_mfma_f32_16x16x32_bf16 v[70:73], v[6:9], v[198:201], v[70:73]
	v_mfma_f32_16x16x32_bf16 v[66:69], v[14:17], v[198:201], v[66:69]
	v_mfma_f32_16x16x32_bf16 v[62:65], v[6:9], v[216:219], v[62:65]
	v_mfma_f32_16x16x32_bf16 v[58:61], v[14:17], v[216:219], v[58:61]
	v_mfma_f32_16x16x32_bf16 v[2:5], v[6:9], v[224:227], v[2:5]
	v_mfma_f32_16x16x32_bf16 v[6:9], v[10:13], v[220:223], v[50:53]
	v_mfma_f32_16x16x32_bf16 v[6:9], v[14:17], v[224:227], v[6:9]
	s_setprio 0
	s_setprio 1
	v_mfma_f32_16x16x32_bf16 v[38:41], v[132:135], v[194:197], v[38:41]
	v_mfma_f32_16x16x32_bf16 v[34:37], v[178:181], v[194:197], v[34:37]
	v_mfma_f32_16x16x32_bf16 v[30:33], v[132:135], v[212:215], v[30:33]
	v_mfma_f32_16x16x32_bf16 v[26:29], v[178:181], v[212:215], v[26:29]
	v_mfma_f32_16x16x32_bf16 v[22:25], v[132:135], v[220:223], v[22:25]
	v_mfma_f32_16x16x32_bf16 v[18:21], v[178:181], v[220:223], v[18:21]
	v_mfma_f32_16x16x32_bf16 v[10:13], v[132:135], v[186:189], v[46:49]
	v_mfma_f32_16x16x32_bf16 v[14:17], v[178:181], v[186:189], v[42:45]
	v_mfma_f32_16x16x32_bf16 v[38:41], v[174:177], v[198:201], v[38:41]
	v_mfma_f32_16x16x32_bf16 v[34:37], v[182:185], v[198:201], v[34:37]
	v_mfma_f32_16x16x32_bf16 v[30:33], v[174:177], v[216:219], v[30:33]
	v_mfma_f32_16x16x32_bf16 v[26:29], v[182:185], v[216:219], v[26:29]
	v_mfma_f32_16x16x32_bf16 v[22:25], v[174:177], v[224:227], v[22:25]
	v_mfma_f32_16x16x32_bf16 v[18:21], v[182:185], v[224:227], v[18:21]
	v_mfma_f32_16x16x32_bf16 v[10:13], v[174:177], v[190:193], v[10:13]
	v_mfma_f32_16x16x32_bf16 v[14:17], v[182:185], v[190:193], v[14:17]
	s_setprio 0
	s_barrier
	s_add_i32 s46, 0, 0x18000
	v_add_u32_e32 v54, s46, v163
	s_add_i32 s47, 0, 0x1c000
	ds_read_b128 v[42:45], v54
	ds_read_b128 v[46:49], v54 offset:1024
	ds_read_b128 v[50:53], v54 offset:2048
	ds_read_b128 v[132:135], v54 offset:3072
	v_add_u32_e32 v54, s47, v163
	ds_read_b128 v[174:177], v54
	ds_read_b128 v[178:181], v54 offset:1024
	ds_read_b128 v[182:185], v54 offset:2048
	ds_read_b128 v[186:189], v54 offset:3072
	s_add_u32 s42, s42, 0x40000
	s_addc_u32 s43, s43, 0
	s_mov_b32 m0, s23
	v_lshl_add_u64 v[140:141], s[42:43], 0, v[160:161]
	ds_read_b128 v[54:57], v167 offset:32768
	ds_read_b128 v[190:193], v167 offset:33792
	ds_read_b128 v[194:197], v167 offset:34816
	ds_read_b128 v[198:201], v167 offset:35840
	ds_read_b128 v[212:215], v167 offset:36864
	ds_read_b128 v[216:219], v167 offset:37888
	ds_read_b128 v[220:223], v167 offset:38912
	ds_read_b128 v[224:227], v167 offset:39936
	global_load_lds_dwordx4 v[140:141], off
	v_lshl_add_u64 v[140:141], s[42:43], 0, v[156:157]
	s_mov_b32 m0, s24
	s_nop 0
	global_load_lds_dwordx4 v[140:141], off
	s_waitcnt vmcnt(8)
	s_waitcnt lgkmcnt(0)
	s_barrier
	s_setprio 1
	s_waitcnt lgkmcnt(0)
	v_mfma_f32_16x16x32_bf16 v[150:153], v[42:45], v[54:57], v[150:153]
	v_mfma_f32_16x16x32_bf16 v[146:149], v[50:53], v[54:57], v[146:149]
	v_mfma_f32_16x16x32_bf16 v[140:143], v[42:45], v[194:197], v[142:145]
	v_mfma_f32_16x16x32_bf16 v[136:139], v[50:53], v[194:197], v[136:139]
	v_mfma_f32_16x16x32_bf16 v[126:129], v[42:45], v[212:215], v[126:129]
	v_mfma_f32_16x16x32_bf16 v[122:125], v[50:53], v[212:215], v[122:125]
	v_mfma_f32_16x16x32_bf16 v[118:121], v[42:45], v[220:223], v[118:121]
	v_mfma_f32_16x16x32_bf16 v[114:117], v[50:53], v[220:223], v[114:117]
	v_mfma_f32_16x16x32_bf16 v[150:153], v[46:49], v[190:193], v[150:153]
	v_mfma_f32_16x16x32_bf16 v[146:149], v[132:135], v[190:193], v[146:149]
	v_mfma_f32_16x16x32_bf16 v[142:145], v[46:49], v[198:201], v[140:143]
	v_mfma_f32_16x16x32_bf16 v[138:141], v[132:135], v[198:201], v[136:139]
	v_mfma_f32_16x16x32_bf16 v[126:129], v[46:49], v[216:219], v[126:129]
	v_mfma_f32_16x16x32_bf16 v[122:125], v[132:135], v[216:219], v[122:125]
	v_mfma_f32_16x16x32_bf16 v[118:121], v[46:49], v[224:227], v[118:121]
	v_mfma_f32_16x16x32_bf16 v[114:117], v[132:135], v[224:227], v[114:117]
	s_setprio 0
	s_setprio 1
	v_mfma_f32_16x16x32_bf16 v[110:113], v[174:177], v[54:57], v[110:113]
	v_mfma_f32_16x16x32_bf16 v[54:57], v[182:185], v[54:57], v[106:109]
	v_mfma_f32_16x16x32_bf16 v[106:109], v[186:189], v[190:193], v[54:57]
	v_mfma_f32_16x16x32_bf16 v[54:57], v[174:177], v[194:197], v[102:105]
	v_mfma_f32_16x16x32_bf16 v[102:105], v[178:181], v[198:201], v[54:57]
	v_mfma_f32_16x16x32_bf16 v[54:57], v[182:185], v[194:197], v[98:101]
	v_mfma_f32_16x16x32_bf16 v[98:101], v[186:189], v[198:201], v[54:57]
	v_mfma_f32_16x16x32_bf16 v[54:57], v[174:177], v[212:215], v[94:97]
	v_mfma_f32_16x16x32_bf16 v[94:97], v[178:181], v[216:219], v[54:57]
	v_mfma_f32_16x16x32_bf16 v[54:57], v[182:185], v[212:215], v[90:93]
	v_mfma_f32_16x16x32_bf16 v[90:93], v[186:189], v[216:219], v[54:57]
	v_mfma_f32_16x16x32_bf16 v[54:57], v[174:177], v[220:223], v[86:89]
	v_mfma_f32_16x16x32_bf16 v[86:89], v[178:181], v[224:227], v[54:57]
	v_mfma_f32_16x16x32_bf16 v[54:57], v[182:185], v[220:223], v[82:85]
	v_mfma_f32_16x16x32_bf16 v[110:113], v[178:181], v[190:193], v[110:113]
	v_mfma_f32_16x16x32_bf16 v[82:85], v[186:189], v[224:227], v[54:57]
	s_setprio 0
	s_barrier
; #define PG8_STAGE(bufoff, gbase, voff) do { _Pragma("unroll") for (int _i = 0; _i < 2; ++_i) \
;         __builtin_amdgcn_global_load_lds((const unsigned*)((const char*)(gbase) + (voff)[_i]), (LAS unsigned*)(lds + (bufoff) + ldsw + _i * 8192), 16, 0, 0); } while (0)
; #define PG8_LDA(dst, b, h) do { _Pragma("unroll") for (int m = 0; m < 4; ++m) _Pragma("unroll") for (int k = 0; k < 2; ++k) dst[m][k] = *(const LAS bf16x8*)(lds + PG8_SA(b, h) + aoff + m * 2048 + k * 1024); } while (0)
; #define PG8_MMA(ai, bj, At, Bt) do { __builtin_amdgcn_s_setprio(1); _Pragma("unroll") for (int m = 0; m < 4; ++m) _Pragma("unroll") for (int n = 0; n < 2; ++n) _Pragma("unroll") for (int k = 0; k < 2; ++k) \
;         acc[ai][bj][m][n] = mma16<I8>(Bt[n][k], At[m][k], acc[ai][bj][m][n]); __builtin_amdgcn_s_setprio(0); } while (0)
; #define PG8_WAIT_V(n) asm volatile("s_waitcnt vmcnt(" #n ")" ::: "memory")
; #define PG8_WAIT_L(n) asm volatile("s_waitcnt lgkmcnt(" #n ")" ::: "memory")
; #define PG8_BAR __builtin_amdgcn_s_barrier()
; #define PG8_SCHED __builtin_amdgcn_sched_barrier(0)
; template <class Epi, class Sched, bool I8 = false>
; __device__ __forceinline__ void gemm_phase(LAS unsigned char* lds, const Gemm g, const Sched& S, const Epi& E) {
;     ...
;         for (int t = 0; t < nt; t += 2) {
;             const bool last = (t == nt - 2);
;             const char* a1 = cA + (size_t)(t + 1) * kstep;
;             const char* a2 = last ? nA : cA + (size_t)(t + 2) * kstep; const char* b2 = last ? nB : cB + (size_t)(t + 2) * kstep;
;             const char* a3 = a2 + kstep; const char* b3 = b2 + kstep;
;     ...
;             PG8_LDA(At, 1, 1); PG8_STAGE(PG8_SB(1, 0), b3, voffB); PG8_STAGE(PG8_SB(1, 1), b3 + hstepB, voffB); PG8_STAGE(PG8_SA(1, 0), a3, voffA);
;             PG8_WAIT_V(8); PG8_WAIT_L(0); PG8_BAR; PG8_MMA(1, 0, At, B0); PG8_MMA(1, 1, At, B1); PG8_BAR; PG8_SCHED;
	s_add_i32 s42, s46, s21
	s_nop 2
	v_lshl_add_u64 v[54:55], v[202:203], 0, s[12:13]
	s_mov_b32 m0, s42
	ds_read_b128 v[190:193], v167 offset:49152
	ds_read_b128 v[194:197], v167 offset:50176
	ds_read_b128 v[198:201], v167 offset:51200
	ds_read_b128 v[212:215], v167 offset:52224
	ds_read_b128 v[216:219], v167 offset:53248
	ds_read_b128 v[220:223], v167 offset:54272
	ds_read_b128 v[224:227], v167 offset:55296
	ds_read_b128 v[228:231], v167 offset:56320
	global_load_lds_dwordx4 v[54:55], off
	s_add_i32 m0, s42, 0x2000
	s_add_u32 s40, s40, 0x10080
	v_lshl_add_u64 v[54:55], v[232:233], 0, s[12:13]
	s_addc_u32 s41, s41, 0
	s_add_i32 s42, s47, s21
	global_load_lds_dwordx4 v[54:55], off
	v_lshl_add_u64 v[54:55], s[40:41], 0, v[158:159]
	s_mov_b32 m0, s42
	s_nop 0
	global_load_lds_dwordx4 v[54:55], off
	v_lshl_add_u64 v[54:55], s[40:41], 0, v[154:155]
	s_add_i32 m0, s42, 0x2000
	s_nop 0
	global_load_lds_dwordx4 v[54:55], off
	v_lshl_add_u64 v[54:55], v[234:235], 0, s[12:13]
	s_mov_b32 m0, s29
	s_nop 0
	global_load_lds_dwordx4 v[54:55], off
	v_lshl_add_u64 v[54:55], v[236:237], 0, s[12:13]
	s_mov_b32 m0, s30
	s_nop 0
	global_load_lds_dwordx4 v[54:55], off
	s_waitcnt vmcnt(8)
	s_waitcnt lgkmcnt(0)
	s_barrier
	s_setprio 1
	s_waitcnt lgkmcnt(0)
	v_mfma_f32_16x16x32_bf16 v[54:57], v[42:45], v[190:193], v[78:81]
	v_mfma_f32_16x16x32_bf16 v[78:81], v[46:49], v[194:197], v[54:57]
	v_mfma_f32_16x16x32_bf16 v[54:57], v[50:53], v[190:193], v[74:77]
	v_mfma_f32_16x16x32_bf16 v[74:77], v[132:135], v[194:197], v[54:57]
	v_mfma_f32_16x16x32_bf16 v[54:57], v[42:45], v[198:201], v[70:73]
	v_mfma_f32_16x16x32_bf16 v[70:73], v[46:49], v[212:215], v[54:57]
	v_mfma_f32_16x16x32_bf16 v[54:57], v[50:53], v[198:201], v[66:69]
	v_mfma_f32_16x16x32_bf16 v[66:69], v[132:135], v[212:215], v[54:57]
	v_mfma_f32_16x16x32_bf16 v[54:57], v[42:45], v[216:219], v[62:65]
	v_mfma_f32_16x16x32_bf16 v[62:65], v[46:49], v[220:223], v[54:57]
	v_mfma_f32_16x16x32_bf16 v[54:57], v[50:53], v[216:219], v[58:61]
	v_mfma_f32_16x16x32_bf16 v[2:5], v[42:45], v[224:227], v[2:5]
	v_mfma_f32_16x16x32_bf16 v[58:61], v[132:135], v[220:223], v[54:57]
	v_mfma_f32_16x16x32_bf16 v[54:57], v[46:49], v[228:231], v[2:5]
	v_mfma_f32_16x16x32_bf16 v[2:5], v[50:53], v[224:227], v[6:9]
	v_mfma_f32_16x16x32_bf16 v[50:53], v[132:135], v[228:231], v[2:5]
	s_setprio 0
	s_setprio 1
	v_mfma_f32_16x16x32_bf16 v[2:5], v[174:177], v[190:193], v[10:13]
	v_mfma_f32_16x16x32_bf16 v[46:49], v[178:181], v[194:197], v[2:5]
	v_mfma_f32_16x16x32_bf16 v[2:5], v[182:185], v[190:193], v[14:17]
	v_mfma_f32_16x16x32_bf16 v[42:45], v[186:189], v[194:197], v[2:5]
	v_mfma_f32_16x16x32_bf16 v[2:5], v[174:177], v[198:201], v[38:41]
	v_mfma_f32_16x16x32_bf16 v[38:41], v[178:181], v[212:215], v[2:5]
	v_mfma_f32_16x16x32_bf16 v[2:5], v[182:185], v[198:201], v[34:37]
	v_mfma_f32_16x16x32_bf16 v[34:37], v[186:189], v[212:215], v[2:5]
	v_mfma_f32_16x16x32_bf16 v[2:5], v[174:177], v[216:219], v[30:33]
	v_mfma_f32_16x16x32_bf16 v[30:33], v[178:181], v[220:223], v[2:5]
	v_mfma_f32_16x16x32_bf16 v[2:5], v[182:185], v[216:219], v[26:29]
	v_mfma_f32_16x16x32_bf16 v[26:29], v[186:189], v[220:223], v[2:5]
	v_mfma_f32_16x16x32_bf16 v[2:5], v[174:177], v[224:227], v[22:25]
	v_mfma_f32_16x16x32_bf16 v[22:25], v[178:181], v[228:231], v[2:5]
	v_mfma_f32_16x16x32_bf16 v[2:5], v[182:185], v[224:227], v[18:21]
	v_mfma_f32_16x16x32_bf16 v[18:21], v[186:189], v[228:231], v[2:5]
	s_setprio 0
	s_add_i32 s45, s45, 2
	s_add_u32 s0, s0, 0x100
	s_addc_u32 s1, s1, 0
	s_add_u32 s27, s27, 0x100
	s_addc_u32 s44, s44, 0
	s_cmp_gt_u32 s45, 13
	s_barrier
	s_cbranch_scc0 .LBB0_768
	s_and_b64 vcc, exec, s[6:7]
	s_cbranch_vccz .LBB0_771
	s_barrier

; #define PG8_STAGE(bufoff, gbase, voff) do { _Pragma("unroll") for (int _i = 0; _i < 2; ++_i) \
;         __builtin_amdgcn_global_load_lds((const unsigned*)((const char*)(gbase) + (voff)[_i]), (LAS unsigned*)(lds + (bufoff) + ldsw + _i * 8192), 16, 0, 0); } while (0)
; #define PG8_LDA(dst, b, h) do { _Pragma("unroll") for (int m = 0; m < 4; ++m) _Pragma("unroll") for (int k = 0; k < 2; ++k) dst[m][k] = *(const LAS bf16x8*)(lds + PG8_SA(b, h) + aoff + m * 2048 + k * 1024); } while (0)
; #define PG8_LDB(dst, b, h) do { _Pragma("unroll") for (int n = 0; n < 2; ++n) _Pragma("unroll") for (int k = 0; k < 2; ++k) dst[n][k] = *(const LAS bf16x8*)(lds + PG8_SB(b, h) + boff + n * 2048 + k * 1024); } while (0)
; #define PG8_MMA(ai, bj, At, Bt) do { __builtin_amdgcn_s_setprio(1); _Pragma("unroll") for (int m = 0; m < 4; ++m) _Pragma("unroll") for (int n = 0; n < 2; ++n) _Pragma("unroll") for (int k = 0; k < 2; ++k) \
;         acc[ai][bj][m][n] = mma16<I8>(Bt[n][k], At[m][k], acc[ai][bj][m][n]); __builtin_amdgcn_s_setprio(0); } while (0)
; #define PG8_WAIT_V(n) asm volatile("s_waitcnt vmcnt(" #n ")" ::: "memory")
; #define PG8_WAIT_L(n) asm volatile("s_waitcnt lgkmcnt(" #n ")" ::: "memory")
; #define PG8_BAR __builtin_amdgcn_s_barrier()
; #define PG8_SCHED __builtin_amdgcn_sched_barrier(0)
; template <class Epi, class Sched, bool I8 = false>
; __device__ __forceinline__ void gemm_phase(LAS unsigned char* lds, const Gemm g, const Sched& S, const Epi& E) {
;     ...
;         for (int t = 0; t < nt; t += 2) {
;             const bool last = (t == nt - 2);
;             const char* a1 = cA + (size_t)(t + 1) * kstep;
;             const char* a2 = last ? nA : cA + (size_t)(t + 2) * kstep; const char* b2 = last ? nB : cB + (size_t)(t + 2) * kstep;
;             const char* a3 = a2 + kstep; const char* b3 = b2 + kstep;
;             if (PG8_SP2) {
;             PG8_LDB(B0, 0, 0); PG8_LDB(B1, 0, 1); PG8_SCHED; PG8_LDA(At, 0, 0); PG8_STAGE(PG8_SA(1, 1), a1 + hstepA, voffA);
;             PG8_WAIT_V(8); PG8_WAIT_L(0); PG8_BAR; PG8_MMA(0, 0, At, B0); PG8_MMA(0, 1, At, B1); PG8_BAR; PG8_SCHED;
;             PG8_LDA(At, 0, 1); PG8_STAGE(PG8_SB(0, 0), b2, voffB); PG8_STAGE(PG8_SB(0, 1), b2 + hstepB, voffB); PG8_STAGE(PG8_SA(0, 0), a2, voffA);
;             PG8_WAIT_V(8); PG8_WAIT_L(0); PG8_BAR; PG8_MMA(1, 0, At, B0); PG8_MMA(1, 1, At, B1); PG8_BAR; PG8_SCHED;
.LBB0_901:
	s_add_u32 s6, s4, 0x100
	s_addc_u32 s7, s5, 0
	s_cmp_lg_u32 s29, 12
	s_cselect_b32 s8, s6, 0
	s_add_u32 s16, s40, s8
	s_addc_u32 s17, s41, 0
	s_add_i32 s30, 0, 0x10000
	s_add_u32 s8, s0, s8
	s_addc_u32 s9, s1, 0
	s_add_i32 s31, 0, 0x14000
	v_add_u32_e32 v158, s30, v144
	v_add_u32_e32 v174, s31, v144
	ds_read_b128 v[146:149], v158
	ds_read_b128 v[150:153], v158 offset:1024
	ds_read_b128 v[154:157], v158 offset:2048
	ds_read_b128 v[158:161], v158 offset:3072
	ds_read_b128 v[162:165], v174
	ds_read_b128 v[166:169], v174 offset:1024
	ds_read_b128 v[170:173], v174 offset:2048
	ds_read_b128 v[174:177], v174 offset:3072
	v_lshl_add_u64 v[202:203], v[138:139], 0, s[4:5]
	s_add_i32 m0, s2, 0xc000
	ds_read_b128 v[178:181], v145
	ds_read_b128 v[182:185], v145 offset:1024
	ds_read_b128 v[186:189], v145 offset:2048
	ds_read_b128 v[190:193], v145 offset:3072
	ds_read_b128 v[194:197], v145 offset:4096
	ds_read_b128 v[198:201], v145 offset:5120
	ds_read_b128 v[212:215], v145 offset:6144
	ds_read_b128 v[216:219], v145 offset:7168
	global_load_lds_dwordx4 v[202:203], off
	v_lshl_add_u64 v[202:203], v[140:141], 0, s[4:5]
	s_add_i32 m0, s2, 0xe000
	s_nop 0
	global_load_lds_dwordx4 v[202:203], off
	s_waitcnt vmcnt(8)
	s_waitcnt lgkmcnt(0)
	s_barrier
	s_setprio 1
	s_waitcnt lgkmcnt(0)
	v_mfma_f32_16x16x32_bf16 v[126:129], v[146:149], v[178:181], v[126:129]
	v_mfma_f32_16x16x32_bf16 v[122:125], v[154:157], v[178:181], v[122:125]
	v_mfma_f32_16x16x32_bf16 v[118:121], v[146:149], v[186:189], v[118:121]
	v_mfma_f32_16x16x32_bf16 v[114:117], v[154:157], v[186:189], v[114:117]
	v_mfma_f32_16x16x32_bf16 v[110:113], v[146:149], v[194:197], v[110:113]
	v_mfma_f32_16x16x32_bf16 v[102:105], v[154:157], v[194:197], v[102:105]
	v_mfma_f32_16x16x32_bf16 v[94:97], v[146:149], v[212:215], v[94:97]
	v_mfma_f32_16x16x32_bf16 v[86:89], v[154:157], v[212:215], v[86:89]
	v_mfma_f32_16x16x32_bf16 v[126:129], v[150:153], v[182:185], v[126:129]
	v_mfma_f32_16x16x32_bf16 v[122:125], v[158:161], v[182:185], v[122:125]
	v_mfma_f32_16x16x32_bf16 v[118:121], v[150:153], v[190:193], v[118:121]
	v_mfma_f32_16x16x32_bf16 v[114:117], v[158:161], v[190:193], v[114:117]
	v_mfma_f32_16x16x32_bf16 v[110:113], v[150:153], v[198:201], v[110:113]
	v_mfma_f32_16x16x32_bf16 v[102:105], v[158:161], v[198:201], v[102:105]
	v_mfma_f32_16x16x32_bf16 v[94:97], v[150:153], v[216:219], v[94:97]
	v_mfma_f32_16x16x32_bf16 v[86:89], v[158:161], v[216:219], v[86:89]
	s_setprio 0
	s_setprio 1
	v_mfma_f32_16x16x32_bf16 v[106:109], v[162:165], v[178:181], v[106:109]
	v_mfma_f32_16x16x32_bf16 v[98:101], v[170:173], v[178:181], v[98:101]
	v_mfma_f32_16x16x32_bf16 v[90:93], v[162:165], v[186:189], v[90:93]
	v_mfma_f32_16x16x32_bf16 v[82:85], v[170:173], v[186:189], v[82:85]
	v_mfma_f32_16x16x32_bf16 v[78:81], v[162:165], v[194:197], v[78:81]
	v_mfma_f32_16x16x32_bf16 v[74:77], v[170:173], v[194:197], v[74:77]
	v_mfma_f32_16x16x32_bf16 v[70:73], v[162:165], v[212:215], v[70:73]
	v_mfma_f32_16x16x32_bf16 v[66:69], v[170:173], v[212:215], v[66:69]
	v_mfma_f32_16x16x32_bf16 v[106:109], v[166:169], v[182:185], v[106:109]
	v_mfma_f32_16x16x32_bf16 v[98:101], v[174:177], v[182:185], v[98:101]
	v_mfma_f32_16x16x32_bf16 v[90:93], v[166:169], v[190:193], v[90:93]
	v_mfma_f32_16x16x32_bf16 v[82:85], v[174:177], v[190:193], v[82:85]
	v_mfma_f32_16x16x32_bf16 v[78:81], v[166:169], v[198:201], v[78:81]
	v_mfma_f32_16x16x32_bf16 v[74:77], v[174:177], v[198:201], v[74:77]
	v_mfma_f32_16x16x32_bf16 v[70:73], v[166:169], v[216:219], v[70:73]
	v_mfma_f32_16x16x32_bf16 v[66:69], v[174:177], v[216:219], v[66:69]
	s_setprio 0
	s_barrier
	s_add_i32 s4, s30, s21
	v_lshl_add_u64 v[202:203], s[8:9], 0, v[130:131]
	s_mov_b32 m0, s4
	ds_read_b128 v[178:181], v145 offset:16384
	ds_read_b128 v[182:185], v145 offset:17408
	ds_read_b128 v[186:189], v145 offset:18432
	ds_read_b128 v[190:193], v145 offset:19456
	ds_read_b128 v[194:197], v145 offset:20480
	ds_read_b128 v[198:201], v145 offset:21504
	ds_read_b128 v[212:215], v145 offset:22528
	ds_read_b128 v[216:219], v145 offset:23552
	global_load_lds_dwordx4 v[202:203], off
	s_add_i32 m0, s4, 0x2000
	s_add_u32 s4, s8, 0x10000
	v_lshl_add_u64 v[220:221], s[8:9], 0, v[132:133]
	s_addc_u32 s5, s9, 0
	s_add_i32 s30, s31, s21
	global_load_lds_dwordx4 v[220:221], off
	v_lshl_add_u64 v[222:223], s[4:5], 0, v[130:131]
	s_mov_b32 m0, s30
	v_lshl_add_u64 v[224:225], s[16:17], 0, v[134:135]
	global_load_lds_dwordx4 v[222:223], off
	v_lshl_add_u64 v[222:223], s[4:5], 0, v[132:133]
	s_add_i32 m0, s30, 0x2000
	s_nop 0
	global_load_lds_dwordx4 v[222:223], off
	v_lshl_add_u64 v[222:223], s[16:17], 0, v[136:137]
	s_mov_b32 m0, s2
	s_nop 0
	global_load_lds_dwordx4 v[222:223], off
	s_mov_b32 m0, s3
	s_nop 0
	global_load_lds_dwordx4 v[224:225], off
	s_waitcnt vmcnt(8)
	s_waitcnt lgkmcnt(0)
	s_barrier
; #define PG8_STAGE(bufoff, gbase, voff) do { _Pragma("unroll") for (int _i = 0; _i < 2; ++_i) \
;         __builtin_amdgcn_global_load_lds((const unsigned*)((const char*)(gbase) + (voff)[_i]), (LAS unsigned*)(lds + (bufoff) + ldsw + _i * 8192), 16, 0, 0); } while (0)
; #define PG8_LDA(dst, b, h) do { _Pragma("unroll") for (int m = 0; m < 4; ++m) _Pragma("unroll") for (int k = 0; k < 2; ++k) dst[m][k] = *(const LAS bf16x8*)(lds + PG8_SA(b, h) + aoff + m * 2048 + k * 1024); } while (0)
; #define PG8_LDB(dst, b, h) do { _Pragma("unroll") for (int n = 0; n < 2; ++n) _Pragma("unroll") for (int k = 0; k < 2; ++k) dst[n][k] = *(const LAS bf16x8*)(lds + PG8_SB(b, h) + boff + n * 2048 + k * 1024); } while (0)
; #define PG8_MMA(ai, bj, At, Bt) do { __builtin_amdgcn_s_setprio(1); _Pragma("unroll") for (int m = 0; m < 4; ++m) _Pragma("unroll") for (int n = 0; n < 2; ++n) _Pragma("unroll") for (int k = 0; k < 2; ++k) \
;         acc[ai][bj][m][n] = mma16<I8>(Bt[n][k], At[m][k], acc[ai][bj][m][n]); __builtin_amdgcn_s_setprio(0); } while (0)
; #define PG8_WAIT_V(n) asm volatile("s_waitcnt vmcnt(" #n ")" ::: "memory")
; #define PG8_WAIT_L(n) asm volatile("s_waitcnt lgkmcnt(" #n ")" ::: "memory")
; #define PG8_BAR __builtin_amdgcn_s_barrier()
; #define PG8_SCHED __builtin_amdgcn_sched_barrier(0)
; template <class Epi, class Sched, bool I8 = false>
; __device__ __forceinline__ void gemm_phase(LAS unsigned char* lds, const Gemm g, const Sched& S, const Epi& E) {
;     ...
;             PG8_WAIT_V(8); PG8_WAIT_L(0); PG8_BAR; PG8_MMA(1, 0, At, B0); PG8_MMA(1, 1, At, B1); PG8_BAR; PG8_SCHED;
;             PG8_LDB(B0, 1, 0); PG8_LDB(B1, 1, 1); PG8_SCHED; PG8_LDA(At, 1, 0); PG8_STAGE(PG8_SA(0, 1), a2 + hstepA, voffA);
;             PG8_WAIT_V(8); PG8_WAIT_L(0); PG8_BAR; PG8_MMA(0, 0, At, B0); PG8_MMA(0, 1, At, B1); PG8_BAR; PG8_SCHED;
	s_setprio 1
	s_waitcnt lgkmcnt(0)
	v_mfma_f32_16x16x32_bf16 v[62:65], v[146:149], v[178:181], v[62:65]
	v_mfma_f32_16x16x32_bf16 v[58:61], v[154:157], v[178:181], v[58:61]
	v_mfma_f32_16x16x32_bf16 v[54:57], v[146:149], v[186:189], v[54:57]
	v_mfma_f32_16x16x32_bf16 v[50:53], v[154:157], v[186:189], v[50:53]
	v_mfma_f32_16x16x32_bf16 v[42:45], v[146:149], v[194:197], v[42:45]
	v_mfma_f32_16x16x32_bf16 v[34:37], v[154:157], v[194:197], v[34:37]
	v_mfma_f32_16x16x32_bf16 v[26:29], v[146:149], v[212:215], v[26:29]
	v_mfma_f32_16x16x32_bf16 v[18:21], v[154:157], v[212:215], v[18:21]
	v_mfma_f32_16x16x32_bf16 v[62:65], v[150:153], v[182:185], v[62:65]
	v_mfma_f32_16x16x32_bf16 v[58:61], v[158:161], v[182:185], v[58:61]
	v_mfma_f32_16x16x32_bf16 v[54:57], v[150:153], v[190:193], v[54:57]
	v_mfma_f32_16x16x32_bf16 v[50:53], v[158:161], v[190:193], v[50:53]
	v_mfma_f32_16x16x32_bf16 v[42:45], v[150:153], v[198:201], v[42:45]
	v_mfma_f32_16x16x32_bf16 v[34:37], v[158:161], v[198:201], v[34:37]
	v_mfma_f32_16x16x32_bf16 v[26:29], v[150:153], v[216:219], v[26:29]
	v_mfma_f32_16x16x32_bf16 v[18:21], v[158:161], v[216:219], v[18:21]
	s_setprio 0
	s_setprio 1
	v_mfma_f32_16x16x32_bf16 v[46:49], v[162:165], v[178:181], v[46:49]
	v_mfma_f32_16x16x32_bf16 v[38:41], v[170:173], v[178:181], v[38:41]
	v_mfma_f32_16x16x32_bf16 v[30:33], v[162:165], v[186:189], v[30:33]
	v_mfma_f32_16x16x32_bf16 v[22:25], v[170:173], v[186:189], v[22:25]
	v_mfma_f32_16x16x32_bf16 v[14:17], v[162:165], v[194:197], v[14:17]
	v_mfma_f32_16x16x32_bf16 v[10:13], v[170:173], v[194:197], v[10:13]
	v_mfma_f32_16x16x32_bf16 v[6:9], v[162:165], v[212:215], v[6:9]
	v_mfma_f32_16x16x32_bf16 v[2:5], v[170:173], v[212:215], v[2:5]
	v_mfma_f32_16x16x32_bf16 v[46:49], v[166:169], v[182:185], v[46:49]
	v_mfma_f32_16x16x32_bf16 v[38:41], v[174:177], v[182:185], v[38:41]
	v_mfma_f32_16x16x32_bf16 v[30:33], v[166:169], v[190:193], v[30:33]
	v_mfma_f32_16x16x32_bf16 v[22:25], v[174:177], v[190:193], v[22:25]
	v_mfma_f32_16x16x32_bf16 v[14:17], v[166:169], v[198:201], v[14:17]
	v_mfma_f32_16x16x32_bf16 v[10:13], v[174:177], v[198:201], v[10:13]
	v_mfma_f32_16x16x32_bf16 v[6:9], v[166:169], v[216:219], v[6:9]
	v_mfma_f32_16x16x32_bf16 v[2:5], v[174:177], v[216:219], v[2:5]
	s_setprio 0
	s_barrier
	s_add_i32 s30, 0, 0x18000
	s_add_i32 s31, 0, 0x1c000
	v_add_u32_e32 v158, s30, v144
	v_add_u32_e32 v174, s31, v144
	ds_read_b128 v[146:149], v158
	ds_read_b128 v[150:153], v158 offset:1024
	ds_read_b128 v[154:157], v158 offset:2048
	ds_read_b128 v[158:161], v158 offset:3072
	ds_read_b128 v[162:165], v174
	ds_read_b128 v[166:169], v174 offset:1024
	ds_read_b128 v[170:173], v174 offset:2048
	ds_read_b128 v[174:177], v174 offset:3072
	s_add_u32 s4, s16, 0x40000
	s_addc_u32 s5, s17, 0
	s_mov_b32 m0, s22
	v_lshl_add_u64 v[226:227], s[4:5], 0, v[136:137]
	ds_read_b128 v[178:181], v145 offset:32768
	ds_read_b128 v[182:185], v145 offset:33792
	ds_read_b128 v[186:189], v145 offset:34816
	ds_read_b128 v[190:193], v145 offset:35840
	ds_read_b128 v[194:197], v145 offset:36864
	ds_read_b128 v[198:201], v145 offset:37888
	ds_read_b128 v[212:215], v145 offset:38912
	ds_read_b128 v[216:219], v145 offset:39936
	global_load_lds_dwordx4 v[226:227], off
	v_lshl_add_u64 v[226:227], s[4:5], 0, v[134:135]
	s_mov_b32 m0, s23
	s_nop 0
	global_load_lds_dwordx4 v[226:227], off
	s_waitcnt vmcnt(8)
	s_waitcnt lgkmcnt(0)
	s_barrier
	s_setprio 1
	s_waitcnt lgkmcnt(0)
	v_mfma_f32_16x16x32_bf16 v[126:129], v[146:149], v[178:181], v[126:129]
	v_mfma_f32_16x16x32_bf16 v[122:125], v[154:157], v[178:181], v[122:125]
	v_mfma_f32_16x16x32_bf16 v[118:121], v[146:149], v[186:189], v[118:121]
	v_mfma_f32_16x16x32_bf16 v[114:117], v[154:157], v[186:189], v[114:117]
	v_mfma_f32_16x16x32_bf16 v[110:113], v[146:149], v[194:197], v[110:113]
	v_mfma_f32_16x16x32_bf16 v[102:105], v[154:157], v[194:197], v[102:105]
	v_mfma_f32_16x16x32_bf16 v[94:97], v[146:149], v[212:215], v[94:97]
	v_mfma_f32_16x16x32_bf16 v[86:89], v[154:157], v[212:215], v[86:89]
	v_mfma_f32_16x16x32_bf16 v[126:129], v[150:153], v[182:185], v[126:129]
	v_mfma_f32_16x16x32_bf16 v[122:125], v[158:161], v[182:185], v[122:125]
	v_mfma_f32_16x16x32_bf16 v[118:121], v[150:153], v[190:193], v[118:121]
	v_mfma_f32_16x16x32_bf16 v[114:117], v[158:161], v[190:193], v[114:117]
	v_mfma_f32_16x16x32_bf16 v[110:113], v[150:153], v[198:201], v[110:113]
	v_mfma_f32_16x16x32_bf16 v[102:105], v[158:161], v[198:201], v[102:105]
	v_mfma_f32_16x16x32_bf16 v[94:97], v[150:153], v[216:219], v[94:97]
	v_mfma_f32_16x16x32_bf16 v[86:89], v[158:161], v[216:219], v[86:89]
	s_setprio 0
	s_setprio 1
	v_mfma_f32_16x16x32_bf16 v[106:109], v[162:165], v[178:181], v[106:109]
	v_mfma_f32_16x16x32_bf16 v[98:101], v[170:173], v[178:181], v[98:101]
	v_mfma_f32_16x16x32_bf16 v[90:93], v[162:165], v[186:189], v[90:93]
	v_mfma_f32_16x16x32_bf16 v[82:85], v[170:173], v[186:189], v[82:85]
	v_mfma_f32_16x16x32_bf16 v[78:81], v[162:165], v[194:197], v[78:81]
	v_mfma_f32_16x16x32_bf16 v[74:77], v[170:173], v[194:197], v[74:77]
	v_mfma_f32_16x16x32_bf16 v[70:73], v[162:165], v[212:215], v[70:73]
	v_mfma_f32_16x16x32_bf16 v[66:69], v[170:173], v[212:215], v[66:69]
	v_mfma_f32_16x16x32_bf16 v[106:109], v[166:169], v[182:185], v[106:109]
	v_mfma_f32_16x16x32_bf16 v[98:101], v[174:177], v[182:185], v[98:101]
	v_mfma_f32_16x16x32_bf16 v[90:93], v[166:169], v[190:193], v[90:93]
	v_mfma_f32_16x16x32_bf16 v[82:85], v[174:177], v[190:193], v[82:85]
	v_mfma_f32_16x16x32_bf16 v[78:81], v[166:169], v[198:201], v[78:81]
	v_mfma_f32_16x16x32_bf16 v[74:77], v[174:177], v[198:201], v[74:77]
	v_mfma_f32_16x16x32_bf16 v[70:73], v[166:169], v[216:219], v[70:73]
	v_mfma_f32_16x16x32_bf16 v[66:69], v[174:177], v[216:219], v[66:69]
	s_setprio 0
	s_barrier
; #define PG8_STAGE(bufoff, gbase, voff) do { _Pragma("unroll") for (int _i = 0; _i < 2; ++_i) \
;         __builtin_amdgcn_global_load_lds((const unsigned*)((const char*)(gbase) + (voff)[_i]), (LAS unsigned*)(lds + (bufoff) + ldsw + _i * 8192), 16, 0, 0); } while (0)
; #define PG8_LDA(dst, b, h) do { _Pragma("unroll") for (int m = 0; m < 4; ++m) _Pragma("unroll") for (int k = 0; k < 2; ++k) dst[m][k] = *(const LAS bf16x8*)(lds + PG8_SA(b, h) + aoff + m * 2048 + k * 1024); } while (0)
; #define PG8_MMA(ai, bj, At, Bt) do { __builtin_amdgcn_s_setprio(1); _Pragma("unroll") for (int m = 0; m < 4; ++m) _Pragma("unroll") for (int n = 0; n < 2; ++n) _Pragma("unroll") for (int k = 0; k < 2; ++k) \
;         acc[ai][bj][m][n] = mma16<I8>(Bt[n][k], At[m][k], acc[ai][bj][m][n]); __builtin_amdgcn_s_setprio(0); } while (0)
; #define PG8_WAIT_V(n) asm volatile("s_waitcnt vmcnt(" #n ")" ::: "memory")
; #define PG8_WAIT_L(n) asm volatile("s_waitcnt lgkmcnt(" #n ")" ::: "memory")
; #define PG8_BAR __builtin_amdgcn_s_barrier()
; #define PG8_SCHED __builtin_amdgcn_sched_barrier(0)
; template <class Epi, class Sched, bool I8 = false>
; __device__ __forceinline__ void gemm_phase(LAS unsigned char* lds, const Gemm g, const Sched& S, const Epi& E) {
;     ...
;         for (int t = 0; t < nt; t += 2) {
;             const bool last = (t == nt - 2);
;             const char* a1 = cA + (size_t)(t + 1) * kstep;
;             const char* a2 = last ? nA : cA + (size_t)(t + 2) * kstep; const char* b2 = last ? nB : cB + (size_t)(t + 2) * kstep;
;             const char* a3 = a2 + kstep; const char* b3 = b2 + kstep;
;     ...
;             PG8_LDA(At, 1, 1); PG8_STAGE(PG8_SB(1, 0), b3, voffB); PG8_STAGE(PG8_SB(1, 1), b3 + hstepB, voffB); PG8_STAGE(PG8_SA(1, 0), a3, voffA);
;             PG8_WAIT_V(8); PG8_WAIT_L(0); PG8_BAR; PG8_MMA(1, 0, At, B0); PG8_MMA(1, 1, At, B1); PG8_BAR; PG8_SCHED;
	s_add_i32 s4, s30, s21
	v_lshl_add_u64 v[202:203], v[202:203], 0, s[12:13]
	s_mov_b32 m0, s4
	ds_read_b128 v[178:181], v145 offset:49152
	ds_read_b128 v[182:185], v145 offset:50176
	ds_read_b128 v[186:189], v145 offset:51200
	ds_read_b128 v[190:193], v145 offset:52224
	ds_read_b128 v[194:197], v145 offset:53248
	ds_read_b128 v[198:201], v145 offset:54272
	ds_read_b128 v[212:215], v145 offset:55296
	ds_read_b128 v[216:219], v145 offset:56320
	global_load_lds_dwordx4 v[202:203], off
	s_add_i32 m0, s4, 0x2000
	s_add_u32 s4, s8, 0x10080
	v_lshl_add_u64 v[202:203], v[220:221], 0, s[12:13]
	s_addc_u32 s5, s9, 0
	s_add_i32 s8, s31, s21
	global_load_lds_dwordx4 v[202:203], off
	v_lshl_add_u64 v[202:203], s[4:5], 0, v[130:131]
	s_mov_b32 m0, s8
	s_nop 0
	global_load_lds_dwordx4 v[202:203], off
	v_lshl_add_u64 v[202:203], s[4:5], 0, v[132:133]
	s_add_i32 m0, s8, 0x2000
	s_nop 0
	global_load_lds_dwordx4 v[202:203], off
	v_lshl_add_u64 v[202:203], v[222:223], 0, s[12:13]
	s_mov_b32 m0, s26
	s_nop 0
	global_load_lds_dwordx4 v[202:203], off
	v_lshl_add_u64 v[202:203], v[224:225], 0, s[12:13]
	s_mov_b32 m0, s27
	s_nop 0
	global_load_lds_dwordx4 v[202:203], off
	s_waitcnt vmcnt(8)
	s_waitcnt lgkmcnt(0)
	s_barrier
	s_setprio 1
	s_waitcnt lgkmcnt(0)
	v_mfma_f32_16x16x32_bf16 v[62:65], v[146:149], v[178:181], v[62:65]
	v_mfma_f32_16x16x32_bf16 v[58:61], v[154:157], v[178:181], v[58:61]
	v_mfma_f32_16x16x32_bf16 v[54:57], v[146:149], v[186:189], v[54:57]
	v_mfma_f32_16x16x32_bf16 v[50:53], v[154:157], v[186:189], v[50:53]
	v_mfma_f32_16x16x32_bf16 v[42:45], v[146:149], v[194:197], v[42:45]
	v_mfma_f32_16x16x32_bf16 v[34:37], v[154:157], v[194:197], v[34:37]
	v_mfma_f32_16x16x32_bf16 v[26:29], v[146:149], v[212:215], v[26:29]
	v_mfma_f32_16x16x32_bf16 v[18:21], v[154:157], v[212:215], v[18:21]
	v_mfma_f32_16x16x32_bf16 v[62:65], v[150:153], v[182:185], v[62:65]
	v_mfma_f32_16x16x32_bf16 v[58:61], v[158:161], v[182:185], v[58:61]
	v_mfma_f32_16x16x32_bf16 v[54:57], v[150:153], v[190:193], v[54:57]
	v_mfma_f32_16x16x32_bf16 v[50:53], v[158:161], v[190:193], v[50:53]
	v_mfma_f32_16x16x32_bf16 v[42:45], v[150:153], v[198:201], v[42:45]
	v_mfma_f32_16x16x32_bf16 v[34:37], v[158:161], v[198:201], v[34:37]
	v_mfma_f32_16x16x32_bf16 v[26:29], v[150:153], v[216:219], v[26:29]
	v_mfma_f32_16x16x32_bf16 v[18:21], v[158:161], v[216:219], v[18:21]
	s_setprio 0
	s_setprio 1
	v_mfma_f32_16x16x32_bf16 v[46:49], v[162:165], v[178:181], v[46:49]
	v_mfma_f32_16x16x32_bf16 v[38:41], v[170:173], v[178:181], v[38:41]
	v_mfma_f32_16x16x32_bf16 v[30:33], v[162:165], v[186:189], v[30:33]
	v_mfma_f32_16x16x32_bf16 v[22:25], v[170:173], v[186:189], v[22:25]
	v_mfma_f32_16x16x32_bf16 v[14:17], v[162:165], v[194:197], v[14:17]
	v_mfma_f32_16x16x32_bf16 v[10:13], v[170:173], v[194:197], v[10:13]
	v_mfma_f32_16x16x32_bf16 v[6:9], v[162:165], v[212:215], v[6:9]
	v_mfma_f32_16x16x32_bf16 v[2:5], v[170:173], v[212:215], v[2:5]
	v_mfma_f32_16x16x32_bf16 v[46:49], v[166:169], v[182:185], v[46:49]
	v_mfma_f32_16x16x32_bf16 v[38:41], v[174:177], v[182:185], v[38:41]
	v_mfma_f32_16x16x32_bf16 v[30:33], v[166:169], v[190:193], v[30:33]
	v_mfma_f32_16x16x32_bf16 v[22:25], v[174:177], v[190:193], v[22:25]
	v_mfma_f32_16x16x32_bf16 v[14:17], v[166:169], v[198:201], v[14:17]
	v_mfma_f32_16x16x32_bf16 v[10:13], v[174:177], v[198:201], v[10:13]
	v_mfma_f32_16x16x32_bf16 v[6:9], v[166:169], v[216:219], v[6:9]
	v_mfma_f32_16x16x32_bf16 v[2:5], v[174:177], v[216:219], v[2:5]
	s_setprio 0
	s_add_i32 s29, s29, 2
	s_cmp_gt_u32 s29, 13
	s_mov_b64 s[4:5], s[6:7]
	s_barrier
	s_cbranch_scc0 .LBB0_901
	s_cmpk_lt_u32 s14, 0x100
	s_cbranch_scc0 .LBB0_904
	s_barrier

;     __device__ __forceinline__ bool next(int i, Unit& u) const { u.seg = 0; u.ks = -1; u.nt = ntk; u.koff = 0; return unit(i, u); }
;     __device__ __forceinline__ bool next(int i, Unit& u) const { const int t = i / 3; u.seg = i - 3 * t; u.ks = -1; u.nt = ntk; u.koff = 0; return unit(t, u); }
;     __device__ __forceinline__ bool next(int i, Unit& u) const { if (i > 0 || c < 80 || c >= 144) return false; const int k = c - 80; u.pm = k & 1; u.pn = k >> 1; u.seg = 0; u.ks = -1; u.nt = DM / BK; u.koff = 0; return true; }
; #define PG8_STAGE(bufoff, gbase, voff) do { _Pragma("unroll") for (int _i = 0; _i < 2; ++_i) \
;         __builtin_amdgcn_global_load_lds((const unsigned*)((const char*)(gbase) + (voff)[_i]), (LAS unsigned*)(lds + (bufoff) + ldsw + _i * 8192), 16, 0, 0); } while (0)
; #define PG8_LDA(dst, b, h) do { _Pragma("unroll") for (int m = 0; m < 4; ++m) _Pragma("unroll") for (int k = 0; k < 2; ++k) dst[m][k] = *(const LAS bf16x8*)(lds + PG8_SA(b, h) + aoff + m * 2048 + k * 1024); } while (0)
; template <class Epi, class Sched, bool I8 = false>
; __device__ __forceinline__ void gemm_phase(LAS unsigned char* lds, const Gemm g, const Sched& S, const Epi& E) {
;     ...
;         const bool has_next = S.next(ui + 1, nxt);
;         const char* nA = has_next ? g.A + (size_t)nxt.seg * g.segA + (size_t)nxt.pm * tstepA + nxt.koff : cA; const char* nB = has_next ? g.Bt + (size_t)nxt.seg * g.segB + (size_t)nxt.pn * tstepB + nxt.koff : cB;
;         const int nt = cur.nt;
;         for (int t = 0; t < nt; t += 2) {
;             const bool last = (t == nt - 2);
;             const char* a1 = cA + (size_t)(t + 1) * kstep;
;             const char* a2 = last ? nA : cA + (size_t)(t + 2) * kstep; const char* b2 = last ? nB : cB + (size_t)(t + 2) * kstep;
;             const char* a3 = a2 + kstep; const char* b3 = b2 + kstep;
;             if (PG8_SP2) {
;             PG8_LDB(B0, 0, 0); PG8_LDB(B1, 0, 1); PG8_SCHED; PG8_LDA(At, 0, 0); PG8_STAGE(PG8_SA(1, 1), a1 + hstepA, voffA);
;             PG8_WAIT_V(8); PG8_WAIT_L(0); PG8_BAR; PG8_MMA(0, 0, At, B0); PG8_MMA(0, 1, At, B1); PG8_BAR; PG8_SCHED;
;             PG8_LDA(At, 0, 1); PG8_STAGE(PG8_SB(0, 0), b2, voffB); PG8_STAGE(PG8_SB(0, 1), b2 + hstepB, voffB); PG8_STAGE(PG8_SA(0, 0), a2, voffA);
;             PG8_WAIT_V(8); PG8_WAIT_L(0); PG8_BAR; PG8_MMA(1, 0, At, B0); PG8_MMA(1, 1, At, B1); PG8_BAR; PG8_SCHED;
.LBB0_1153:
	s_add_i32 s63, s58, 2
	s_add_u32 s42, s40, 0xfff80080
	s_addc_u32 s43, s41, -1
	s_add_i32 s82, 0, 0x10000
	s_cmp_eq_u32 s47, s58
	s_cselect_b32 s59, s9, s43
	s_cselect_b32 s58, s45, s42
	v_add_u32_e32 v130, s82, v143
	s_cselect_b32 s43, s17, s62
	s_cselect_b32 s42, s46, s49
	s_add_i32 s84, 0, 0x14000
	ds_read_b128 v[150:153], v130
	ds_read_b128 v[154:157], v130 offset:1024
	ds_read_b128 v[158:161], v130 offset:2048
	ds_read_b128 v[162:165], v130 offset:3072
	v_add_u32_e32 v130, s84, v143
	ds_read_b128 v[166:169], v130
	ds_read_b128 v[170:173], v130 offset:1024
	ds_read_b128 v[174:177], v130 offset:2048
	ds_read_b128 v[178:181], v130 offset:3072
	v_lshl_add_u64 v[202:203], s[40:41], 0, v[146:147]
	s_add_i32 m0, s21, 0xc000
	ds_read_b128 v[182:185], v145
	ds_read_b128 v[186:189], v145 offset:1024
	ds_read_b128 v[190:193], v145 offset:2048
	ds_read_b128 v[194:197], v145 offset:3072
	ds_read_b128 v[198:201], v145 offset:4096
	ds_read_b128 v[212:215], v145 offset:5120
	ds_read_b128 v[216:219], v145 offset:6144
	ds_read_b128 v[220:223], v145 offset:7168
	global_load_lds_dwordx4 v[202:203], off
	v_lshl_add_u64 v[202:203], s[40:41], 0, v[148:149]
	s_add_i32 m0, s21, 0xe000
	s_nop 0
	global_load_lds_dwordx4 v[202:203], off
	s_waitcnt vmcnt(8)
	s_waitcnt lgkmcnt(0)
	s_barrier
	s_setprio 1
	s_waitcnt lgkmcnt(0)
	v_mfma_f32_16x16x32_bf16 v[126:129], v[150:153], v[182:185], v[126:129]
	v_mfma_f32_16x16x32_bf16 v[122:125], v[158:161], v[182:185], v[122:125]
	v_mfma_f32_16x16x32_bf16 v[110:113], v[150:153], v[190:193], v[110:113]
	v_mfma_f32_16x16x32_bf16 v[106:109], v[158:161], v[190:193], v[106:109]
	v_mfma_f32_16x16x32_bf16 v[94:97], v[150:153], v[198:201], v[94:97]
	v_mfma_f32_16x16x32_bf16 v[90:93], v[158:161], v[198:201], v[90:93]
	v_mfma_f32_16x16x32_bf16 v[78:81], v[150:153], v[216:219], v[78:81]
	v_mfma_f32_16x16x32_bf16 v[74:77], v[158:161], v[216:219], v[74:77]
	v_mfma_f32_16x16x32_bf16 v[126:129], v[154:157], v[186:189], v[126:129]
	v_mfma_f32_16x16x32_bf16 v[122:125], v[162:165], v[186:189], v[122:125]
	v_mfma_f32_16x16x32_bf16 v[110:113], v[154:157], v[194:197], v[110:113]
	v_mfma_f32_16x16x32_bf16 v[106:109], v[162:165], v[194:197], v[106:109]
	v_mfma_f32_16x16x32_bf16 v[94:97], v[154:157], v[212:215], v[94:97]
	v_mfma_f32_16x16x32_bf16 v[90:93], v[162:165], v[212:215], v[90:93]
	v_mfma_f32_16x16x32_bf16 v[78:81], v[154:157], v[220:223], v[78:81]
	v_mfma_f32_16x16x32_bf16 v[74:77], v[162:165], v[220:223], v[74:77]
	s_setprio 0
	s_setprio 1
	v_mfma_f32_16x16x32_bf16 v[118:121], v[166:169], v[182:185], v[118:121]
	v_mfma_f32_16x16x32_bf16 v[114:117], v[174:177], v[182:185], v[114:117]
	v_mfma_f32_16x16x32_bf16 v[102:105], v[166:169], v[190:193], v[102:105]
	v_mfma_f32_16x16x32_bf16 v[98:101], v[174:177], v[190:193], v[98:101]
	v_mfma_f32_16x16x32_bf16 v[86:89], v[166:169], v[198:201], v[86:89]
	v_mfma_f32_16x16x32_bf16 v[82:85], v[174:177], v[198:201], v[82:85]
	v_mfma_f32_16x16x32_bf16 v[70:73], v[166:169], v[216:219], v[70:73]
	v_mfma_f32_16x16x32_bf16 v[66:69], v[174:177], v[216:219], v[66:69]
	v_mfma_f32_16x16x32_bf16 v[118:121], v[170:173], v[186:189], v[118:121]
	v_mfma_f32_16x16x32_bf16 v[114:117], v[178:181], v[186:189], v[114:117]
	v_mfma_f32_16x16x32_bf16 v[102:105], v[170:173], v[194:197], v[102:105]
	v_mfma_f32_16x16x32_bf16 v[98:101], v[178:181], v[194:197], v[98:101]
	v_mfma_f32_16x16x32_bf16 v[86:89], v[170:173], v[212:215], v[86:89]
	v_mfma_f32_16x16x32_bf16 v[82:85], v[178:181], v[212:215], v[82:85]
	v_mfma_f32_16x16x32_bf16 v[70:73], v[170:173], v[220:223], v[70:73]
	v_mfma_f32_16x16x32_bf16 v[66:69], v[178:181], v[220:223], v[66:69]
	s_setprio 0
	s_barrier
	s_add_i32 s82, s82, s14
	v_lshl_add_u64 v[202:203], s[42:43], 0, v[136:137]
	s_mov_b32 m0, s82
	ds_read_b128 v[182:185], v145 offset:16384
	ds_read_b128 v[186:189], v145 offset:17408
	ds_read_b128 v[190:193], v145 offset:18432
	ds_read_b128 v[194:197], v145 offset:19456
	ds_read_b128 v[198:201], v145 offset:20480
	ds_read_b128 v[212:215], v145 offset:21504
	ds_read_b128 v[216:219], v145 offset:22528
	ds_read_b128 v[220:223], v145 offset:23552
	global_load_lds_dwordx4 v[202:203], off
	s_add_i32 m0, s82, 0x2000
	s_add_u32 s82, s42, 0x20000
	v_lshl_add_u64 v[224:225], s[42:43], 0, v[132:133]
	s_addc_u32 s83, s43, 0
	s_add_i32 s84, s84, s14
	global_load_lds_dwordx4 v[224:225], off
	v_lshl_add_u64 v[226:227], s[82:83], 0, v[136:137]
	s_mov_b32 m0, s84
	v_lshl_add_u64 v[228:229], s[58:59], 0, v[134:135]
	global_load_lds_dwordx4 v[226:227], off
	v_lshl_add_u64 v[226:227], s[82:83], 0, v[132:133]
	s_add_i32 m0, s84, 0x2000
	s_nop 0
	global_load_lds_dwordx4 v[226:227], off
	v_lshl_add_u64 v[226:227], s[58:59], 0, v[138:139]
	s_mov_b32 m0, s21
	s_nop 0
	global_load_lds_dwordx4 v[226:227], off
	s_mov_b32 m0, s22
	s_nop 0
	global_load_lds_dwordx4 v[228:229], off
	s_waitcnt vmcnt(8)
	s_waitcnt lgkmcnt(0)
	s_barrier
; #define PG8_STAGE(bufoff, gbase, voff) do { _Pragma("unroll") for (int _i = 0; _i < 2; ++_i) \
;         __builtin_amdgcn_global_load_lds((const unsigned*)((const char*)(gbase) + (voff)[_i]), (LAS unsigned*)(lds + (bufoff) + ldsw + _i * 8192), 16, 0, 0); } while (0)
; #define PG8_LDA(dst, b, h) do { _Pragma("unroll") for (int m = 0; m < 4; ++m) _Pragma("unroll") for (int k = 0; k < 2; ++k) dst[m][k] = *(const LAS bf16x8*)(lds + PG8_SA(b, h) + aoff + m * 2048 + k * 1024); } while (0)
; #define PG8_LDB(dst, b, h) do { _Pragma("unroll") for (int n = 0; n < 2; ++n) _Pragma("unroll") for (int k = 0; k < 2; ++k) dst[n][k] = *(const LAS bf16x8*)(lds + PG8_SB(b, h) + boff + n * 2048 + k * 1024); } while (0)
; #define PG8_MMA(ai, bj, At, Bt) do { __builtin_amdgcn_s_setprio(1); _Pragma("unroll") for (int m = 0; m < 4; ++m) _Pragma("unroll") for (int n = 0; n < 2; ++n) _Pragma("unroll") for (int k = 0; k < 2; ++k) \
;         acc[ai][bj][m][n] = mma16<I8>(Bt[n][k], At[m][k], acc[ai][bj][m][n]); __builtin_amdgcn_s_setprio(0); } while (0)
; #define PG8_WAIT_V(n) asm volatile("s_waitcnt vmcnt(" #n ")" ::: "memory")
; #define PG8_WAIT_L(n) asm volatile("s_waitcnt lgkmcnt(" #n ")" ::: "memory")
; #define PG8_BAR __builtin_amdgcn_s_barrier()
; #define PG8_SCHED __builtin_amdgcn_sched_barrier(0)
; template <class Epi, class Sched, bool I8 = false>
; __device__ __forceinline__ void gemm_phase(LAS unsigned char* lds, const Gemm g, const Sched& S, const Epi& E) {
;     ...
;             PG8_WAIT_V(8); PG8_WAIT_L(0); PG8_BAR; PG8_MMA(1, 0, At, B0); PG8_MMA(1, 1, At, B1); PG8_BAR; PG8_SCHED;
;             PG8_LDB(B0, 1, 0); PG8_LDB(B1, 1, 1); PG8_SCHED; PG8_LDA(At, 1, 0); PG8_STAGE(PG8_SA(0, 1), a2 + hstepA, voffA);
;             PG8_WAIT_V(8); PG8_WAIT_L(0); PG8_BAR; PG8_MMA(0, 0, At, B0); PG8_MMA(0, 1, At, B1); PG8_BAR; PG8_SCHED;
	s_setprio 1
	s_waitcnt lgkmcnt(0)
	v_mfma_f32_16x16x32_bf16 v[62:65], v[150:153], v[182:185], v[62:65]
	v_mfma_f32_16x16x32_bf16 v[58:61], v[158:161], v[182:185], v[58:61]
	v_mfma_f32_16x16x32_bf16 v[46:49], v[150:153], v[190:193], v[46:49]
	v_mfma_f32_16x16x32_bf16 v[42:45], v[158:161], v[190:193], v[42:45]
	v_mfma_f32_16x16x32_bf16 v[30:33], v[150:153], v[198:201], v[30:33]
	v_mfma_f32_16x16x32_bf16 v[26:29], v[158:161], v[198:201], v[26:29]
	v_mfma_f32_16x16x32_bf16 v[14:17], v[150:153], v[216:219], v[14:17]
	v_mfma_f32_16x16x32_bf16 v[10:13], v[158:161], v[216:219], v[10:13]
	v_mfma_f32_16x16x32_bf16 v[62:65], v[154:157], v[186:189], v[62:65]
	v_mfma_f32_16x16x32_bf16 v[58:61], v[162:165], v[186:189], v[58:61]
	v_mfma_f32_16x16x32_bf16 v[46:49], v[154:157], v[194:197], v[46:49]
	v_mfma_f32_16x16x32_bf16 v[42:45], v[162:165], v[194:197], v[42:45]
	v_mfma_f32_16x16x32_bf16 v[30:33], v[154:157], v[212:215], v[30:33]
	v_mfma_f32_16x16x32_bf16 v[26:29], v[162:165], v[212:215], v[26:29]
	v_mfma_f32_16x16x32_bf16 v[14:17], v[154:157], v[220:223], v[14:17]
	v_mfma_f32_16x16x32_bf16 v[10:13], v[162:165], v[220:223], v[10:13]
	s_setprio 0
	s_setprio 1
	v_mfma_f32_16x16x32_bf16 v[54:57], v[166:169], v[182:185], v[54:57]
	v_mfma_f32_16x16x32_bf16 v[50:53], v[174:177], v[182:185], v[50:53]
	v_mfma_f32_16x16x32_bf16 v[38:41], v[166:169], v[190:193], v[38:41]
	v_mfma_f32_16x16x32_bf16 v[34:37], v[174:177], v[190:193], v[34:37]
	v_mfma_f32_16x16x32_bf16 v[22:25], v[166:169], v[198:201], v[22:25]
	v_mfma_f32_16x16x32_bf16 v[18:21], v[174:177], v[198:201], v[18:21]
	v_mfma_f32_16x16x32_bf16 v[6:9], v[166:169], v[216:219], v[6:9]
	v_mfma_f32_16x16x32_bf16 v[2:5], v[174:177], v[216:219], v[2:5]
	v_mfma_f32_16x16x32_bf16 v[54:57], v[170:173], v[186:189], v[54:57]
	v_mfma_f32_16x16x32_bf16 v[50:53], v[178:181], v[186:189], v[50:53]
	v_mfma_f32_16x16x32_bf16 v[38:41], v[170:173], v[194:197], v[38:41]
	v_mfma_f32_16x16x32_bf16 v[34:37], v[178:181], v[194:197], v[34:37]
	v_mfma_f32_16x16x32_bf16 v[22:25], v[170:173], v[212:215], v[22:25]
	v_mfma_f32_16x16x32_bf16 v[18:21], v[178:181], v[212:215], v[18:21]
	v_mfma_f32_16x16x32_bf16 v[6:9], v[170:173], v[220:223], v[6:9]
	v_mfma_f32_16x16x32_bf16 v[2:5], v[178:181], v[220:223], v[2:5]
	s_setprio 0
	s_barrier
	s_add_i32 s82, 0, 0x18000
	v_add_u32_e32 v130, s82, v143
	s_add_i32 s83, 0, 0x1c000
	ds_read_b128 v[150:153], v130
	ds_read_b128 v[154:157], v130 offset:1024
	ds_read_b128 v[158:161], v130 offset:2048
	ds_read_b128 v[162:165], v130 offset:3072
	v_add_u32_e32 v130, s83, v143
	ds_read_b128 v[166:169], v130
	ds_read_b128 v[170:173], v130 offset:1024
	ds_read_b128 v[174:177], v130 offset:2048
	ds_read_b128 v[178:181], v130 offset:3072
	s_add_u32 s58, s58, 0x80000
	s_addc_u32 s59, s59, 0
	s_mov_b32 m0, s23
	v_lshl_add_u64 v[230:231], s[58:59], 0, v[138:139]
	ds_read_b128 v[182:185], v145 offset:32768
	ds_read_b128 v[186:189], v145 offset:33792
	ds_read_b128 v[190:193], v145 offset:34816
	ds_read_b128 v[194:197], v145 offset:35840
	ds_read_b128 v[198:201], v145 offset:36864
	ds_read_b128 v[212:215], v145 offset:37888
	ds_read_b128 v[216:219], v145 offset:38912
	ds_read_b128 v[220:223], v145 offset:39936
	global_load_lds_dwordx4 v[230:231], off
	v_lshl_add_u64 v[230:231], s[58:59], 0, v[134:135]
	s_mov_b32 m0, s24
	s_nop 0
	global_load_lds_dwordx4 v[230:231], off
	s_waitcnt vmcnt(8)
	s_waitcnt lgkmcnt(0)
	s_barrier
	s_setprio 1
	s_waitcnt lgkmcnt(0)
	v_mfma_f32_16x16x32_bf16 v[126:129], v[150:153], v[182:185], v[126:129]
	v_mfma_f32_16x16x32_bf16 v[122:125], v[158:161], v[182:185], v[122:125]
	v_mfma_f32_16x16x32_bf16 v[110:113], v[150:153], v[190:193], v[110:113]
	v_mfma_f32_16x16x32_bf16 v[106:109], v[158:161], v[190:193], v[106:109]
	v_mfma_f32_16x16x32_bf16 v[94:97], v[150:153], v[198:201], v[94:97]
	v_mfma_f32_16x16x32_bf16 v[90:93], v[158:161], v[198:201], v[90:93]
	v_mfma_f32_16x16x32_bf16 v[78:81], v[150:153], v[216:219], v[78:81]
	v_mfma_f32_16x16x32_bf16 v[74:77], v[158:161], v[216:219], v[74:77]
	v_mfma_f32_16x16x32_bf16 v[126:129], v[154:157], v[186:189], v[126:129]
	v_mfma_f32_16x16x32_bf16 v[122:125], v[162:165], v[186:189], v[122:125]
	v_mfma_f32_16x16x32_bf16 v[110:113], v[154:157], v[194:197], v[110:113]
	v_mfma_f32_16x16x32_bf16 v[106:109], v[162:165], v[194:197], v[106:109]
	v_mfma_f32_16x16x32_bf16 v[94:97], v[154:157], v[212:215], v[94:97]
	v_mfma_f32_16x16x32_bf16 v[90:93], v[162:165], v[212:215], v[90:93]
	v_mfma_f32_16x16x32_bf16 v[78:81], v[154:157], v[220:223], v[78:81]
	v_mfma_f32_16x16x32_bf16 v[74:77], v[162:165], v[220:223], v[74:77]
	s_setprio 0
	s_setprio 1
	v_mfma_f32_16x16x32_bf16 v[118:121], v[166:169], v[182:185], v[118:121]
	v_mfma_f32_16x16x32_bf16 v[114:117], v[174:177], v[182:185], v[114:117]
	v_mfma_f32_16x16x32_bf16 v[102:105], v[166:169], v[190:193], v[102:105]
	v_mfma_f32_16x16x32_bf16 v[98:101], v[174:177], v[190:193], v[98:101]
	v_mfma_f32_16x16x32_bf16 v[86:89], v[166:169], v[198:201], v[86:89]
	v_mfma_f32_16x16x32_bf16 v[82:85], v[174:177], v[198:201], v[82:85]
	v_mfma_f32_16x16x32_bf16 v[70:73], v[166:169], v[216:219], v[70:73]
	v_mfma_f32_16x16x32_bf16 v[66:69], v[174:177], v[216:219], v[66:69]
	v_mfma_f32_16x16x32_bf16 v[118:121], v[170:173], v[186:189], v[118:121]
	v_mfma_f32_16x16x32_bf16 v[114:117], v[178:181], v[186:189], v[114:117]
	v_mfma_f32_16x16x32_bf16 v[102:105], v[170:173], v[194:197], v[102:105]
	v_mfma_f32_16x16x32_bf16 v[98:101], v[178:181], v[194:197], v[98:101]
	v_mfma_f32_16x16x32_bf16 v[86:89], v[170:173], v[212:215], v[86:89]
	v_mfma_f32_16x16x32_bf16 v[82:85], v[178:181], v[212:215], v[82:85]
	v_mfma_f32_16x16x32_bf16 v[70:73], v[170:173], v[220:223], v[70:73]
	v_mfma_f32_16x16x32_bf16 v[66:69], v[178:181], v[220:223], v[66:69]
	s_setprio 0
	s_barrier
; #define PG8_STAGE(bufoff, gbase, voff) do { _Pragma("unroll") for (int _i = 0; _i < 2; ++_i) \
;         __builtin_amdgcn_global_load_lds((const unsigned*)((const char*)(gbase) + (voff)[_i]), (LAS unsigned*)(lds + (bufoff) + ldsw + _i * 8192), 16, 0, 0); } while (0)
; #define PG8_LDA(dst, b, h) do { _Pragma("unroll") for (int m = 0; m < 4; ++m) _Pragma("unroll") for (int k = 0; k < 2; ++k) dst[m][k] = *(const LAS bf16x8*)(lds + PG8_SA(b, h) + aoff + m * 2048 + k * 1024); } while (0)
; #define PG8_MMA(ai, bj, At, Bt) do { __builtin_amdgcn_s_setprio(1); _Pragma("unroll") for (int m = 0; m < 4; ++m) _Pragma("unroll") for (int n = 0; n < 2; ++n) _Pragma("unroll") for (int k = 0; k < 2; ++k) \
;         acc[ai][bj][m][n] = mma16<I8>(Bt[n][k], At[m][k], acc[ai][bj][m][n]); __builtin_amdgcn_s_setprio(0); } while (0)
; #define PG8_WAIT_V(n) asm volatile("s_waitcnt vmcnt(" #n ")" ::: "memory")
; #define PG8_WAIT_L(n) asm volatile("s_waitcnt lgkmcnt(" #n ")" ::: "memory")
; #define PG8_BAR __builtin_amdgcn_s_barrier()
; #define PG8_SCHED __builtin_amdgcn_sched_barrier(0)
; template <class Epi, class Sched, bool I8 = false>
; __device__ __forceinline__ void gemm_phase(LAS unsigned char* lds, const Gemm g, const Sched& S, const Epi& E) {
;     ...
;         for (int t = 0; t < nt; t += 2) {
;             const bool last = (t == nt - 2);
;     ...
;             PG8_LDA(At, 1, 1); PG8_STAGE(PG8_SB(1, 0), b3, voffB); PG8_STAGE(PG8_SB(1, 1), b3 + hstepB, voffB); PG8_STAGE(PG8_SA(1, 0), a3, voffA);
;             PG8_WAIT_V(8); PG8_WAIT_L(0); PG8_BAR; PG8_MMA(1, 0, At, B0); PG8_MMA(1, 1, At, B1); PG8_BAR; PG8_SCHED;
	s_add_i32 s58, s82, s14
	v_lshl_add_u64 v[202:203], v[202:203], 0, s[12:13]
	s_mov_b32 m0, s58
	ds_read_b128 v[182:185], v145 offset:49152
	ds_read_b128 v[186:189], v145 offset:50176
	ds_read_b128 v[190:193], v145 offset:51200
	ds_read_b128 v[194:197], v145 offset:52224
	ds_read_b128 v[198:201], v145 offset:53248
	ds_read_b128 v[212:215], v145 offset:54272
	ds_read_b128 v[216:219], v145 offset:55296
	ds_read_b128 v[220:223], v145 offset:56320
	global_load_lds_dwordx4 v[202:203], off
	s_add_i32 m0, s58, 0x2000
	s_add_u32 s42, s42, 0x20080
	v_lshl_add_u64 v[202:203], v[224:225], 0, s[12:13]
	s_addc_u32 s43, s43, 0
	s_add_i32 s58, s83, s14
	global_load_lds_dwordx4 v[202:203], off
	v_lshl_add_u64 v[202:203], s[42:43], 0, v[136:137]
	s_mov_b32 m0, s58
	s_nop 0
	global_load_lds_dwordx4 v[202:203], off
	v_lshl_add_u64 v[202:203], s[42:43], 0, v[132:133]
	s_add_i32 m0, s58, 0x2000
	s_nop 0
	global_load_lds_dwordx4 v[202:203], off
	v_lshl_add_u64 v[202:203], v[226:227], 0, s[12:13]
	s_mov_b32 m0, s30
	s_nop 0
	global_load_lds_dwordx4 v[202:203], off
	v_lshl_add_u64 v[202:203], v[228:229], 0, s[12:13]
	s_mov_b32 m0, s31
	s_nop 0
	global_load_lds_dwordx4 v[202:203], off
	s_waitcnt vmcnt(8)
	s_waitcnt lgkmcnt(0)
	s_barrier
	s_setprio 1
	s_waitcnt lgkmcnt(0)
	v_mfma_f32_16x16x32_bf16 v[62:65], v[150:153], v[182:185], v[62:65]
	v_mfma_f32_16x16x32_bf16 v[58:61], v[158:161], v[182:185], v[58:61]
	v_mfma_f32_16x16x32_bf16 v[46:49], v[150:153], v[190:193], v[46:49]
	v_mfma_f32_16x16x32_bf16 v[42:45], v[158:161], v[190:193], v[42:45]
	v_mfma_f32_16x16x32_bf16 v[30:33], v[150:153], v[198:201], v[30:33]
	v_mfma_f32_16x16x32_bf16 v[26:29], v[158:161], v[198:201], v[26:29]
	v_mfma_f32_16x16x32_bf16 v[14:17], v[150:153], v[216:219], v[14:17]
	v_mfma_f32_16x16x32_bf16 v[10:13], v[158:161], v[216:219], v[10:13]
	v_mfma_f32_16x16x32_bf16 v[62:65], v[154:157], v[186:189], v[62:65]
	v_mfma_f32_16x16x32_bf16 v[58:61], v[162:165], v[186:189], v[58:61]
	v_mfma_f32_16x16x32_bf16 v[46:49], v[154:157], v[194:197], v[46:49]
	v_mfma_f32_16x16x32_bf16 v[42:45], v[162:165], v[194:197], v[42:45]
	v_mfma_f32_16x16x32_bf16 v[30:33], v[154:157], v[212:215], v[30:33]
	v_mfma_f32_16x16x32_bf16 v[26:29], v[162:165], v[212:215], v[26:29]
	v_mfma_f32_16x16x32_bf16 v[14:17], v[154:157], v[220:223], v[14:17]
	v_mfma_f32_16x16x32_bf16 v[10:13], v[162:165], v[220:223], v[10:13]
	s_setprio 0
	s_setprio 1
	v_mfma_f32_16x16x32_bf16 v[54:57], v[166:169], v[182:185], v[54:57]
	v_mfma_f32_16x16x32_bf16 v[50:53], v[174:177], v[182:185], v[50:53]
	v_mfma_f32_16x16x32_bf16 v[38:41], v[166:169], v[190:193], v[38:41]
	v_mfma_f32_16x16x32_bf16 v[34:37], v[174:177], v[190:193], v[34:37]
	v_mfma_f32_16x16x32_bf16 v[22:25], v[166:169], v[198:201], v[22:25]
	v_mfma_f32_16x16x32_bf16 v[18:21], v[174:177], v[198:201], v[18:21]
	v_mfma_f32_16x16x32_bf16 v[6:9], v[166:169], v[216:219], v[6:9]
	v_mfma_f32_16x16x32_bf16 v[2:5], v[174:177], v[216:219], v[2:5]
	v_mfma_f32_16x16x32_bf16 v[54:57], v[170:173], v[186:189], v[54:57]
	v_mfma_f32_16x16x32_bf16 v[50:53], v[178:181], v[186:189], v[50:53]
	v_mfma_f32_16x16x32_bf16 v[38:41], v[170:173], v[194:197], v[38:41]
	v_mfma_f32_16x16x32_bf16 v[34:37], v[178:181], v[194:197], v[34:37]
	v_mfma_f32_16x16x32_bf16 v[22:25], v[170:173], v[212:215], v[22:25]
	v_mfma_f32_16x16x32_bf16 v[18:21], v[178:181], v[212:215], v[18:21]
	v_mfma_f32_16x16x32_bf16 v[6:9], v[170:173], v[220:223], v[6:9]
	v_mfma_f32_16x16x32_bf16 v[2:5], v[178:181], v[220:223], v[2:5]
	s_setprio 0
	s_add_u32 s40, s40, 0x100
	s_addc_u32 s41, s41, 0
	s_add_u32 s49, s49, 0x100
	s_addc_u32 s62, s62, 0
	s_cmp_ge_u32 s63, s39
	s_mov_b32 s58, s63
	s_barrier
	s_cbranch_scc0 .LBB0_1153
	s_and_b64 vcc, exec, s[4:5]
	s_cbranch_vccz .LBB0_1156
	s_barrier

;     __device__ __forceinline__ bool next(int i, Unit& u) const { u.seg = 0; u.ks = -1; u.nt = ntk; u.koff = 0; return unit(i, u); }
;     __device__ __forceinline__ bool next(int i, Unit& u) const { const int t = i / 3; u.seg = i - 3 * t; u.ks = -1; u.nt = ntk; u.koff = 0; return unit(t, u); }
;     __device__ __forceinline__ bool next(int i, Unit& u) const { if (i > 0 || c < 80 || c >= 144) return false; const int k = c - 80; u.pm = k & 1; u.pn = k >> 1; u.seg = 0; u.ks = -1; u.nt = DM / BK; u.koff = 0; return true; }
; #define PG8_STAGE(bufoff, gbase, voff) do { _Pragma("unroll") for (int _i = 0; _i < 2; ++_i) \
;         __builtin_amdgcn_global_load_lds((const unsigned*)((const char*)(gbase) + (voff)[_i]), (LAS unsigned*)(lds + (bufoff) + ldsw + _i * 8192), 16, 0, 0); } while (0)
; #define PG8_LDA(dst, b, h) do { _Pragma("unroll") for (int m = 0; m < 4; ++m) _Pragma("unroll") for (int k = 0; k < 2; ++k) dst[m][k] = *(const LAS bf16x8*)(lds + PG8_SA(b, h) + aoff + m * 2048 + k * 1024); } while (0)
; template <class Epi, class Sched, bool I8 = false>
; __device__ __forceinline__ void gemm_phase(LAS unsigned char* lds, const Gemm g, const Sched& S, const Epi& E) {
;     ...
;         const bool has_next = S.next(ui + 1, nxt);
;         const char* nA = has_next ? g.A + (size_t)nxt.seg * g.segA + (size_t)nxt.pm * tstepA + nxt.koff : cA; const char* nB = has_next ? g.Bt + (size_t)nxt.seg * g.segB + (size_t)nxt.pn * tstepB + nxt.koff : cB;
;         const int nt = cur.nt;
;         for (int t = 0; t < nt; t += 2) {
;             const bool last = (t == nt - 2);
;             const char* a1 = cA + (size_t)(t + 1) * kstep;
;             const char* a2 = last ? nA : cA + (size_t)(t + 2) * kstep; const char* b2 = last ? nB : cB + (size_t)(t + 2) * kstep;
;             const char* a3 = a2 + kstep; const char* b3 = b2 + kstep;
;             if (PG8_SP2) {
;             PG8_LDB(B0, 0, 0); PG8_LDB(B1, 0, 1); PG8_SCHED; PG8_LDA(At, 0, 0); PG8_STAGE(PG8_SA(1, 1), a1 + hstepA, voffA);
;             PG8_WAIT_V(8); PG8_WAIT_L(0); PG8_BAR; PG8_MMA(0, 0, At, B0); PG8_MMA(0, 1, At, B1); PG8_BAR; PG8_SCHED;
;             PG8_LDA(At, 0, 1); PG8_STAGE(PG8_SB(0, 0), b2, voffB); PG8_STAGE(PG8_SB(0, 1), b2 + hstepB, voffB); PG8_STAGE(PG8_SA(0, 0), a2, voffA);
;             PG8_WAIT_V(8); PG8_WAIT_L(0); PG8_BAR; PG8_MMA(1, 0, At, B0); PG8_MMA(1, 1, At, B1); PG8_BAR; PG8_SCHED;
.LBB0_1336:
	s_add_u32 s40, s0, 0xfffc0080
	s_addc_u32 s41, s1, -1
	s_add_i32 s91, 0, 0x10000
	s_cmp_eq_u32 s90, 12
	s_cselect_b32 s43, s44, s41
	s_cselect_b32 s42, s45, s40
	v_add_u32_e32 v130, s91, v164
	s_cselect_b32 s41, s55, s83
	s_cselect_b32 s40, s57, s82
	s_add_i32 s96, 0, 0x14000
	ds_read_b128 v[114:117], v130
	ds_read_b128 v[118:121], v130 offset:1024
	ds_read_b128 v[126:129], v130 offset:2048
	ds_read_b128 v[136:139], v130 offset:3072
	v_add_u32_e32 v130, s96, v164
	ds_read_b128 v[166:169], v130
	ds_read_b128 v[170:173], v130 offset:1024
	ds_read_b128 v[174:177], v130 offset:2048
	ds_read_b128 v[178:181], v130 offset:3072
	v_lshl_add_u64 v[160:161], s[0:1], 0, v[156:157]
	s_add_i32 m0, s24, 0xc000
	ds_read_b128 v[182:185], v165
	ds_read_b128 v[186:189], v165 offset:1024
	ds_read_b128 v[190:193], v165 offset:2048
	ds_read_b128 v[194:197], v165 offset:3072
	ds_read_b128 v[198:201], v165 offset:4096
	ds_read_b128 v[212:215], v165 offset:5120
	ds_read_b128 v[216:219], v165 offset:6144
	ds_read_b128 v[220:223], v165 offset:7168
	global_load_lds_dwordx4 v[160:161], off
	v_lshl_add_u64 v[160:161], s[0:1], 0, v[158:159]
	s_add_i32 m0, s24, 0xe000
	s_nop 0
	global_load_lds_dwordx4 v[160:161], off
	s_waitcnt vmcnt(8)
	s_waitcnt lgkmcnt(0)
	s_barrier
	s_setprio 1
	s_waitcnt lgkmcnt(0)
	v_mfma_i32_16x16x64_i8 v[144:147], v[114:117], v[182:185], v[144:147]
	v_mfma_i32_16x16x64_i8 v[140:143], v[126:129], v[182:185], v[140:143]
	v_mfma_i32_16x16x64_i8 v[110:113], v[114:117], v[190:193], v[110:113]
	v_mfma_i32_16x16x64_i8 v[106:109], v[126:129], v[190:193], v[106:109]
	v_mfma_i32_16x16x64_i8 v[94:97], v[114:117], v[198:201], v[94:97]
	v_mfma_i32_16x16x64_i8 v[90:93], v[126:129], v[198:201], v[90:93]
	v_mfma_i32_16x16x64_i8 v[78:81], v[114:117], v[216:219], v[78:81]
	v_mfma_i32_16x16x64_i8 v[74:77], v[126:129], v[216:219], v[74:77]
	v_mfma_i32_16x16x64_i8 v[144:147], v[118:121], v[186:189], v[144:147]
	v_mfma_i32_16x16x64_i8 v[140:143], v[136:139], v[186:189], v[140:143]
	v_mfma_i32_16x16x64_i8 v[110:113], v[118:121], v[194:197], v[110:113]
	v_mfma_i32_16x16x64_i8 v[106:109], v[136:139], v[194:197], v[106:109]
	v_mfma_i32_16x16x64_i8 v[94:97], v[118:121], v[212:215], v[94:97]
	v_mfma_i32_16x16x64_i8 v[90:93], v[136:139], v[212:215], v[90:93]
	v_mfma_i32_16x16x64_i8 v[78:81], v[118:121], v[220:223], v[78:81]
	v_mfma_i32_16x16x64_i8 v[74:77], v[136:139], v[220:223], v[74:77]
	s_setprio 0
	s_setprio 1
	v_mfma_i32_16x16x64_i8 v[132:135], v[166:169], v[182:185], v[132:135]
	v_mfma_i32_16x16x64_i8 v[122:125], v[174:177], v[182:185], v[122:125]
	v_mfma_i32_16x16x64_i8 v[102:105], v[166:169], v[190:193], v[102:105]
	v_mfma_i32_16x16x64_i8 v[98:101], v[174:177], v[190:193], v[98:101]
	v_mfma_i32_16x16x64_i8 v[86:89], v[166:169], v[198:201], v[86:89]
	v_mfma_i32_16x16x64_i8 v[82:85], v[174:177], v[198:201], v[82:85]
	v_mfma_i32_16x16x64_i8 v[70:73], v[166:169], v[216:219], v[70:73]
	v_mfma_i32_16x16x64_i8 v[66:69], v[174:177], v[216:219], v[66:69]
	v_mfma_i32_16x16x64_i8 v[132:135], v[170:173], v[186:189], v[132:135]
	v_mfma_i32_16x16x64_i8 v[122:125], v[178:181], v[186:189], v[122:125]
	v_mfma_i32_16x16x64_i8 v[102:105], v[170:173], v[194:197], v[102:105]
	v_mfma_i32_16x16x64_i8 v[98:101], v[178:181], v[194:197], v[98:101]
	v_mfma_i32_16x16x64_i8 v[86:89], v[170:173], v[212:215], v[86:89]
	v_mfma_i32_16x16x64_i8 v[82:85], v[178:181], v[212:215], v[82:85]
	v_mfma_i32_16x16x64_i8 v[70:73], v[170:173], v[220:223], v[70:73]
	v_mfma_i32_16x16x64_i8 v[66:69], v[178:181], v[220:223], v[66:69]
	s_setprio 0
	s_barrier
	s_add_i32 s91, s91, s21
	v_lshl_add_u64 v[160:161], s[40:41], 0, v[152:153]
	s_mov_b32 m0, s91
	ds_read_b128 v[182:185], v165 offset:16384
	ds_read_b128 v[186:189], v165 offset:17408
	ds_read_b128 v[190:193], v165 offset:18432
	ds_read_b128 v[194:197], v165 offset:19456
	ds_read_b128 v[198:201], v165 offset:20480
	ds_read_b128 v[212:215], v165 offset:21504
	ds_read_b128 v[216:219], v165 offset:22528
	ds_read_b128 v[220:223], v165 offset:23552
	global_load_lds_dwordx4 v[160:161], off
	s_add_i32 m0, s91, 0x2000
	s_add_u32 s94, s40, 0x10000
	v_lshl_add_u64 v[202:203], s[40:41], 0, v[148:149]
	s_addc_u32 s95, s41, 0
	s_add_i32 s91, s96, s21
	global_load_lds_dwordx4 v[202:203], off
	v_lshl_add_u64 v[224:225], s[94:95], 0, v[152:153]
	s_mov_b32 m0, s91
	v_lshl_add_u64 v[226:227], s[42:43], 0, v[150:151]
	global_load_lds_dwordx4 v[224:225], off
	v_lshl_add_u64 v[224:225], s[94:95], 0, v[148:149]
	s_add_i32 m0, s91, 0x2000
	s_nop 0
	global_load_lds_dwordx4 v[224:225], off
	v_lshl_add_u64 v[224:225], s[42:43], 0, v[154:155]
	s_mov_b32 m0, s24
	s_nop 0
	global_load_lds_dwordx4 v[224:225], off
	s_mov_b32 m0, s25
	s_nop 0
	global_load_lds_dwordx4 v[226:227], off
	s_waitcnt vmcnt(8)
	s_waitcnt lgkmcnt(0)
	s_barrier
; #define PG8_STAGE(bufoff, gbase, voff) do { _Pragma("unroll") for (int _i = 0; _i < 2; ++_i) \
;         __builtin_amdgcn_global_load_lds((const unsigned*)((const char*)(gbase) + (voff)[_i]), (LAS unsigned*)(lds + (bufoff) + ldsw + _i * 8192), 16, 0, 0); } while (0)
; #define PG8_LDA(dst, b, h) do { _Pragma("unroll") for (int m = 0; m < 4; ++m) _Pragma("unroll") for (int k = 0; k < 2; ++k) dst[m][k] = *(const LAS bf16x8*)(lds + PG8_SA(b, h) + aoff + m * 2048 + k * 1024); } while (0)
; #define PG8_LDB(dst, b, h) do { _Pragma("unroll") for (int n = 0; n < 2; ++n) _Pragma("unroll") for (int k = 0; k < 2; ++k) dst[n][k] = *(const LAS bf16x8*)(lds + PG8_SB(b, h) + boff + n * 2048 + k * 1024); } while (0)
; #define PG8_MMA(ai, bj, At, Bt) do { __builtin_amdgcn_s_setprio(1); _Pragma("unroll") for (int m = 0; m < 4; ++m) _Pragma("unroll") for (int n = 0; n < 2; ++n) _Pragma("unroll") for (int k = 0; k < 2; ++k) \
;         acc[ai][bj][m][n] = mma16<I8>(Bt[n][k], At[m][k], acc[ai][bj][m][n]); __builtin_amdgcn_s_setprio(0); } while (0)
; #define PG8_WAIT_V(n) asm volatile("s_waitcnt vmcnt(" #n ")" ::: "memory")
; #define PG8_WAIT_L(n) asm volatile("s_waitcnt lgkmcnt(" #n ")" ::: "memory")
; #define PG8_BAR __builtin_amdgcn_s_barrier()
; #define PG8_SCHED __builtin_amdgcn_sched_barrier(0)
; template <class Epi, class Sched, bool I8 = false>
; __device__ __forceinline__ void gemm_phase(LAS unsigned char* lds, const Gemm g, const Sched& S, const Epi& E) {
;     ...
;             PG8_WAIT_V(8); PG8_WAIT_L(0); PG8_BAR; PG8_MMA(1, 0, At, B0); PG8_MMA(1, 1, At, B1); PG8_BAR; PG8_SCHED;
;             PG8_LDB(B0, 1, 0); PG8_LDB(B1, 1, 1); PG8_SCHED; PG8_LDA(At, 1, 0); PG8_STAGE(PG8_SA(0, 1), a2 + hstepA, voffA);
;             PG8_WAIT_V(8); PG8_WAIT_L(0); PG8_BAR; PG8_MMA(0, 0, At, B0); PG8_MMA(0, 1, At, B1); PG8_BAR; PG8_SCHED;
	s_setprio 1
	s_waitcnt lgkmcnt(0)
	v_mfma_i32_16x16x64_i8 v[62:65], v[114:117], v[182:185], v[62:65]
	v_mfma_i32_16x16x64_i8 v[58:61], v[126:129], v[182:185], v[58:61]
	v_mfma_i32_16x16x64_i8 v[46:49], v[114:117], v[190:193], v[46:49]
	v_mfma_i32_16x16x64_i8 v[42:45], v[126:129], v[190:193], v[42:45]
	v_mfma_i32_16x16x64_i8 v[30:33], v[114:117], v[198:201], v[30:33]
	v_mfma_i32_16x16x64_i8 v[26:29], v[126:129], v[198:201], v[26:29]
	v_mfma_i32_16x16x64_i8 v[14:17], v[114:117], v[216:219], v[14:17]
	v_mfma_i32_16x16x64_i8 v[10:13], v[126:129], v[216:219], v[10:13]
	v_mfma_i32_16x16x64_i8 v[62:65], v[118:121], v[186:189], v[62:65]
	v_mfma_i32_16x16x64_i8 v[58:61], v[136:139], v[186:189], v[58:61]
	v_mfma_i32_16x16x64_i8 v[46:49], v[118:121], v[194:197], v[46:49]
	v_mfma_i32_16x16x64_i8 v[42:45], v[136:139], v[194:197], v[42:45]
	v_mfma_i32_16x16x64_i8 v[30:33], v[118:121], v[212:215], v[30:33]
	v_mfma_i32_16x16x64_i8 v[26:29], v[136:139], v[212:215], v[26:29]
	v_mfma_i32_16x16x64_i8 v[14:17], v[118:121], v[220:223], v[14:17]
	v_mfma_i32_16x16x64_i8 v[10:13], v[136:139], v[220:223], v[10:13]
	s_setprio 0
	s_setprio 1
	v_mfma_i32_16x16x64_i8 v[54:57], v[166:169], v[182:185], v[54:57]
	v_mfma_i32_16x16x64_i8 v[50:53], v[174:177], v[182:185], v[50:53]
	v_mfma_i32_16x16x64_i8 v[38:41], v[166:169], v[190:193], v[38:41]
	v_mfma_i32_16x16x64_i8 v[34:37], v[174:177], v[190:193], v[34:37]
	v_mfma_i32_16x16x64_i8 v[22:25], v[166:169], v[198:201], v[22:25]
	v_mfma_i32_16x16x64_i8 v[18:21], v[174:177], v[198:201], v[18:21]
	v_mfma_i32_16x16x64_i8 v[6:9], v[166:169], v[216:219], v[6:9]
	v_mfma_i32_16x16x64_i8 v[2:5], v[174:177], v[216:219], v[2:5]
	v_mfma_i32_16x16x64_i8 v[54:57], v[170:173], v[186:189], v[54:57]
	v_mfma_i32_16x16x64_i8 v[50:53], v[178:181], v[186:189], v[50:53]
	v_mfma_i32_16x16x64_i8 v[38:41], v[170:173], v[194:197], v[38:41]
	v_mfma_i32_16x16x64_i8 v[34:37], v[178:181], v[194:197], v[34:37]
	v_mfma_i32_16x16x64_i8 v[22:25], v[170:173], v[212:215], v[22:25]
	v_mfma_i32_16x16x64_i8 v[18:21], v[178:181], v[212:215], v[18:21]
	v_mfma_i32_16x16x64_i8 v[6:9], v[170:173], v[220:223], v[6:9]
	v_mfma_i32_16x16x64_i8 v[2:5], v[178:181], v[220:223], v[2:5]
	s_setprio 0
	s_barrier
	s_add_i32 s91, 0, 0x18000
	v_add_u32_e32 v130, s91, v164
	s_add_i32 s94, 0, 0x1c000
	ds_read_b128 v[114:117], v130
	ds_read_b128 v[118:121], v130 offset:1024
	ds_read_b128 v[126:129], v130 offset:2048
	ds_read_b128 v[136:139], v130 offset:3072
	v_add_u32_e32 v130, s94, v164
	ds_read_b128 v[166:169], v130
	ds_read_b128 v[170:173], v130 offset:1024
	ds_read_b128 v[174:177], v130 offset:2048
	ds_read_b128 v[178:181], v130 offset:3072
	s_add_u32 s42, s42, 0x40000
	s_addc_u32 s43, s43, 0
	s_mov_b32 m0, s29
	v_lshl_add_u64 v[228:229], s[42:43], 0, v[154:155]
	ds_read_b128 v[182:185], v165 offset:32768
	ds_read_b128 v[186:189], v165 offset:33792
	ds_read_b128 v[190:193], v165 offset:34816
	ds_read_b128 v[194:197], v165 offset:35840
	ds_read_b128 v[198:201], v165 offset:36864
	ds_read_b128 v[212:215], v165 offset:37888
	ds_read_b128 v[216:219], v165 offset:38912
	ds_read_b128 v[220:223], v165 offset:39936
	global_load_lds_dwordx4 v[228:229], off
	v_lshl_add_u64 v[228:229], s[42:43], 0, v[150:151]
	s_mov_b32 m0, s30
	s_nop 0
	global_load_lds_dwordx4 v[228:229], off
	s_waitcnt vmcnt(8)
	s_waitcnt lgkmcnt(0)
	s_barrier
	s_setprio 1
	s_waitcnt lgkmcnt(0)
	v_mfma_i32_16x16x64_i8 v[144:147], v[114:117], v[182:185], v[144:147]
	v_mfma_i32_16x16x64_i8 v[140:143], v[126:129], v[182:185], v[140:143]
	v_mfma_i32_16x16x64_i8 v[110:113], v[114:117], v[190:193], v[110:113]
	v_mfma_i32_16x16x64_i8 v[106:109], v[126:129], v[190:193], v[106:109]
	v_mfma_i32_16x16x64_i8 v[94:97], v[114:117], v[198:201], v[94:97]
	v_mfma_i32_16x16x64_i8 v[90:93], v[126:129], v[198:201], v[90:93]
	v_mfma_i32_16x16x64_i8 v[78:81], v[114:117], v[216:219], v[78:81]
	v_mfma_i32_16x16x64_i8 v[74:77], v[126:129], v[216:219], v[74:77]
	v_mfma_i32_16x16x64_i8 v[144:147], v[118:121], v[186:189], v[144:147]
	v_mfma_i32_16x16x64_i8 v[140:143], v[136:139], v[186:189], v[140:143]
	v_mfma_i32_16x16x64_i8 v[110:113], v[118:121], v[194:197], v[110:113]
	v_mfma_i32_16x16x64_i8 v[106:109], v[136:139], v[194:197], v[106:109]
	v_mfma_i32_16x16x64_i8 v[94:97], v[118:121], v[212:215], v[94:97]
	v_mfma_i32_16x16x64_i8 v[90:93], v[136:139], v[212:215], v[90:93]
	v_mfma_i32_16x16x64_i8 v[78:81], v[118:121], v[220:223], v[78:81]
	v_mfma_i32_16x16x64_i8 v[74:77], v[136:139], v[220:223], v[74:77]
	s_setprio 0
	s_setprio 1
	v_mfma_i32_16x16x64_i8 v[132:135], v[166:169], v[182:185], v[132:135]
	v_mfma_i32_16x16x64_i8 v[122:125], v[174:177], v[182:185], v[122:125]
	v_mfma_i32_16x16x64_i8 v[102:105], v[166:169], v[190:193], v[102:105]
	v_mfma_i32_16x16x64_i8 v[98:101], v[174:177], v[190:193], v[98:101]
	v_mfma_i32_16x16x64_i8 v[86:89], v[166:169], v[198:201], v[86:89]
	v_mfma_i32_16x16x64_i8 v[82:85], v[174:177], v[198:201], v[82:85]
	v_mfma_i32_16x16x64_i8 v[70:73], v[166:169], v[216:219], v[70:73]
	v_mfma_i32_16x16x64_i8 v[66:69], v[174:177], v[216:219], v[66:69]
	v_mfma_i32_16x16x64_i8 v[132:135], v[170:173], v[186:189], v[132:135]
	v_mfma_i32_16x16x64_i8 v[122:125], v[178:181], v[186:189], v[122:125]
	v_mfma_i32_16x16x64_i8 v[102:105], v[170:173], v[194:197], v[102:105]
	v_mfma_i32_16x16x64_i8 v[98:101], v[178:181], v[194:197], v[98:101]
	v_mfma_i32_16x16x64_i8 v[86:89], v[170:173], v[212:215], v[86:89]
	v_mfma_i32_16x16x64_i8 v[82:85], v[178:181], v[212:215], v[82:85]
	v_mfma_i32_16x16x64_i8 v[70:73], v[170:173], v[220:223], v[70:73]
	v_mfma_i32_16x16x64_i8 v[66:69], v[178:181], v[220:223], v[66:69]
	s_setprio 0
	s_barrier
; #define PG8_STAGE(bufoff, gbase, voff) do { _Pragma("unroll") for (int _i = 0; _i < 2; ++_i) \
;         __builtin_amdgcn_global_load_lds((const unsigned*)((const char*)(gbase) + (voff)[_i]), (LAS unsigned*)(lds + (bufoff) + ldsw + _i * 8192), 16, 0, 0); } while (0)
; #define PG8_LDA(dst, b, h) do { _Pragma("unroll") for (int m = 0; m < 4; ++m) _Pragma("unroll") for (int k = 0; k < 2; ++k) dst[m][k] = *(const LAS bf16x8*)(lds + PG8_SA(b, h) + aoff + m * 2048 + k * 1024); } while (0)
; #define PG8_MMA(ai, bj, At, Bt) do { __builtin_amdgcn_s_setprio(1); _Pragma("unroll") for (int m = 0; m < 4; ++m) _Pragma("unroll") for (int n = 0; n < 2; ++n) _Pragma("unroll") for (int k = 0; k < 2; ++k) \
;         acc[ai][bj][m][n] = mma16<I8>(Bt[n][k], At[m][k], acc[ai][bj][m][n]); __builtin_amdgcn_s_setprio(0); } while (0)
; #define PG8_WAIT_V(n) asm volatile("s_waitcnt vmcnt(" #n ")" ::: "memory")
; #define PG8_WAIT_L(n) asm volatile("s_waitcnt lgkmcnt(" #n ")" ::: "memory")
; #define PG8_BAR __builtin_amdgcn_s_barrier()
; #define PG8_SCHED __builtin_amdgcn_sched_barrier(0)
; template <class Epi, class Sched, bool I8 = false>
; __device__ __forceinline__ void gemm_phase(LAS unsigned char* lds, const Gemm g, const Sched& S, const Epi& E) {
;     ...
;         for (int t = 0; t < nt; t += 2) {
;             const bool last = (t == nt - 2);
;     ...
;             PG8_LDA(At, 1, 1); PG8_STAGE(PG8_SB(1, 0), b3, voffB); PG8_STAGE(PG8_SB(1, 1), b3 + hstepB, voffB); PG8_STAGE(PG8_SA(1, 0), a3, voffA);
;             PG8_WAIT_V(8); PG8_WAIT_L(0); PG8_BAR; PG8_MMA(1, 0, At, B0); PG8_MMA(1, 1, At, B1); PG8_BAR; PG8_SCHED;
	s_add_i32 s42, s91, s21
	v_lshl_add_u64 v[160:161], v[160:161], 0, s[12:13]
	s_mov_b32 m0, s42
	ds_read_b128 v[182:185], v165 offset:49152
	ds_read_b128 v[186:189], v165 offset:50176
	ds_read_b128 v[190:193], v165 offset:51200
	ds_read_b128 v[194:197], v165 offset:52224
	ds_read_b128 v[198:201], v165 offset:53248
	ds_read_b128 v[212:215], v165 offset:54272
	ds_read_b128 v[216:219], v165 offset:55296
	ds_read_b128 v[220:223], v165 offset:56320
	global_load_lds_dwordx4 v[160:161], off
	s_add_i32 m0, s42, 0x2000
	s_add_u32 s40, s40, 0x10080
	v_lshl_add_u64 v[160:161], v[202:203], 0, s[12:13]
	s_addc_u32 s41, s41, 0
	s_add_i32 s42, s94, s21
	global_load_lds_dwordx4 v[160:161], off
	v_lshl_add_u64 v[160:161], s[40:41], 0, v[152:153]
	s_mov_b32 m0, s42
	s_nop 0
	global_load_lds_dwordx4 v[160:161], off
	v_lshl_add_u64 v[160:161], s[40:41], 0, v[148:149]
	s_add_i32 m0, s42, 0x2000
	s_nop 0
	global_load_lds_dwordx4 v[160:161], off
	v_lshl_add_u64 v[160:161], v[224:225], 0, s[12:13]
	s_mov_b32 m0, s49
	s_nop 0
	global_load_lds_dwordx4 v[160:161], off
	v_lshl_add_u64 v[160:161], v[226:227], 0, s[12:13]
	s_mov_b32 m0, s80
	s_nop 0
	global_load_lds_dwordx4 v[160:161], off
	s_waitcnt vmcnt(8)
	s_waitcnt lgkmcnt(0)
	s_barrier
	s_setprio 1
	s_waitcnt lgkmcnt(0)
	v_mfma_i32_16x16x64_i8 v[62:65], v[114:117], v[182:185], v[62:65]
	v_mfma_i32_16x16x64_i8 v[58:61], v[126:129], v[182:185], v[58:61]
	v_mfma_i32_16x16x64_i8 v[46:49], v[114:117], v[190:193], v[46:49]
	v_mfma_i32_16x16x64_i8 v[42:45], v[126:129], v[190:193], v[42:45]
	v_mfma_i32_16x16x64_i8 v[30:33], v[114:117], v[198:201], v[30:33]
	v_mfma_i32_16x16x64_i8 v[26:29], v[126:129], v[198:201], v[26:29]
	v_mfma_i32_16x16x64_i8 v[14:17], v[114:117], v[216:219], v[14:17]
	v_mfma_i32_16x16x64_i8 v[10:13], v[126:129], v[216:219], v[10:13]
	v_mfma_i32_16x16x64_i8 v[62:65], v[118:121], v[186:189], v[62:65]
	v_mfma_i32_16x16x64_i8 v[58:61], v[136:139], v[186:189], v[58:61]
	v_mfma_i32_16x16x64_i8 v[46:49], v[118:121], v[194:197], v[46:49]
	v_mfma_i32_16x16x64_i8 v[42:45], v[136:139], v[194:197], v[42:45]
	v_mfma_i32_16x16x64_i8 v[30:33], v[118:121], v[212:215], v[30:33]
	v_mfma_i32_16x16x64_i8 v[26:29], v[136:139], v[212:215], v[26:29]
	v_mfma_i32_16x16x64_i8 v[14:17], v[118:121], v[220:223], v[14:17]
	v_mfma_i32_16x16x64_i8 v[10:13], v[136:139], v[220:223], v[10:13]
	s_setprio 0
	s_setprio 1
	v_mfma_i32_16x16x64_i8 v[54:57], v[166:169], v[182:185], v[54:57]
	v_mfma_i32_16x16x64_i8 v[50:53], v[174:177], v[182:185], v[50:53]
	v_mfma_i32_16x16x64_i8 v[38:41], v[166:169], v[190:193], v[38:41]
	v_mfma_i32_16x16x64_i8 v[34:37], v[174:177], v[190:193], v[34:37]
	v_mfma_i32_16x16x64_i8 v[22:25], v[166:169], v[198:201], v[22:25]
	v_mfma_i32_16x16x64_i8 v[18:21], v[174:177], v[198:201], v[18:21]
	v_mfma_i32_16x16x64_i8 v[6:9], v[166:169], v[216:219], v[6:9]
	v_mfma_i32_16x16x64_i8 v[2:5], v[174:177], v[216:219], v[2:5]
	v_mfma_i32_16x16x64_i8 v[54:57], v[170:173], v[186:189], v[54:57]
	v_mfma_i32_16x16x64_i8 v[50:53], v[178:181], v[186:189], v[50:53]
	v_mfma_i32_16x16x64_i8 v[38:41], v[170:173], v[194:197], v[38:41]
	v_mfma_i32_16x16x64_i8 v[34:37], v[178:181], v[194:197], v[34:37]
	v_mfma_i32_16x16x64_i8 v[22:25], v[170:173], v[212:215], v[22:25]
	v_mfma_i32_16x16x64_i8 v[18:21], v[178:181], v[212:215], v[18:21]
	v_mfma_i32_16x16x64_i8 v[6:9], v[170:173], v[220:223], v[6:9]
	v_mfma_i32_16x16x64_i8 v[2:5], v[178:181], v[220:223], v[2:5]
	s_setprio 0
	s_add_i32 s90, s90, 2
	s_add_u32 s0, s0, 0x100
	s_addc_u32 s1, s1, 0
	s_add_u32 s82, s82, 0x100
	s_addc_u32 s83, s83, 0
	s_cmp_gt_u32 s90, 13
	s_barrier
	s_cbranch_scc0 .LBB0_1336
	s_and_b64 vcc, exec, s[6:7]
	s_cbranch_vccz .LBB0_1339
	s_barrier

;     __device__ __forceinline__ bool next(int i, Unit& u) const { u.seg = 0; u.ks = -1; u.nt = ntk; u.koff = 0; return unit(i, u); }
;     __device__ __forceinline__ bool next(int i, Unit& u) const { const int t = i / 3; u.seg = i - 3 * t; u.ks = -1; u.nt = ntk; u.koff = 0; return unit(t, u); }
;     __device__ __forceinline__ bool next(int i, Unit& u) const { if (i > 0 || c < 80 || c >= 144) return false; const int k = c - 80; u.pm = k & 1; u.pn = k >> 1; u.seg = 0; u.ks = -1; u.nt = DM / BK; u.koff = 0; return true; }
; #define PG8_STAGE(bufoff, gbase, voff) do { _Pragma("unroll") for (int _i = 0; _i < 2; ++_i) \
;         __builtin_amdgcn_global_load_lds((const unsigned*)((const char*)(gbase) + (voff)[_i]), (LAS unsigned*)(lds + (bufoff) + ldsw + _i * 8192), 16, 0, 0); } while (0)
; #define PG8_LDA(dst, b, h) do { _Pragma("unroll") for (int m = 0; m < 4; ++m) _Pragma("unroll") for (int k = 0; k < 2; ++k) dst[m][k] = *(const LAS bf16x8*)(lds + PG8_SA(b, h) + aoff + m * 2048 + k * 1024); } while (0)
; template <class Epi, class Sched, bool I8 = false>
; __device__ __forceinline__ void gemm_phase(LAS unsigned char* lds, const Gemm g, const Sched& S, const Epi& E) {
;     ...
;         const bool has_next = S.next(ui + 1, nxt);
;         const char* nA = has_next ? g.A + (size_t)nxt.seg * g.segA + (size_t)nxt.pm * tstepA + nxt.koff : cA; const char* nB = has_next ? g.Bt + (size_t)nxt.seg * g.segB + (size_t)nxt.pn * tstepB + nxt.koff : cB;
;         const int nt = cur.nt;
;         for (int t = 0; t < nt; t += 2) {
;             const bool last = (t == nt - 2);
;             const char* a1 = cA + (size_t)(t + 1) * kstep;
;             const char* a2 = last ? nA : cA + (size_t)(t + 2) * kstep; const char* b2 = last ? nB : cB + (size_t)(t + 2) * kstep;
;             const char* a3 = a2 + kstep; const char* b3 = b2 + kstep;
;             if (PG8_SP2) {
;             PG8_LDB(B0, 0, 0); PG8_LDB(B1, 0, 1); PG8_SCHED; PG8_LDA(At, 0, 0); PG8_STAGE(PG8_SA(1, 1), a1 + hstepA, voffA);
;             PG8_WAIT_V(8); PG8_WAIT_L(0); PG8_BAR; PG8_MMA(0, 0, At, B0); PG8_MMA(0, 1, At, B1); PG8_BAR; PG8_SCHED;
;             PG8_LDA(At, 0, 1); PG8_STAGE(PG8_SB(0, 0), b2, voffB); PG8_STAGE(PG8_SB(0, 1), b2 + hstepB, voffB); PG8_STAGE(PG8_SA(0, 0), a2, voffA);
;             PG8_WAIT_V(8); PG8_WAIT_L(0); PG8_BAR; PG8_MMA(1, 0, At, B0); PG8_MMA(1, 1, At, B1); PG8_BAR; PG8_SCHED;
.LBB0_1574:
	s_add_i32 s80, s42, 2
	s_add_u32 s40, s0, 0xfff00080
	s_addc_u32 s41, s1, -1
	s_add_i32 s82, 0, 0x10000
	s_cmp_eq_u32 s56, s42
	s_cselect_b32 s43, s23, s41
	s_cselect_b32 s42, s44, s40
	s_cselect_b32 s41, s45, s63
	s_cselect_b32 s40, s46, s57
	s_add_i32 s91, 0, 0x14000
	v_add_u32_e32 v62, s82, v175
	v_add_u32_e32 v78, s91, v175
	ds_read_b128 v[50:53], v62
	ds_read_b128 v[54:57], v62 offset:1024
	ds_read_b128 v[58:61], v62 offset:2048
	ds_read_b128 v[62:65], v62 offset:3072
	ds_read_b128 v[66:69], v78
	ds_read_b128 v[70:73], v78 offset:1024
	ds_read_b128 v[74:77], v78 offset:2048
	ds_read_b128 v[78:81], v78 offset:3072
	v_lshl_add_u64 v[202:203], s[0:1], 0, v[178:179]
	s_add_i32 m0, s34, 0xc000
	ds_read_b128 v[182:185], v177
	ds_read_b128 v[186:189], v177 offset:1024
	ds_read_b128 v[190:193], v177 offset:2048
	ds_read_b128 v[194:197], v177 offset:3072
	ds_read_b128 v[198:201], v177 offset:4096
	ds_read_b128 v[212:215], v177 offset:5120
	ds_read_b128 v[216:219], v177 offset:6144
	ds_read_b128 v[220:223], v177 offset:7168
	global_load_lds_dwordx4 v[202:203], off
	v_lshl_add_u64 v[202:203], s[0:1], 0, v[180:181]
	s_add_i32 m0, s34, 0xe000
	s_nop 0
	global_load_lds_dwordx4 v[202:203], off
	s_waitcnt vmcnt(8)
	s_waitcnt lgkmcnt(0)
	s_barrier
	s_setprio 1
	s_waitcnt lgkmcnt(0)
	v_mfma_i32_16x16x64_i8 v[160:163], v[50:53], v[182:185], v[160:163]
	v_mfma_i32_16x16x64_i8 v[156:159], v[58:61], v[182:185], v[156:159]
	v_mfma_i32_16x16x64_i8 v[144:147], v[50:53], v[190:193], v[144:147]
	v_mfma_i32_16x16x64_i8 v[140:143], v[58:61], v[190:193], v[140:143]
	v_mfma_i32_16x16x64_i8 v[126:129], v[50:53], v[198:201], v[126:129]
	v_mfma_i32_16x16x64_i8 v[122:125], v[58:61], v[198:201], v[122:125]
	v_mfma_i32_16x16x64_i8 v[110:113], v[50:53], v[216:219], v[110:113]
	v_mfma_i32_16x16x64_i8 v[106:109], v[58:61], v[216:219], v[106:109]
	v_mfma_i32_16x16x64_i8 v[160:163], v[54:57], v[186:189], v[160:163]
	v_mfma_i32_16x16x64_i8 v[156:159], v[62:65], v[186:189], v[156:159]
	v_mfma_i32_16x16x64_i8 v[144:147], v[54:57], v[194:197], v[144:147]
	v_mfma_i32_16x16x64_i8 v[140:143], v[62:65], v[194:197], v[140:143]
	v_mfma_i32_16x16x64_i8 v[126:129], v[54:57], v[212:215], v[126:129]
	v_mfma_i32_16x16x64_i8 v[122:125], v[62:65], v[212:215], v[122:125]
	v_mfma_i32_16x16x64_i8 v[110:113], v[54:57], v[220:223], v[110:113]
	v_mfma_i32_16x16x64_i8 v[106:109], v[62:65], v[220:223], v[106:109]
	s_setprio 0
	s_setprio 1
	v_mfma_i32_16x16x64_i8 v[152:155], v[66:69], v[182:185], v[152:155]
	v_mfma_i32_16x16x64_i8 v[148:151], v[74:77], v[182:185], v[148:151]
	v_mfma_i32_16x16x64_i8 v[136:139], v[66:69], v[190:193], v[136:139]
	v_mfma_i32_16x16x64_i8 v[132:135], v[74:77], v[190:193], v[132:135]
	v_mfma_i32_16x16x64_i8 v[118:121], v[66:69], v[198:201], v[118:121]
	v_mfma_i32_16x16x64_i8 v[114:117], v[74:77], v[198:201], v[114:117]
	v_mfma_i32_16x16x64_i8 v[102:105], v[66:69], v[216:219], v[102:105]
	v_mfma_i32_16x16x64_i8 v[98:101], v[74:77], v[216:219], v[98:101]
	v_mfma_i32_16x16x64_i8 v[152:155], v[70:73], v[186:189], v[152:155]
	v_mfma_i32_16x16x64_i8 v[148:151], v[78:81], v[186:189], v[148:151]
	v_mfma_i32_16x16x64_i8 v[136:139], v[70:73], v[194:197], v[136:139]
	v_mfma_i32_16x16x64_i8 v[132:135], v[78:81], v[194:197], v[132:135]
	v_mfma_i32_16x16x64_i8 v[118:121], v[70:73], v[212:215], v[118:121]
	v_mfma_i32_16x16x64_i8 v[114:117], v[78:81], v[212:215], v[114:117]
	v_mfma_i32_16x16x64_i8 v[102:105], v[70:73], v[220:223], v[102:105]
	v_mfma_i32_16x16x64_i8 v[98:101], v[78:81], v[220:223], v[98:101]
	s_setprio 0
	s_barrier
	s_add_i32 s82, s82, s85
	v_lshl_add_u64 v[202:203], s[40:41], 0, v[168:169]
	s_mov_b32 m0, s82
	ds_read_b128 v[182:185], v177 offset:16384
	ds_read_b128 v[186:189], v177 offset:17408
	ds_read_b128 v[190:193], v177 offset:18432
	ds_read_b128 v[194:197], v177 offset:19456
	ds_read_b128 v[198:201], v177 offset:20480
	ds_read_b128 v[212:215], v177 offset:21504
	ds_read_b128 v[216:219], v177 offset:22528
	ds_read_b128 v[220:223], v177 offset:23552
	global_load_lds_dwordx4 v[202:203], off
	s_add_i32 m0, s82, 0x2000
	s_add_u32 s82, s40, 0x40000
	v_lshl_add_u64 v[228:229], s[40:41], 0, v[164:165]
	s_addc_u32 s83, s41, 0
	s_add_i32 s91, s91, s85
	global_load_lds_dwordx4 v[228:229], off
	v_lshl_add_u64 v[224:225], s[82:83], 0, v[168:169]
	s_mov_b32 m0, s91
	v_lshl_add_u64 v[230:231], s[42:43], 0, v[170:171]
	global_load_lds_dwordx4 v[224:225], off
	v_lshl_add_u64 v[224:225], s[82:83], 0, v[164:165]
	s_add_i32 m0, s91, 0x2000
	v_lshl_add_u64 v[232:233], s[42:43], 0, v[166:167]
	global_load_lds_dwordx4 v[224:225], off
	s_mov_b32 m0, s34
	s_nop 0
	global_load_lds_dwordx4 v[230:231], off
	s_mov_b32 m0, s35
	s_nop 0
	global_load_lds_dwordx4 v[232:233], off
	s_waitcnt vmcnt(8)
	s_waitcnt lgkmcnt(0)
	s_barrier
; #define PG8_STAGE(bufoff, gbase, voff) do { _Pragma("unroll") for (int _i = 0; _i < 2; ++_i) \
;         __builtin_amdgcn_global_load_lds((const unsigned*)((const char*)(gbase) + (voff)[_i]), (LAS unsigned*)(lds + (bufoff) + ldsw + _i * 8192), 16, 0, 0); } while (0)
; #define PG8_LDA(dst, b, h) do { _Pragma("unroll") for (int m = 0; m < 4; ++m) _Pragma("unroll") for (int k = 0; k < 2; ++k) dst[m][k] = *(const LAS bf16x8*)(lds + PG8_SA(b, h) + aoff + m * 2048 + k * 1024); } while (0)
; #define PG8_LDB(dst, b, h) do { _Pragma("unroll") for (int n = 0; n < 2; ++n) _Pragma("unroll") for (int k = 0; k < 2; ++k) dst[n][k] = *(const LAS bf16x8*)(lds + PG8_SB(b, h) + boff + n * 2048 + k * 1024); } while (0)
; #define PG8_MMA(ai, bj, At, Bt) do { __builtin_amdgcn_s_setprio(1); _Pragma("unroll") for (int m = 0; m < 4; ++m) _Pragma("unroll") for (int n = 0; n < 2; ++n) _Pragma("unroll") for (int k = 0; k < 2; ++k) \
;         acc[ai][bj][m][n] = mma16<I8>(Bt[n][k], At[m][k], acc[ai][bj][m][n]); __builtin_amdgcn_s_setprio(0); } while (0)
; #define PG8_WAIT_V(n) asm volatile("s_waitcnt vmcnt(" #n ")" ::: "memory")
; #define PG8_WAIT_L(n) asm volatile("s_waitcnt lgkmcnt(" #n ")" ::: "memory")
; #define PG8_BAR __builtin_amdgcn_s_barrier()
; #define PG8_SCHED __builtin_amdgcn_sched_barrier(0)
; template <class Epi, class Sched, bool I8 = false>
; __device__ __forceinline__ void gemm_phase(LAS unsigned char* lds, const Gemm g, const Sched& S, const Epi& E) {
;     ...
;             PG8_WAIT_V(8); PG8_WAIT_L(0); PG8_BAR; PG8_MMA(1, 0, At, B0); PG8_MMA(1, 1, At, B1); PG8_BAR; PG8_SCHED;
;             PG8_LDB(B0, 1, 0); PG8_LDB(B1, 1, 1); PG8_SCHED; PG8_LDA(At, 1, 0); PG8_STAGE(PG8_SA(0, 1), a2 + hstepA, voffA);
;             PG8_WAIT_V(8); PG8_WAIT_L(0); PG8_BAR; PG8_MMA(0, 0, At, B0); PG8_MMA(0, 1, At, B1); PG8_BAR; PG8_SCHED;
	s_setprio 1
	s_waitcnt lgkmcnt(0)
	v_mfma_i32_16x16x64_i8 v[94:97], v[50:53], v[182:185], v[94:97]
	v_mfma_i32_16x16x64_i8 v[90:93], v[58:61], v[182:185], v[90:93]
	v_mfma_i32_16x16x64_i8 v[46:49], v[50:53], v[190:193], v[46:49]
	v_mfma_i32_16x16x64_i8 v[42:45], v[58:61], v[190:193], v[42:45]
	v_mfma_i32_16x16x64_i8 v[30:33], v[50:53], v[198:201], v[30:33]
	v_mfma_i32_16x16x64_i8 v[26:29], v[58:61], v[198:201], v[26:29]
	v_mfma_i32_16x16x64_i8 v[14:17], v[50:53], v[216:219], v[14:17]
	v_mfma_i32_16x16x64_i8 v[10:13], v[58:61], v[216:219], v[10:13]
	v_mfma_i32_16x16x64_i8 v[94:97], v[54:57], v[186:189], v[94:97]
	v_mfma_i32_16x16x64_i8 v[90:93], v[62:65], v[186:189], v[90:93]
	v_mfma_i32_16x16x64_i8 v[46:49], v[54:57], v[194:197], v[46:49]
	v_mfma_i32_16x16x64_i8 v[42:45], v[62:65], v[194:197], v[42:45]
	v_mfma_i32_16x16x64_i8 v[30:33], v[54:57], v[212:215], v[30:33]
	v_mfma_i32_16x16x64_i8 v[26:29], v[62:65], v[212:215], v[26:29]
	v_mfma_i32_16x16x64_i8 v[14:17], v[54:57], v[220:223], v[14:17]
	v_mfma_i32_16x16x64_i8 v[10:13], v[62:65], v[220:223], v[10:13]
	s_setprio 0
	s_setprio 1
	v_mfma_i32_16x16x64_i8 v[38:41], v[66:69], v[190:193], v[38:41]
	v_mfma_i32_16x16x64_i8 v[34:37], v[74:77], v[190:193], v[34:37]
	v_mfma_i32_16x16x64_i8 v[22:25], v[66:69], v[198:201], v[22:25]
	v_mfma_i32_16x16x64_i8 v[18:21], v[74:77], v[198:201], v[18:21]
	v_mfma_i32_16x16x64_i8 v[6:9], v[66:69], v[216:219], v[6:9]
	v_mfma_i32_16x16x64_i8 v[2:5], v[74:77], v[216:219], v[2:5]
	v_mfma_i32_16x16x64_i8 v[50:53], v[66:69], v[182:185], v[86:89]
	v_mfma_i32_16x16x64_i8 v[54:57], v[74:77], v[182:185], v[82:85]
	v_mfma_i32_16x16x64_i8 v[38:41], v[70:73], v[194:197], v[38:41]
	v_mfma_i32_16x16x64_i8 v[34:37], v[78:81], v[194:197], v[34:37]
	v_mfma_i32_16x16x64_i8 v[22:25], v[70:73], v[212:215], v[22:25]
	v_mfma_i32_16x16x64_i8 v[18:21], v[78:81], v[212:215], v[18:21]
	v_mfma_i32_16x16x64_i8 v[6:9], v[70:73], v[220:223], v[6:9]
	v_mfma_i32_16x16x64_i8 v[2:5], v[78:81], v[220:223], v[2:5]
	v_mfma_i32_16x16x64_i8 v[50:53], v[70:73], v[186:189], v[50:53]
	v_mfma_i32_16x16x64_i8 v[54:57], v[78:81], v[186:189], v[54:57]
	s_setprio 0
	s_barrier
	s_add_i32 s82, 0, 0x18000
	s_add_i32 s83, 0, 0x1c000
	v_add_u32_e32 v70, s82, v175
	v_add_u32_e32 v82, s83, v175
	ds_read_b128 v[58:61], v70
	ds_read_b128 v[62:65], v70 offset:1024
	ds_read_b128 v[66:69], v70 offset:2048
	ds_read_b128 v[70:73], v70 offset:3072
	ds_read_b128 v[74:77], v82
	ds_read_b128 v[78:81], v82 offset:1024
	ds_read_b128 v[182:185], v82 offset:2048
	ds_read_b128 v[186:189], v82 offset:3072
	s_add_u32 s42, s42, 0x100000
	s_addc_u32 s43, s43, 0
	s_mov_b32 m0, s30
	v_lshl_add_u64 v[224:225], s[42:43], 0, v[170:171]
	ds_read_b128 v[82:85], v177 offset:32768
	ds_read_b128 v[86:89], v177 offset:33792
	ds_read_b128 v[190:193], v177 offset:34816
	ds_read_b128 v[194:197], v177 offset:35840
	ds_read_b128 v[198:201], v177 offset:36864
	ds_read_b128 v[212:215], v177 offset:37888
	ds_read_b128 v[216:219], v177 offset:38912
	ds_read_b128 v[220:223], v177 offset:39936
	global_load_lds_dwordx4 v[224:225], off
	v_lshl_add_u64 v[224:225], s[42:43], 0, v[166:167]
	s_mov_b32 m0, s31
	s_nop 0
	global_load_lds_dwordx4 v[224:225], off
	s_waitcnt vmcnt(8)
	s_waitcnt lgkmcnt(0)
	s_barrier
	s_setprio 1
	s_waitcnt lgkmcnt(0)
	v_mfma_i32_16x16x64_i8 v[160:163], v[58:61], v[82:85], v[160:163]
	v_mfma_i32_16x16x64_i8 v[156:159], v[66:69], v[82:85], v[156:159]
	v_mfma_i32_16x16x64_i8 v[144:147], v[58:61], v[190:193], v[144:147]
	v_mfma_i32_16x16x64_i8 v[140:143], v[66:69], v[190:193], v[140:143]
	v_mfma_i32_16x16x64_i8 v[126:129], v[58:61], v[198:201], v[126:129]
	v_mfma_i32_16x16x64_i8 v[122:125], v[66:69], v[198:201], v[122:125]
	v_mfma_i32_16x16x64_i8 v[110:113], v[58:61], v[216:219], v[110:113]
	v_mfma_i32_16x16x64_i8 v[106:109], v[66:69], v[216:219], v[106:109]
	v_mfma_i32_16x16x64_i8 v[160:163], v[62:65], v[86:89], v[160:163]
	v_mfma_i32_16x16x64_i8 v[156:159], v[70:73], v[86:89], v[156:159]
	v_mfma_i32_16x16x64_i8 v[144:147], v[62:65], v[194:197], v[144:147]
	v_mfma_i32_16x16x64_i8 v[140:143], v[70:73], v[194:197], v[140:143]
	v_mfma_i32_16x16x64_i8 v[126:129], v[62:65], v[212:215], v[126:129]
	v_mfma_i32_16x16x64_i8 v[122:125], v[70:73], v[212:215], v[122:125]
	v_mfma_i32_16x16x64_i8 v[110:113], v[62:65], v[220:223], v[110:113]
	v_mfma_i32_16x16x64_i8 v[106:109], v[70:73], v[220:223], v[106:109]
	s_setprio 0
	s_setprio 1
	v_mfma_i32_16x16x64_i8 v[152:155], v[74:77], v[82:85], v[152:155]
	v_mfma_i32_16x16x64_i8 v[82:85], v[182:185], v[82:85], v[148:151]
	v_mfma_i32_16x16x64_i8 v[148:151], v[186:189], v[86:89], v[82:85]
	v_mfma_i32_16x16x64_i8 v[82:85], v[74:77], v[190:193], v[136:139]
	v_mfma_i32_16x16x64_i8 v[136:139], v[78:81], v[194:197], v[82:85]
	v_mfma_i32_16x16x64_i8 v[82:85], v[182:185], v[190:193], v[132:135]
	v_mfma_i32_16x16x64_i8 v[132:135], v[186:189], v[194:197], v[82:85]
	v_mfma_i32_16x16x64_i8 v[82:85], v[74:77], v[198:201], v[118:121]
	v_mfma_i32_16x16x64_i8 v[118:121], v[78:81], v[212:215], v[82:85]
	v_mfma_i32_16x16x64_i8 v[82:85], v[182:185], v[198:201], v[114:117]
	v_mfma_i32_16x16x64_i8 v[114:117], v[186:189], v[212:215], v[82:85]
	v_mfma_i32_16x16x64_i8 v[82:85], v[74:77], v[216:219], v[102:105]
	v_mfma_i32_16x16x64_i8 v[102:105], v[78:81], v[220:223], v[82:85]
	v_mfma_i32_16x16x64_i8 v[82:85], v[182:185], v[216:219], v[98:101]
	v_mfma_i32_16x16x64_i8 v[152:155], v[78:81], v[86:89], v[152:155]
	v_mfma_i32_16x16x64_i8 v[98:101], v[186:189], v[220:223], v[82:85]
	s_setprio 0
	s_barrier
; #define PG8_STAGE(bufoff, gbase, voff) do { _Pragma("unroll") for (int _i = 0; _i < 2; ++_i) \
;         __builtin_amdgcn_global_load_lds((const unsigned*)((const char*)(gbase) + (voff)[_i]), (LAS unsigned*)(lds + (bufoff) + ldsw + _i * 8192), 16, 0, 0); } while (0)
; #define PG8_LDA(dst, b, h) do { _Pragma("unroll") for (int m = 0; m < 4; ++m) _Pragma("unroll") for (int k = 0; k < 2; ++k) dst[m][k] = *(const LAS bf16x8*)(lds + PG8_SA(b, h) + aoff + m * 2048 + k * 1024); } while (0)
; #define PG8_MMA(ai, bj, At, Bt) do { __builtin_amdgcn_s_setprio(1); _Pragma("unroll") for (int m = 0; m < 4; ++m) _Pragma("unroll") for (int n = 0; n < 2; ++n) _Pragma("unroll") for (int k = 0; k < 2; ++k) \
;         acc[ai][bj][m][n] = mma16<I8>(Bt[n][k], At[m][k], acc[ai][bj][m][n]); __builtin_amdgcn_s_setprio(0); } while (0)
; #define PG8_WAIT_V(n) asm volatile("s_waitcnt vmcnt(" #n ")" ::: "memory")
; #define PG8_WAIT_L(n) asm volatile("s_waitcnt lgkmcnt(" #n ")" ::: "memory")
; #define PG8_BAR __builtin_amdgcn_s_barrier()
; #define PG8_SCHED __builtin_amdgcn_sched_barrier(0)
; template <class Epi, class Sched, bool I8 = false>
; __device__ __forceinline__ void gemm_phase(LAS unsigned char* lds, const Gemm g, const Sched& S, const Epi& E) {
;     ...
;         for (int t = 0; t < nt; t += 2) {
;             const bool last = (t == nt - 2);
;     ...
;             PG8_LDA(At, 1, 1); PG8_STAGE(PG8_SB(1, 0), b3, voffB); PG8_STAGE(PG8_SB(1, 1), b3 + hstepB, voffB); PG8_STAGE(PG8_SA(1, 0), a3, voffA);
;             PG8_WAIT_V(8); PG8_WAIT_L(0); PG8_BAR; PG8_MMA(1, 0, At, B0); PG8_MMA(1, 1, At, B1); PG8_BAR; PG8_SCHED;
	s_add_i32 s42, s82, s85
	v_lshl_add_u64 v[86:87], v[202:203], 0, s[12:13]
	s_mov_b32 m0, s42
	s_nop 0
	ds_read_b128 v[82:85], v177 offset:49152
	ds_read_b128 v[190:193], v177 offset:50176
	ds_read_b128 v[194:197], v177 offset:51200
	ds_read_b128 v[198:201], v177 offset:52224
	ds_read_b128 v[212:215], v177 offset:53248
	ds_read_b128 v[216:219], v177 offset:54272
	ds_read_b128 v[220:223], v177 offset:55296
	ds_read_b128 v[224:227], v177 offset:56320
	global_load_lds_dwordx4 v[86:87], off
	s_add_i32 m0, s42, 0x2000
	s_add_u32 s40, s40, 0x40080
	v_lshl_add_u64 v[86:87], v[228:229], 0, s[12:13]
	s_addc_u32 s41, s41, 0
	s_add_i32 s42, s83, s85
	global_load_lds_dwordx4 v[86:87], off
	v_lshl_add_u64 v[86:87], s[40:41], 0, v[168:169]
	s_mov_b32 m0, s42
	s_nop 0
	global_load_lds_dwordx4 v[86:87], off
	v_lshl_add_u64 v[86:87], s[40:41], 0, v[164:165]
	s_add_i32 m0, s42, 0x2000
	s_nop 0
	global_load_lds_dwordx4 v[86:87], off
	v_lshl_add_u64 v[86:87], v[230:231], 0, s[12:13]
	s_mov_b32 m0, s3
	s_nop 0
	global_load_lds_dwordx4 v[86:87], off
	v_lshl_add_u64 v[86:87], v[232:233], 0, s[12:13]
	s_mov_b32 m0, s2
	s_nop 0
	global_load_lds_dwordx4 v[86:87], off
	s_waitcnt vmcnt(8)
	s_waitcnt lgkmcnt(0)
	s_barrier
	s_setprio 1
	s_waitcnt lgkmcnt(0)
	v_mfma_i32_16x16x64_i8 v[86:89], v[58:61], v[82:85], v[94:97]
	v_mfma_i32_16x16x64_i8 v[94:97], v[62:65], v[190:193], v[86:89]
	v_mfma_i32_16x16x64_i8 v[86:89], v[66:69], v[82:85], v[90:93]
	v_mfma_i32_16x16x64_i8 v[46:49], v[58:61], v[194:197], v[46:49]
	v_mfma_i32_16x16x64_i8 v[42:45], v[66:69], v[194:197], v[42:45]
	v_mfma_i32_16x16x64_i8 v[30:33], v[58:61], v[212:215], v[30:33]
	v_mfma_i32_16x16x64_i8 v[26:29], v[66:69], v[212:215], v[26:29]
	v_mfma_i32_16x16x64_i8 v[14:17], v[58:61], v[220:223], v[14:17]
	v_mfma_i32_16x16x64_i8 v[10:13], v[66:69], v[220:223], v[10:13]
	v_mfma_i32_16x16x64_i8 v[90:93], v[70:73], v[190:193], v[86:89]
	v_mfma_i32_16x16x64_i8 v[46:49], v[62:65], v[198:201], v[46:49]
	v_mfma_i32_16x16x64_i8 v[42:45], v[70:73], v[198:201], v[42:45]
	v_mfma_i32_16x16x64_i8 v[30:33], v[62:65], v[216:219], v[30:33]
	v_mfma_i32_16x16x64_i8 v[26:29], v[70:73], v[216:219], v[26:29]
	v_mfma_i32_16x16x64_i8 v[14:17], v[62:65], v[224:227], v[14:17]
	v_mfma_i32_16x16x64_i8 v[10:13], v[70:73], v[224:227], v[10:13]
	s_setprio 0
	s_setprio 1
	v_mfma_i32_16x16x64_i8 v[50:53], v[74:77], v[82:85], v[50:53]
	v_mfma_i32_16x16x64_i8 v[86:89], v[78:81], v[190:193], v[50:53]
	v_mfma_i32_16x16x64_i8 v[50:53], v[182:185], v[82:85], v[54:57]
	v_mfma_i32_16x16x64_i8 v[38:41], v[74:77], v[194:197], v[38:41]
	v_mfma_i32_16x16x64_i8 v[34:37], v[182:185], v[194:197], v[34:37]
	v_mfma_i32_16x16x64_i8 v[22:25], v[74:77], v[212:215], v[22:25]
	v_mfma_i32_16x16x64_i8 v[18:21], v[182:185], v[212:215], v[18:21]
	v_mfma_i32_16x16x64_i8 v[6:9], v[74:77], v[220:223], v[6:9]
	v_mfma_i32_16x16x64_i8 v[2:5], v[182:185], v[220:223], v[2:5]
	v_mfma_i32_16x16x64_i8 v[82:85], v[186:189], v[190:193], v[50:53]
	v_mfma_i32_16x16x64_i8 v[38:41], v[78:81], v[198:201], v[38:41]
	v_mfma_i32_16x16x64_i8 v[34:37], v[186:189], v[198:201], v[34:37]
	v_mfma_i32_16x16x64_i8 v[22:25], v[78:81], v[216:219], v[22:25]
	v_mfma_i32_16x16x64_i8 v[18:21], v[186:189], v[216:219], v[18:21]
	v_mfma_i32_16x16x64_i8 v[6:9], v[78:81], v[224:227], v[6:9]
	v_mfma_i32_16x16x64_i8 v[2:5], v[186:189], v[224:227], v[2:5]
	s_setprio 0
	s_add_u32 s0, s0, 0x100
	s_addc_u32 s1, s1, 0
	s_add_u32 s57, s57, 0x100
	s_addc_u32 s63, s63, 0
	s_cmp_ge_u32 s80, s22
	s_mov_b32 s42, s80
	s_barrier
	s_cbranch_scc0 .LBB0_1574
	s_and_b64 vcc, exec, s[36:37]
	s_cbranch_vccz .LBB0_1577
	s_barrier
